# barrier: early L1 invalidate behind arrival atomic; sc1 write-through GEMM epilogue stores, skip L2 writeback at barriers after GEMM phases
# speedup vs baseline: 1.0064x; 1.0064x over previous
; __device__ __forceinline__ unsigned xb_ld(unsigned* p)              { return __hip_atomic_load(p, __ATOMIC_RELAXED, __HIP_MEMORY_SCOPE_AGENT); }
; __device__ __forceinline__ unsigned xb_add(unsigned* p, unsigned v) { return __hip_atomic_fetch_add(p, v, __ATOMIC_RELAXED, __HIP_MEMORY_SCOPE_AGENT); }
; #define XB_SPIN(cond, bar) do { unsigned _sp = 0; while (cond) { __builtin_amdgcn_s_sleep(1); \
;     if ((++_sp & 255u) == 0u) { if (xb_ld(&(bar)[XB_TMO])) break; if (_sp > XB_SPIN_CAP) { atomicAdd(&(bar)[XB_TMO], 1u); break; } } } } while (0)
; __device__ __forceinline__ void xcd_barrier(const XcdBarrier& b) {
;     ...
;     if (threadIdx.x == 0) {
;         unsigned* bar = b.bar;
;         __builtin_amdgcn_s_waitcnt(0);
;         unsigned nloc = b.st[0], nx = b.st[1];
;         if (nloc == 0u) { xcd_barrier_complete(bar, b.x, nloc, nx); b.st[0] = nloc; b.st[1] = nx; }
;         const unsigned old = xb_add(&bar[XB_XSUB(b.x)], 1u);
;         const unsigned gen = old / nloc;
;         if (old + 1u == (gen + 1u) * nloc) {
;             __builtin_amdgcn_fence(__ATOMIC_RELEASE, "agent");
;             asm volatile("s_waitcnt vmcnt(0)" ::: "memory");
;             const unsigned og = xb_add(&bar[XB_TOP], 1u);
;             const unsigned tg = og / nx;
;             if (og + 1u == (tg + 1u) * nx) xb_add(&bar[XB_TOPGEN], 1u);
;             else XB_SPIN(xb_ld(&bar[XB_TOPGEN]) == tg, bar);
;             __builtin_amdgcn_fence(__ATOMIC_ACQUIRE, "agent");
;             xb_add(&bar[XB_XGEN(b.x)], 1u);
;             asm volatile("s_waitcnt vmcnt(0)" ::: "memory");
;         } else {
;             XB_SPIN(xb_ld(&bar[XB_XGEN(b.x)]) == gen, bar);
.LBB0_27:
	s_mov_b64 s[14:15], exec
	v_mbcnt_lo_u32_b32 v1, s14, 0
	v_mbcnt_hi_u32_b32 v1, s15, v1
	v_cmp_eq_u32_e32 vcc, 0, v1
	s_and_saveexec_b64 s[12:13], vcc
	s_cbranch_execz .LBB0_29
	s_bcnt1_i32_b64 s0, s[14:15]
	v_mov_b32_e32 v3, s0
	v_readlane_b32 s0, v253, 8
	v_readlane_b32 s1, v253, 9
	s_nop 4
	global_atomic_add v3, v33, v3, s[0:1] sc0
	buffer_inv sc1
.LBB0_29:
	s_or_b64 exec, exec, s[12:13]
	v_cvt_f32_u32_e32 v4, v2
	s_waitcnt vmcnt(1)
	v_readfirstlane_b32 s0, v3
	v_sub_u32_e32 v3, 0, v2
	v_rcp_iflag_f32_e32 v4, v4
	v_add_u32_e32 v5, s0, v1
	v_mul_f32_e32 v4, 0x4f7ffffe, v4
	v_cvt_u32_f32_e32 v4, v4
	v_mul_lo_u32 v1, v3, v4
	v_mul_hi_u32 v1, v4, v1
	v_add_u32_e32 v1, v4, v1
	v_mul_hi_u32 v1, v5, v1
	v_mul_lo_u32 v3, v1, v2
	v_sub_u32_e32 v3, v5, v3
	v_add_u32_e32 v4, 1, v1
	v_cmp_ge_u32_e32 vcc, v3, v2
	s_nop 1
	v_cndmask_b32_e32 v1, v1, v4, vcc
	v_sub_u32_e32 v4, v3, v2
	v_cndmask_b32_e32 v3, v3, v4, vcc
	v_add_u32_e32 v4, 1, v1
	v_cmp_ge_u32_e32 vcc, v3, v2
	v_add_u32_e32 v3, 1, v5
	s_nop 0
	v_cndmask_b32_e32 v1, v1, v4, vcc
	v_mul_lo_u32 v4, v2, v1
	v_add_u32_e32 v2, v4, v2
	v_cmp_ne_u32_e32 vcc, v3, v2
	s_and_saveexec_b64 s[0:1], vcc
	s_xor_b64 s[12:13], exec, s[0:1]
	s_cbranch_execz .LBB0_43
	v_readlane_b32 s0, v253, 10
	v_readlane_b32 s1, v253, 11
	s_waitcnt lgkmcnt(0)
	s_nop 3
	global_load_dword v0, v33, s[0:1] sc1
	s_waitcnt vmcnt(0)
	v_cmp_eq_u32_e32 vcc, v0, v1
	s_and_saveexec_b64 s[14:15], vcc
	s_cbranch_execz .LBB0_42
	s_mov_b32 s0, 1
	s_mov_b64 s[16:17], 0
	s_branch .LBB0_33

; __device__ __forceinline__ unsigned xb_ld(unsigned* p)              { return __hip_atomic_load(p, __ATOMIC_RELAXED, __HIP_MEMORY_SCOPE_AGENT); }
; __device__ __forceinline__ unsigned xb_add(unsigned* p, unsigned v) { return __hip_atomic_fetch_add(p, v, __ATOMIC_RELAXED, __HIP_MEMORY_SCOPE_AGENT); }
; #define XB_SPIN(cond, bar) do { unsigned _sp = 0; while (cond) { __builtin_amdgcn_s_sleep(1); \
;     if ((++_sp & 255u) == 0u) { if (xb_ld(&(bar)[XB_TMO])) break; if (_sp > XB_SPIN_CAP) { atomicAdd(&(bar)[XB_TMO], 1u); break; } } } } while (0)
; __device__ __forceinline__ void xcd_barrier(const XcdBarrier& b) {
;     ...
;             __builtin_amdgcn_fence(__ATOMIC_RELEASE, "agent");
;             asm volatile("s_waitcnt vmcnt(0)" ::: "memory");
;             const unsigned og = xb_add(&bar[XB_TOP], 1u);
;             const unsigned tg = og / nx;
;             if (og + 1u == (tg + 1u) * nx) xb_add(&bar[XB_TOPGEN], 1u);
;             else XB_SPIN(xb_ld(&bar[XB_TOPGEN]) == tg, bar);
;             __builtin_amdgcn_fence(__ATOMIC_ACQUIRE, "agent");
;             xb_add(&bar[XB_XGEN(b.x)], 1u);
;             asm volatile("s_waitcnt vmcnt(0)" ::: "memory");
;         } else {
;             XB_SPIN(xb_ld(&bar[XB_XGEN(b.x)]) == gen, bar);
;             __builtin_amdgcn_fence(__ATOMIC_ACQUIRE, "agent");
;             asm volatile("s_waitcnt vmcnt(0)" ::: "memory");
.LBB0_42:
	s_or_b64 exec, exec, s[14:15]
	s_waitcnt vmcnt(0)
	s_waitcnt vmcnt(0)
.LBB0_43:
	s_andn2_saveexec_b64 s[0:1], s[12:13]
	s_cbranch_execz .LBB0_63
	s_mov_b64 s[12:13], exec
	s_mov_b32 s0, 0xd96c8
	s_bitcmp1_b32 s0, s72
	s_cbranch_scc1 .Lnowb_main
	buffer_wbl2 sc1
.Lnowb_main:
	s_waitcnt lgkmcnt(0)
	s_waitcnt vmcnt(0)
	v_mbcnt_lo_u32_b32 v1, s12, 0
	v_mbcnt_hi_u32_b32 v1, s13, v1
	v_cmp_eq_u32_e32 vcc, 0, v1
	s_and_saveexec_b64 s[14:15], vcc
	s_cbranch_execz .LBB0_46
	s_bcnt1_i32_b64 s0, s[12:13]
	v_mov_b32_e32 v2, s0
	v_readlane_b32 s0, v253, 12
	v_readlane_b32 s1, v253, 13
	s_nop 4
	global_atomic_add v2, v33, v2, s[0:1] sc0

; __device__ __forceinline__ unsigned xb_ld(unsigned* p)              { return __hip_atomic_load(p, __ATOMIC_RELAXED, __HIP_MEMORY_SCOPE_AGENT); }
; __device__ __forceinline__ unsigned xb_add(unsigned* p, unsigned v) { return __hip_atomic_fetch_add(p, v, __ATOMIC_RELAXED, __HIP_MEMORY_SCOPE_AGENT); }
; #define XB_SPIN(cond, bar) do { unsigned _sp = 0; while (cond) { __builtin_amdgcn_s_sleep(1); \
;     if ((++_sp & 255u) == 0u) { if (xb_ld(&(bar)[XB_TMO])) break; if (_sp > XB_SPIN_CAP) { atomicAdd(&(bar)[XB_TMO], 1u); break; } } } } while (0)
; __device__ __forceinline__ void xcd_barrier(const XcdBarrier& b) {
;     ...
;             if (og + 1u == (tg + 1u) * nx) xb_add(&bar[XB_TOPGEN], 1u);
;             else XB_SPIN(xb_ld(&bar[XB_TOPGEN]) == tg, bar);
;             __builtin_amdgcn_fence(__ATOMIC_ACQUIRE, "agent");
;             xb_add(&bar[XB_XGEN(b.x)], 1u);
;             asm volatile("s_waitcnt vmcnt(0)" ::: "memory");
.LBB0_60:
	s_or_b64 exec, exec, s[12:13]
	s_mov_b64 s[12:13], exec
	v_mbcnt_lo_u32_b32 v0, s12, 0
	v_mbcnt_hi_u32_b32 v0, s13, v0
	v_cmp_eq_u32_e32 vcc, 0, v0
	s_waitcnt vmcnt(0)
	s_and_saveexec_b64 s[14:15], vcc
	s_cbranch_execz .LBB0_62
	s_bcnt1_i32_b64 s0, s[12:13]
	v_mov_b32_e32 v0, s0
	v_readlane_b32 s0, v253, 10
	v_readlane_b32 s1, v253, 11
	s_nop 4
	global_atomic_add v33, v0, s[0:1]

; __device__ __forceinline__ unsigned cvt_pk_bf16(float lo, float hi) { unsigned r; asm volatile("v_cvt_pk_bf16_f32 %0, %1, %2" : "=v"(r) : "v"(lo), "v"(hi)); return r; }
;     __device__ __forceinline__ void operator()(const f32x4 (&acc)[2][2][4][2], const Unit& u, int wr, int wc, int fr, int fq) const {
;         const int row0 = u.pm * BM + wr * 64 + fr, col0 = u.pn * BM + wc * 32 + 8 * fq;
;         bf16_t* ob = u.slab < 0 ? O : SL + (size_t)u.slab * (1024 * 1024) - (size_t)ML * 1024;
; #pragma unroll
;         for (int ai = 0; ai < 2; ++ai)
; #pragma unroll
;             for (int m = 0; m < 4; ++m) { bf16_t* rowp = ob + (size_t)(row0 + ai * HALF + m * 16) * 1024 + col0;
; #pragma unroll
;                 for (int bj = 0; bj < 2; ++bj) { const f32x4 v0 = acc[ai][bj][m][0], v1 = acc[ai][bj][m][1];
;                     u32x4 w; w.x = cvt_pk_bf16(v0[0], v0[1]); w.y = cvt_pk_bf16(v0[2], v0[3]); w.z = cvt_pk_bf16(v1[0], v1[1]); w.w = cvt_pk_bf16(v1[2], v1[3]);
;                     *(u32x4*)(rowp + bj * HALF) = w; } }
;     }
.LBB0_187:
	v_mov_b32_e32 v141, v142
	s_lshl_b32 s18, s80, 8
	v_ashrrev_i32_e32 v140, 1, v141
	v_and_b32_e32 v140, -8, v140
	s_or_b32 s18, s18, s66
	v_add_u32_e32 v140, s18, v140
	s_lshl_b64 s[18:19], s[8:9], 21
	s_add_u32 s18, s24, s18
	s_addc_u32 s19, s25, s19
	s_add_u32 s18, s18, 0xfe000000
	s_addc_u32 s19, s19, -1
	s_cmp_lt_i32 s8, 0
	v_and_or_b32 v141, v141, 15, s65
	s_cselect_b32 s8, s5, s19
	s_cselect_b32 s18, s4, s18
	v_lshl_add_u32 v148, s79, 8, v141
	v_mov_b32_e32 v146, s18
	v_mov_b32_e32 v147, s8
	v_ashrrev_i32_e32 v141, 31, v140
	v_ashrrev_i32_e32 v149, 31, v148
	v_lshl_add_u64 v[146:147], v[140:141], 1, v[146:147]
	v_lshlrev_b64 v[140:141], 11, v[148:149]
	v_lshl_add_u64 v[140:141], v[146:147], 0, v[140:141]
	v_cvt_pk_bf16_f32 v126, v126, v127
	v_cvt_pk_bf16_f32 v127, v128, v129
	v_cvt_pk_bf16_f32 v128, v122, v123
	v_cvt_pk_bf16_f32 v129, v124, v125
	global_store_dwordx4 v[140:141], v[126:129], off sc1
	v_cvt_pk_bf16_f32 v114, v114, v115
	v_cvt_pk_bf16_f32 v115, v116, v117
	v_cvt_pk_bf16_f32 v116, v106, v107
	v_or_b32_e32 v106, 16, v148
	v_ashrrev_i32_e32 v107, 31, v106
	v_lshlrev_b64 v[106:107], 11, v[106:107]
	v_cvt_pk_bf16_f32 v117, v108, v109
	global_store_dwordx4 v[140:141], v[114:117], off offset:256 sc1
	s_mov_b32 s8, 0x40000
	s_mov_b64 s[18:19], 0x40000
	v_lshl_add_u64 v[114:115], v[146:147], 0, v[106:107]
	v_cvt_pk_bf16_f32 v106, v118, v119
	v_cvt_pk_bf16_f32 v107, v120, v121
	v_cvt_pk_bf16_f32 v108, v110, v111
	v_cvt_pk_bf16_f32 v109, v112, v113
	global_store_dwordx4 v[114:115], v[106:109], off sc1
	v_cvt_pk_bf16_f32 v98, v98, v99
	v_cvt_pk_bf16_f32 v99, v100, v101
	v_cvt_pk_bf16_f32 v100, v90, v91
	v_or_b32_e32 v90, 32, v148
	v_ashrrev_i32_e32 v91, 31, v90
	v_lshlrev_b64 v[90:91], 11, v[90:91]
	v_cvt_pk_bf16_f32 v101, v92, v93
	global_store_dwordx4 v[114:115], v[98:101], off offset:256 sc1
	s_nop 1
	v_lshl_add_u64 v[98:99], v[146:147], 0, v[90:91]
	v_cvt_pk_bf16_f32 v90, v102, v103
	v_cvt_pk_bf16_f32 v91, v104, v105
	v_cvt_pk_bf16_f32 v92, v94, v95
	v_cvt_pk_bf16_f32 v93, v96, v97
	global_store_dwordx4 v[98:99], v[90:93], off sc1
	v_cvt_pk_bf16_f32 v82, v82, v83
	v_cvt_pk_bf16_f32 v83, v84, v85
	v_cvt_pk_bf16_f32 v84, v74, v75
	v_or_b32_e32 v74, 48, v148
	v_ashrrev_i32_e32 v75, 31, v74
	v_lshlrev_b64 v[74:75], 11, v[74:75]
	v_cvt_pk_bf16_f32 v85, v76, v77
	global_store_dwordx4 v[98:99], v[82:85], off offset:256 sc1
	s_nop 1
	v_lshl_add_u64 v[82:83], v[146:147], 0, v[74:75]
	v_cvt_pk_bf16_f32 v74, v86, v87
	v_cvt_pk_bf16_f32 v75, v88, v89
	v_cvt_pk_bf16_f32 v76, v78, v79
	v_cvt_pk_bf16_f32 v77, v80, v81
	global_store_dwordx4 v[82:83], v[74:77], off sc1
	v_cvt_pk_bf16_f32 v70, v70, v71
	v_cvt_pk_bf16_f32 v71, v72, v73
	v_cvt_pk_bf16_f32 v72, v66, v67
	v_cvt_pk_bf16_f32 v73, v68, v69
	global_store_dwordx4 v[82:83], v[70:73], off offset:256 sc1
	v_cvt_pk_bf16_f32 v62, v62, v63
	v_cvt_pk_bf16_f32 v63, v64, v65
	v_cvt_pk_bf16_f32 v64, v58, v59
	v_add_co_u32_e32 v58, vcc, s8, v140
	v_lshl_add_u64 v[66:67], v[140:141], 0, s[18:19]
	s_nop 0
	v_addc_co_u32_e32 v59, vcc, 0, v141, vcc
	v_cvt_pk_bf16_f32 v65, v60, v61
	global_store_dwordx4 v[58:59], v[62:65], off sc1
	v_cvt_pk_bf16_f32 v50, v50, v51
	v_cvt_pk_bf16_f32 v51, v52, v53
	v_cvt_pk_bf16_f32 v52, v42, v43
	v_cvt_pk_bf16_f32 v53, v44, v45
	global_store_dwordx4 v[66:67], v[50:53], off offset:256 sc1
	s_mov_b64 s[18:19], 0x48000
	v_cvt_pk_bf16_f32 v42, v54, v55
	v_cvt_pk_bf16_f32 v43, v56, v57
	v_cvt_pk_bf16_f32 v44, v46, v47
	v_add_co_u32_e32 v46, vcc, s93, v140
	v_lshl_add_u64 v[50:51], v[140:141], 0, s[18:19]
	s_nop 0
	v_addc_co_u32_e32 v47, vcc, 0, v141, vcc
	s_mov_b32 s8, 0x50000
	v_cvt_pk_bf16_f32 v45, v48, v49
	global_store_dwordx4 v[46:47], v[42:45], off sc1
	v_cvt_pk_bf16_f32 v34, v34, v35
	v_cvt_pk_bf16_f32 v35, v36, v37
	v_cvt_pk_bf16_f32 v36, v24, v25
	v_cvt_pk_bf16_f32 v37, v26, v27
	global_store_dwordx4 v[50:51], v[34:37], off offset:256 sc1
	s_mov_b64 s[18:19], 0x50000
	v_cvt_pk_bf16_f32 v24, v38, v39
	v_cvt_pk_bf16_f32 v25, v40, v41
	v_cvt_pk_bf16_f32 v26, v28, v29
	v_add_co_u32_e32 v28, vcc, s8, v140
	v_lshl_add_u64 v[34:35], v[140:141], 0, s[18:19]
	s_nop 0
	v_addc_co_u32_e32 v29, vcc, 0, v141, vcc
	s_mov_b32 s8, 0x58000
	v_cvt_pk_bf16_f32 v27, v30, v31
	global_store_dwordx4 v[28:29], v[24:27], off sc1
	v_cvt_pk_bf16_f32 v16, v16, v17
	v_cvt_pk_bf16_f32 v17, v18, v19
	v_cvt_pk_bf16_f32 v18, v8, v9
	v_cvt_pk_bf16_f32 v19, v10, v11
	global_store_dwordx4 v[34:35], v[16:19], off offset:256 sc1
	v_cvt_pk_bf16_f32 v8, v20, v21
	v_cvt_pk_bf16_f32 v9, v22, v23
	v_cvt_pk_bf16_f32 v10, v12, v13
	v_add_co_u32_e32 v12, vcc, s8, v140
	s_mov_b64 s[18:19], 0x58000
	s_nop 0
	v_addc_co_u32_e32 v13, vcc, 0, v141, vcc
	v_lshl_add_u64 v[16:17], v[140:141], 0, s[18:19]
	s_andn2_b64 vcc, exec, s[52:53]
	s_mov_b64 s[18:19], -1
	v_cvt_pk_bf16_f32 v11, v14, v15
	global_store_dwordx4 v[12:13], v[8:11], off sc1
	v_cvt_pk_bf16_f32 v4, v4, v5
	v_cvt_pk_bf16_f32 v5, v6, v7
	v_cvt_pk_bf16_f32 v6, v0, v1
	v_cvt_pk_bf16_f32 v7, v2, v3
	global_store_dwordx4 v[16:17], v[4:7], off offset:256 sc1
	s_cbranch_vccnz .LBB0_169
	s_andn2_b64 vcc, exec, s[20:21]
	s_cbranch_vccnz .LBB0_168
	s_barrier
	s_branch .LBB0_168

; __device__ __forceinline__ unsigned cvt_pk_bf16(float lo, float hi) { unsigned r; asm volatile("v_cvt_pk_bf16_f32 %0, %1, %2" : "=v"(r) : "v"(lo), "v"(hi)); return r; }
; __device__ __forceinline__ float siluf_(float x) { return x * __builtin_amdgcn_rcpf(1.0f + __expf(-x)); }
;     __device__ __forceinline__ void operator()(const f32x4 (&acc)[2][2][4][2], const Unit& u, int wr, int wc, int fr, int fq) const {
;         const int row0 = u.pm * BM + wr * 64 + fr, col0 = u.pn * 128 + wc * 32 + 8 * fq;
; #pragma unroll
;         for (int ai = 0; ai < 2; ++ai)
; #pragma unroll
;             for (int m = 0; m < 4; ++m) { bf16_t* rowp = O + (size_t)(row0 + ai * HALF + m * 16) * DFF + col0;
;                 float r[8];
; #pragma unroll
;                 for (int n = 0; n < 2; ++n)
; #pragma unroll
;                     for (int j = 0; j < 4; ++j) r[n * 4 + j] = siluf_(acc[ai][0][m][n][j]) * acc[ai][1][m][n][j];
;                 u32x4 w; w.x = cvt_pk_bf16(r[0], r[1]); w.y = cvt_pk_bf16(r[2], r[3]); w.z = cvt_pk_bf16(r[4], r[5]); w.w = cvt_pk_bf16(r[6], r[7]);
;                 *(u32x4*)rowp = w; }
;     }
.LBB0_205:
	v_mul_f32_e32 v150, 0xbfb8aa3b, v126
	v_exp_f32_e32 v150, v150
	v_mov_b32_e32 v140, v142
	s_lshl_b32 s18, s56, 8
	v_add_f32_e32 v150, 1.0, v150
	v_rcp_f32_e32 v150, v150
	s_add_i32 s18, s18, s47
	v_and_or_b32 v145, v140, 15, s18
	s_lshl_b32 s18, s78, 7
	v_mul_f32_e32 v126, v126, v150
	v_mul_f32_e32 v122, v122, v126
	v_mul_f32_e32 v126, 0xbfb8aa3b, v127
	v_exp_f32_e32 v126, v126
	v_ashrrev_i32_e32 v140, 1, v140
	s_or_b32 s18, s18, s57
	v_and_b32_e32 v140, -8, v140
	v_add_f32_e32 v126, 1.0, v126
	v_rcp_f32_e32 v126, v126
	v_add_u32_e32 v146, s18, v140
	v_readlane_b32 s18, v255, 24
	v_readlane_b32 s19, v255, 25
	v_mul_f32_e32 v126, v127, v126
	v_mul_f32_e32 v123, v123, v126
	v_mul_f32_e32 v126, 0xbfb8aa3b, v128
	v_exp_f32_e32 v126, v126
	v_ashrrev_i32_e32 v147, 31, v146
	v_mov_b64_e32 v[140:141], s[18:19]
	s_movk_i32 s27, 0x1600
	v_add_f32_e32 v126, 1.0, v126
	v_rcp_f32_e32 v126, v126
	v_mad_i64_i32 v[148:149], s[18:19], v145, s27, v[140:141]
	s_andn2_b64 vcc, exec, s[40:41]
	v_mul_f32_e32 v126, v128, v126
	v_mul_f32_e32 v124, v124, v126
	v_mul_f32_e32 v126, 0xbfb8aa3b, v129
	v_exp_f32_e32 v126, v126
	s_nop 0
	v_add_f32_e32 v126, 1.0, v126
	v_rcp_f32_e32 v126, v126
	s_nop 0
	v_mul_f32_e32 v126, v129, v126
	v_mul_f32_e32 v125, v125, v126
	v_mul_f32_e32 v126, 0xbfb8aa3b, v118
	v_exp_f32_e32 v126, v126
	s_nop 0
	v_add_f32_e32 v126, 1.0, v126
	v_rcp_f32_e32 v126, v126
	s_nop 0
	v_mul_f32_e32 v118, v118, v126
	v_mul_f32_e32 v118, v114, v118
	v_mul_f32_e32 v114, 0xbfb8aa3b, v119
	v_exp_f32_e32 v114, v114
	s_nop 0
	v_add_f32_e32 v114, 1.0, v114
	v_rcp_f32_e32 v114, v114
	s_nop 0
	v_mul_f32_e32 v114, v119, v114
	v_mul_f32_e32 v119, v115, v114
	v_mul_f32_e32 v114, 0xbfb8aa3b, v120
	v_exp_f32_e32 v114, v114
	s_nop 0
	v_add_f32_e32 v114, 1.0, v114
	v_rcp_f32_e32 v114, v114
	s_nop 0
	v_mul_f32_e32 v114, v120, v114
	v_mul_f32_e32 v126, v116, v114
	v_mul_f32_e32 v114, 0xbfb8aa3b, v121
	v_exp_f32_e32 v114, v114
	v_cvt_pk_bf16_f32 v116, v122, v123
	s_nop 0
	v_add_f32_e32 v114, 1.0, v114
	v_rcp_f32_e32 v114, v114
	s_nop 0
	v_mul_f32_e32 v114, v121, v114
	v_mul_f32_e32 v127, v117, v114
	v_lshlrev_b64 v[114:115], 1, v[146:147]
	v_lshl_add_u64 v[120:121], v[148:149], 0, v[114:115]
	v_cvt_pk_bf16_f32 v117, v124, v125
	v_cvt_pk_bf16_f32 v118, v118, v119
	v_cvt_pk_bf16_f32 v119, v126, v127
	global_store_dwordx4 v[120:121], v[116:119], off sc1
	s_nop 1
	v_mul_f32_e32 v118, 0xbfb8aa3b, v110
	v_exp_f32_e32 v118, v118
	v_or_b32_e32 v116, 16, v145
	v_mad_i64_i32 v[116:117], s[18:19], v116, s27, v[140:141]
	v_add_f32_e32 v118, 1.0, v118
	v_rcp_f32_e32 v118, v118
	s_nop 0
	v_mul_f32_e32 v110, v110, v118
	v_mul_f32_e32 v106, v106, v110
	v_mul_f32_e32 v110, 0xbfb8aa3b, v111
	v_exp_f32_e32 v110, v110
	s_nop 0
	v_add_f32_e32 v110, 1.0, v110
	v_rcp_f32_e32 v110, v110
	s_nop 0
	v_mul_f32_e32 v110, v111, v110
	v_mul_f32_e32 v107, v107, v110
	v_mul_f32_e32 v110, 0xbfb8aa3b, v112
	v_exp_f32_e32 v110, v110
	s_nop 0
	v_add_f32_e32 v110, 1.0, v110
	v_rcp_f32_e32 v110, v110
	s_nop 0
	v_mul_f32_e32 v110, v112, v110
	v_mul_f32_e32 v108, v108, v110
	v_mul_f32_e32 v110, 0xbfb8aa3b, v113
	v_exp_f32_e32 v110, v110
	s_nop 0
	v_add_f32_e32 v110, 1.0, v110
	v_rcp_f32_e32 v110, v110
	s_nop 0
	v_mul_f32_e32 v110, v113, v110
	v_mul_f32_e32 v109, v109, v110
	v_mul_f32_e32 v110, 0xbfb8aa3b, v102
	v_exp_f32_e32 v110, v110
	s_nop 0
	v_add_f32_e32 v110, 1.0, v110
	v_rcp_f32_e32 v110, v110
	s_nop 0
	v_mul_f32_e32 v102, v102, v110
	v_mul_f32_e32 v110, v98, v102
	v_mul_f32_e32 v98, 0xbfb8aa3b, v103
	v_exp_f32_e32 v98, v98
	s_nop 0
	v_add_f32_e32 v98, 1.0, v98
	v_rcp_f32_e32 v98, v98
	s_nop 0
	v_mul_f32_e32 v98, v103, v98
	v_mul_f32_e32 v111, v99, v98
	v_mul_f32_e32 v98, 0xbfb8aa3b, v104
	v_exp_f32_e32 v98, v98
	v_lshl_add_u64 v[102:103], v[116:117], 0, v[114:115]
	v_add_f32_e32 v98, 1.0, v98
	v_rcp_f32_e32 v98, v98
	s_nop 0
	v_mul_f32_e32 v98, v104, v98
	v_mul_f32_e32 v104, v100, v98
	v_mul_f32_e32 v98, 0xbfb8aa3b, v105
	v_exp_f32_e32 v98, v98
	s_nop 0
	v_add_f32_e32 v98, 1.0, v98
	v_rcp_f32_e32 v98, v98
	s_nop 0
	v_mul_f32_e32 v98, v105, v98
	v_mul_f32_e32 v101, v101, v98
	v_cvt_pk_bf16_f32 v98, v106, v107
	v_cvt_pk_bf16_f32 v99, v108, v109
	v_cvt_pk_bf16_f32 v100, v110, v111
	v_cvt_pk_bf16_f32 v101, v104, v101
	global_store_dwordx4 v[102:103], v[98:101], off sc1
	s_nop 1
	v_mul_f32_e32 v100, 0xbfb8aa3b, v94
	v_exp_f32_e32 v100, v100
	v_or_b32_e32 v98, 32, v145
	v_mad_i64_i32 v[98:99], s[18:19], v98, s27, v[140:141]
	v_add_f32_e32 v100, 1.0, v100
	v_rcp_f32_e32 v100, v100
	s_nop 0
	v_mul_f32_e32 v94, v94, v100
	v_mul_f32_e32 v90, v90, v94
	v_mul_f32_e32 v94, 0xbfb8aa3b, v95
	v_exp_f32_e32 v94, v94
	s_nop 0
	v_add_f32_e32 v94, 1.0, v94
	v_rcp_f32_e32 v94, v94
	s_nop 0
	v_mul_f32_e32 v94, v95, v94
	v_mul_f32_e32 v91, v91, v94
	v_mul_f32_e32 v94, 0xbfb8aa3b, v96
	v_exp_f32_e32 v94, v94
	s_nop 0
	v_add_f32_e32 v94, 1.0, v94
	v_rcp_f32_e32 v94, v94
	s_nop 0
	v_mul_f32_e32 v94, v96, v94
	v_mul_f32_e32 v92, v92, v94
	v_mul_f32_e32 v94, 0xbfb8aa3b, v97
	v_exp_f32_e32 v94, v94
	s_nop 0
	v_add_f32_e32 v94, 1.0, v94
	v_rcp_f32_e32 v94, v94
	s_nop 0
	v_mul_f32_e32 v94, v97, v94
	v_mul_f32_e32 v93, v93, v94
	v_mul_f32_e32 v94, 0xbfb8aa3b, v86
	v_exp_f32_e32 v94, v94
	s_nop 0
	v_add_f32_e32 v94, 1.0, v94
	v_rcp_f32_e32 v94, v94
	s_nop 0
	v_mul_f32_e32 v86, v86, v94
	v_mul_f32_e32 v94, v82, v86
	v_mul_f32_e32 v82, 0xbfb8aa3b, v87
	v_exp_f32_e32 v82, v82
	s_nop 0
	v_add_f32_e32 v82, 1.0, v82
	v_rcp_f32_e32 v82, v82
	s_nop 0
	v_mul_f32_e32 v82, v87, v82
	v_mul_f32_e32 v95, v83, v82
	v_mul_f32_e32 v82, 0xbfb8aa3b, v88
	v_exp_f32_e32 v82, v82
	v_lshl_add_u64 v[86:87], v[98:99], 0, v[114:115]
; __device__ __forceinline__ unsigned cvt_pk_bf16(float lo, float hi) { unsigned r; asm volatile("v_cvt_pk_bf16_f32 %0, %1, %2" : "=v"(r) : "v"(lo), "v"(hi)); return r; }
; __device__ __forceinline__ float siluf_(float x) { return x * __builtin_amdgcn_rcpf(1.0f + __expf(-x)); }
;     __device__ __forceinline__ void operator()(const f32x4 (&acc)[2][2][4][2], const Unit& u, int wr, int wc, int fr, int fq) const {
;         const int row0 = u.pm * BM + wr * 64 + fr, col0 = u.pn * 128 + wc * 32 + 8 * fq;
; #pragma unroll
;         for (int ai = 0; ai < 2; ++ai)
; #pragma unroll
;             for (int m = 0; m < 4; ++m) { bf16_t* rowp = O + (size_t)(row0 + ai * HALF + m * 16) * DFF + col0;
;                 float r[8];
; #pragma unroll
;                 for (int n = 0; n < 2; ++n)
; #pragma unroll
;                     for (int j = 0; j < 4; ++j) r[n * 4 + j] = siluf_(acc[ai][0][m][n][j]) * acc[ai][1][m][n][j];
;                 u32x4 w; w.x = cvt_pk_bf16(r[0], r[1]); w.y = cvt_pk_bf16(r[2], r[3]); w.z = cvt_pk_bf16(r[4], r[5]); w.w = cvt_pk_bf16(r[6], r[7]);
;                 *(u32x4*)rowp = w; }
;     }
	v_add_f32_e32 v82, 1.0, v82
	v_rcp_f32_e32 v82, v82
	s_nop 0
	v_mul_f32_e32 v82, v88, v82
	v_mul_f32_e32 v88, v84, v82
	v_mul_f32_e32 v82, 0xbfb8aa3b, v89
	v_exp_f32_e32 v82, v82
	s_nop 0
	v_add_f32_e32 v82, 1.0, v82
	v_rcp_f32_e32 v82, v82
	s_nop 0
	v_mul_f32_e32 v82, v89, v82
	v_mul_f32_e32 v85, v85, v82
	v_cvt_pk_bf16_f32 v82, v90, v91
	v_cvt_pk_bf16_f32 v83, v92, v93
	v_cvt_pk_bf16_f32 v84, v94, v95
	v_cvt_pk_bf16_f32 v85, v88, v85
	global_store_dwordx4 v[86:87], v[82:85], off sc1
	s_nop 1
	v_mul_f32_e32 v84, 0xbfb8aa3b, v78
	v_exp_f32_e32 v84, v84
	v_or_b32_e32 v82, 48, v145
	v_mad_i64_i32 v[82:83], s[18:19], v82, s27, v[140:141]
	v_add_f32_e32 v84, 1.0, v84
	v_rcp_f32_e32 v84, v84
	s_nop 0
	v_mul_f32_e32 v78, v78, v84
	v_mul_f32_e32 v74, v74, v78
	v_mul_f32_e32 v78, 0xbfb8aa3b, v79
	v_exp_f32_e32 v78, v78
	s_nop 0
	v_add_f32_e32 v78, 1.0, v78
	v_rcp_f32_e32 v78, v78
	s_nop 0
	v_mul_f32_e32 v78, v79, v78
	v_mul_f32_e32 v75, v75, v78
	v_mul_f32_e32 v78, 0xbfb8aa3b, v80
	v_exp_f32_e32 v78, v78
	s_nop 0
	v_add_f32_e32 v78, 1.0, v78
	v_rcp_f32_e32 v78, v78
	s_nop 0
	v_mul_f32_e32 v78, v80, v78
	v_mul_f32_e32 v76, v76, v78
	v_mul_f32_e32 v78, 0xbfb8aa3b, v81
	v_exp_f32_e32 v78, v78
	s_nop 0
	v_add_f32_e32 v78, 1.0, v78
	v_rcp_f32_e32 v78, v78
	s_nop 0
	v_mul_f32_e32 v78, v81, v78
	v_mul_f32_e32 v77, v77, v78
	v_mul_f32_e32 v78, 0xbfb8aa3b, v70
	v_exp_f32_e32 v78, v78
	s_nop 0
	v_add_f32_e32 v78, 1.0, v78
	v_rcp_f32_e32 v78, v78
	s_nop 0
	v_mul_f32_e32 v70, v70, v78
	v_mul_f32_e32 v78, v66, v70
	v_mul_f32_e32 v66, 0xbfb8aa3b, v71
	v_exp_f32_e32 v66, v66
	s_nop 0
	v_add_f32_e32 v66, 1.0, v66
	v_rcp_f32_e32 v66, v66
	s_nop 0
	v_mul_f32_e32 v66, v71, v66
	v_mul_f32_e32 v79, v67, v66
	v_mul_f32_e32 v66, 0xbfb8aa3b, v72
	v_exp_f32_e32 v66, v66
	v_lshl_add_u64 v[70:71], v[82:83], 0, v[114:115]
	v_add_f32_e32 v66, 1.0, v66
	v_rcp_f32_e32 v66, v66
	s_nop 0
	v_mul_f32_e32 v66, v72, v66
	v_mul_f32_e32 v72, v68, v66
	v_mul_f32_e32 v66, 0xbfb8aa3b, v73
	v_exp_f32_e32 v66, v66
	s_nop 0
	v_add_f32_e32 v66, 1.0, v66
	v_rcp_f32_e32 v66, v66
	s_nop 0
	v_mul_f32_e32 v66, v73, v66
	v_mul_f32_e32 v69, v69, v66
	v_cvt_pk_bf16_f32 v66, v74, v75
	v_cvt_pk_bf16_f32 v67, v76, v77
	v_cvt_pk_bf16_f32 v68, v78, v79
	v_cvt_pk_bf16_f32 v69, v72, v69
	global_store_dwordx4 v[70:71], v[66:69], off sc1
	s_nop 1
	v_mul_f32_e32 v68, 0xbfb8aa3b, v62
	v_exp_f32_e32 v68, v68
	v_add_u32_e32 v66, 0x80, v145
	v_mad_i64_i32 v[66:67], s[18:19], v66, s27, v[140:141]
	v_add_f32_e32 v68, 1.0, v68
	v_rcp_f32_e32 v68, v68
	s_nop 0
	v_mul_f32_e32 v62, v62, v68
	v_mul_f32_e32 v58, v58, v62
	v_mul_f32_e32 v62, 0xbfb8aa3b, v63
	v_exp_f32_e32 v62, v62
	s_nop 0
	v_add_f32_e32 v62, 1.0, v62
	v_rcp_f32_e32 v62, v62
	s_nop 0
	v_mul_f32_e32 v62, v63, v62
	v_mul_f32_e32 v59, v59, v62
	v_mul_f32_e32 v62, 0xbfb8aa3b, v64
	v_exp_f32_e32 v62, v62
	s_nop 0
	v_add_f32_e32 v62, 1.0, v62
	v_rcp_f32_e32 v62, v62
	s_nop 0
	v_mul_f32_e32 v62, v64, v62
	v_mul_f32_e32 v60, v60, v62
	v_mul_f32_e32 v62, 0xbfb8aa3b, v65
	v_exp_f32_e32 v62, v62
	s_nop 0
	v_add_f32_e32 v62, 1.0, v62
	v_rcp_f32_e32 v62, v62
	s_nop 0
	v_mul_f32_e32 v62, v65, v62
	v_mul_f32_e32 v61, v61, v62
	v_mul_f32_e32 v62, 0xbfb8aa3b, v54
	v_exp_f32_e32 v62, v62
	s_nop 0
	v_add_f32_e32 v62, 1.0, v62
	v_rcp_f32_e32 v62, v62
	s_nop 0
	v_mul_f32_e32 v54, v54, v62
	v_mul_f32_e32 v62, v50, v54
	v_mul_f32_e32 v50, 0xbfb8aa3b, v55
	v_exp_f32_e32 v50, v50
	s_nop 0
	v_add_f32_e32 v50, 1.0, v50
	v_rcp_f32_e32 v50, v50
	s_nop 0
	v_mul_f32_e32 v50, v55, v50
	v_mul_f32_e32 v63, v51, v50
	v_mul_f32_e32 v50, 0xbfb8aa3b, v56
	v_exp_f32_e32 v50, v50
	v_lshl_add_u64 v[54:55], v[66:67], 0, v[114:115]
	v_add_f32_e32 v50, 1.0, v50
	v_rcp_f32_e32 v50, v50
	s_nop 0
	v_mul_f32_e32 v50, v56, v50
	v_mul_f32_e32 v56, v52, v50
	v_mul_f32_e32 v50, 0xbfb8aa3b, v57
	v_exp_f32_e32 v50, v50
	s_nop 0
	v_add_f32_e32 v50, 1.0, v50
	v_rcp_f32_e32 v50, v50
	s_nop 0
	v_mul_f32_e32 v50, v57, v50
	v_mul_f32_e32 v53, v53, v50
	v_cvt_pk_bf16_f32 v50, v58, v59
	v_cvt_pk_bf16_f32 v51, v60, v61
	v_cvt_pk_bf16_f32 v52, v62, v63
	v_cvt_pk_bf16_f32 v53, v56, v53
	global_store_dwordx4 v[54:55], v[50:53], off sc1
	s_nop 1
	v_mul_f32_e32 v52, 0xbfb8aa3b, v46
	v_exp_f32_e32 v52, v52
	v_add_u32_e32 v50, 0x90, v145
	v_mad_i64_i32 v[50:51], s[18:19], v50, s27, v[140:141]
	v_add_f32_e32 v52, 1.0, v52
	v_rcp_f32_e32 v52, v52
	s_nop 0
	v_mul_f32_e32 v46, v46, v52
	v_mul_f32_e32 v42, v42, v46
	v_mul_f32_e32 v46, 0xbfb8aa3b, v47
	v_exp_f32_e32 v46, v46
	s_nop 0
	v_add_f32_e32 v46, 1.0, v46
	v_rcp_f32_e32 v46, v46
	s_nop 0
	v_mul_f32_e32 v46, v47, v46
	v_mul_f32_e32 v43, v43, v46
	v_mul_f32_e32 v46, 0xbfb8aa3b, v48
	v_exp_f32_e32 v46, v46
	s_nop 0
	v_add_f32_e32 v46, 1.0, v46
	v_rcp_f32_e32 v46, v46
	s_nop 0
	v_mul_f32_e32 v46, v48, v46
	v_mul_f32_e32 v44, v44, v46
	v_mul_f32_e32 v46, 0xbfb8aa3b, v49
; __device__ __forceinline__ unsigned cvt_pk_bf16(float lo, float hi) { unsigned r; asm volatile("v_cvt_pk_bf16_f32 %0, %1, %2" : "=v"(r) : "v"(lo), "v"(hi)); return r; }
; __device__ __forceinline__ float siluf_(float x) { return x * __builtin_amdgcn_rcpf(1.0f + __expf(-x)); }
;     __device__ __forceinline__ void operator()(const f32x4 (&acc)[2][2][4][2], const Unit& u, int wr, int wc, int fr, int fq) const {
;         const int row0 = u.pm * BM + wr * 64 + fr, col0 = u.pn * 128 + wc * 32 + 8 * fq;
; #pragma unroll
;         for (int ai = 0; ai < 2; ++ai)
; #pragma unroll
;             for (int m = 0; m < 4; ++m) { bf16_t* rowp = O + (size_t)(row0 + ai * HALF + m * 16) * DFF + col0;
;                 float r[8];
; #pragma unroll
;                 for (int n = 0; n < 2; ++n)
; #pragma unroll
;                     for (int j = 0; j < 4; ++j) r[n * 4 + j] = siluf_(acc[ai][0][m][n][j]) * acc[ai][1][m][n][j];
;                 u32x4 w; w.x = cvt_pk_bf16(r[0], r[1]); w.y = cvt_pk_bf16(r[2], r[3]); w.z = cvt_pk_bf16(r[4], r[5]); w.w = cvt_pk_bf16(r[6], r[7]);
;                 *(u32x4*)rowp = w; }
;     }
	v_exp_f32_e32 v46, v46
	s_nop 0
	v_add_f32_e32 v46, 1.0, v46
	v_rcp_f32_e32 v46, v46
	s_nop 0
	v_mul_f32_e32 v46, v49, v46
	v_mul_f32_e32 v45, v45, v46
	v_mul_f32_e32 v46, 0xbfb8aa3b, v38
	v_exp_f32_e32 v46, v46
	s_nop 0
	v_add_f32_e32 v46, 1.0, v46
	v_rcp_f32_e32 v46, v46
	s_nop 0
	v_mul_f32_e32 v38, v38, v46
	v_mul_f32_e32 v46, v34, v38
	v_mul_f32_e32 v34, 0xbfb8aa3b, v39
	v_exp_f32_e32 v34, v34
	s_nop 0
	v_add_f32_e32 v34, 1.0, v34
	v_rcp_f32_e32 v34, v34
	s_nop 0
	v_mul_f32_e32 v34, v39, v34
	v_mul_f32_e32 v47, v35, v34
	v_mul_f32_e32 v34, 0xbfb8aa3b, v40
	v_exp_f32_e32 v34, v34
	v_lshl_add_u64 v[38:39], v[50:51], 0, v[114:115]
	v_add_f32_e32 v34, 1.0, v34
	v_rcp_f32_e32 v34, v34
	s_nop 0
	v_mul_f32_e32 v34, v40, v34
	v_mul_f32_e32 v40, v36, v34
	v_mul_f32_e32 v34, 0xbfb8aa3b, v41
	v_exp_f32_e32 v34, v34
	s_nop 0
	v_add_f32_e32 v34, 1.0, v34
	v_rcp_f32_e32 v34, v34
	s_nop 0
	v_mul_f32_e32 v34, v41, v34
	v_mul_f32_e32 v37, v37, v34
	v_cvt_pk_bf16_f32 v34, v42, v43
	v_cvt_pk_bf16_f32 v35, v44, v45
	v_cvt_pk_bf16_f32 v36, v46, v47
	v_cvt_pk_bf16_f32 v37, v40, v37
	global_store_dwordx4 v[38:39], v[34:37], off sc1
	s_nop 1
	v_mul_f32_e32 v36, 0xbfb8aa3b, v28
	v_exp_f32_e32 v36, v36
	v_add_u32_e32 v34, 0xa0, v145
	v_mad_i64_i32 v[34:35], s[18:19], v34, s27, v[140:141]
	v_add_f32_e32 v36, 1.0, v36
	v_rcp_f32_e32 v36, v36
	s_nop 0
	v_mul_f32_e32 v28, v28, v36
	v_mul_f32_e32 v24, v24, v28
	v_mul_f32_e32 v28, 0xbfb8aa3b, v29
	v_exp_f32_e32 v28, v28
	s_nop 0
	v_add_f32_e32 v28, 1.0, v28
	v_rcp_f32_e32 v28, v28
	s_nop 0
	v_mul_f32_e32 v28, v29, v28
	v_mul_f32_e32 v25, v25, v28
	v_mul_f32_e32 v28, 0xbfb8aa3b, v30
	v_exp_f32_e32 v28, v28
	s_nop 0
	v_add_f32_e32 v28, 1.0, v28
	v_rcp_f32_e32 v28, v28
	s_nop 0
	v_mul_f32_e32 v28, v30, v28
	v_mul_f32_e32 v26, v26, v28
	v_mul_f32_e32 v28, 0xbfb8aa3b, v31
	v_exp_f32_e32 v28, v28
	s_nop 0
	v_add_f32_e32 v28, 1.0, v28
	v_rcp_f32_e32 v28, v28
	s_nop 0
	v_mul_f32_e32 v28, v31, v28
	v_mul_f32_e32 v27, v27, v28
	v_mul_f32_e32 v28, 0xbfb8aa3b, v20
	v_exp_f32_e32 v28, v28
	s_nop 0
	v_add_f32_e32 v28, 1.0, v28
	v_rcp_f32_e32 v28, v28
	s_nop 0
	v_mul_f32_e32 v20, v20, v28
	v_mul_f32_e32 v28, v16, v20
	v_mul_f32_e32 v16, 0xbfb8aa3b, v21
	v_exp_f32_e32 v16, v16
	s_nop 0
	v_add_f32_e32 v16, 1.0, v16
	v_rcp_f32_e32 v16, v16
	s_nop 0
	v_mul_f32_e32 v16, v21, v16
	v_mul_f32_e32 v29, v17, v16
	v_mul_f32_e32 v16, 0xbfb8aa3b, v22
	v_exp_f32_e32 v16, v16
	v_lshl_add_u64 v[20:21], v[34:35], 0, v[114:115]
	v_add_f32_e32 v16, 1.0, v16
	v_rcp_f32_e32 v16, v16
	s_nop 0
	v_mul_f32_e32 v16, v22, v16
	v_mul_f32_e32 v22, v18, v16
	v_mul_f32_e32 v16, 0xbfb8aa3b, v23
	v_exp_f32_e32 v16, v16
	s_nop 0
	v_add_f32_e32 v16, 1.0, v16
	v_rcp_f32_e32 v16, v16
	s_nop 0
	v_mul_f32_e32 v16, v23, v16
	v_mul_f32_e32 v19, v19, v16
	v_cvt_pk_bf16_f32 v16, v24, v25
	v_cvt_pk_bf16_f32 v17, v26, v27
	v_cvt_pk_bf16_f32 v18, v28, v29
	v_cvt_pk_bf16_f32 v19, v22, v19
	global_store_dwordx4 v[20:21], v[16:19], off sc1
	s_nop 1
	v_mul_f32_e32 v18, 0xbfb8aa3b, v12
	v_exp_f32_e32 v18, v18
	v_add_u32_e32 v16, 0xb0, v145
	v_mad_i64_i32 v[16:17], s[18:19], v16, s27, v[140:141]
	v_add_f32_e32 v18, 1.0, v18
	v_rcp_f32_e32 v18, v18
	s_mov_b64 s[18:19], -1
	v_mul_f32_e32 v12, v12, v18
	v_mul_f32_e32 v8, v8, v12
	v_mul_f32_e32 v12, 0xbfb8aa3b, v13
	v_exp_f32_e32 v12, v12
	s_nop 0
	v_add_f32_e32 v12, 1.0, v12
	v_rcp_f32_e32 v12, v12
	s_nop 0
	v_mul_f32_e32 v12, v13, v12
	v_mul_f32_e32 v9, v9, v12
	v_mul_f32_e32 v12, 0xbfb8aa3b, v14
	v_exp_f32_e32 v12, v12
	s_nop 0
	v_add_f32_e32 v12, 1.0, v12
	v_rcp_f32_e32 v12, v12
	s_nop 0
	v_mul_f32_e32 v12, v14, v12
	v_mul_f32_e32 v10, v10, v12
	v_mul_f32_e32 v12, 0xbfb8aa3b, v15
	v_exp_f32_e32 v12, v12
	s_nop 0
	v_add_f32_e32 v12, 1.0, v12
	v_rcp_f32_e32 v12, v12
	s_nop 0
	v_mul_f32_e32 v12, v15, v12
	v_mul_f32_e32 v11, v11, v12
	v_mul_f32_e32 v12, 0xbfb8aa3b, v4
	v_exp_f32_e32 v12, v12
	s_nop 0
	v_add_f32_e32 v12, 1.0, v12
	v_rcp_f32_e32 v12, v12
	s_nop 0
	v_mul_f32_e32 v4, v4, v12
	v_mul_f32_e32 v12, v0, v4
	v_mul_f32_e32 v0, 0xbfb8aa3b, v5
	v_exp_f32_e32 v0, v0
	s_nop 0
	v_add_f32_e32 v0, 1.0, v0
	v_rcp_f32_e32 v0, v0
	s_nop 0
	v_mul_f32_e32 v0, v5, v0
	v_mul_f32_e32 v13, v1, v0
	v_mul_f32_e32 v0, 0xbfb8aa3b, v6
	v_exp_f32_e32 v0, v0
	v_lshl_add_u64 v[4:5], v[16:17], 0, v[114:115]
	v_add_f32_e32 v0, 1.0, v0
	v_rcp_f32_e32 v0, v0
	s_nop 0
	v_mul_f32_e32 v0, v6, v0
	v_mul_f32_e32 v6, v2, v0
	v_mul_f32_e32 v0, 0xbfb8aa3b, v7
	v_exp_f32_e32 v0, v0
	s_nop 0
	v_add_f32_e32 v0, 1.0, v0
	v_rcp_f32_e32 v0, v0
	s_nop 0
	v_mul_f32_e32 v0, v7, v0
	v_mul_f32_e32 v3, v3, v0
	v_cvt_pk_bf16_f32 v0, v8, v9
	v_cvt_pk_bf16_f32 v1, v10, v11
	v_cvt_pk_bf16_f32 v2, v12, v13
	v_cvt_pk_bf16_f32 v3, v6, v3
	global_store_dwordx4 v[4:5], v[0:3], off sc1
	s_cbranch_vccnz .LBB0_198
	s_andn2_b64 vcc, exec, s[20:21]
	s_cbranch_vccnz .LBB0_197
	s_barrier
	s_branch .LBB0_197

; __device__ __forceinline__ unsigned xb_ld(unsigned* p)              { return __hip_atomic_load(p, __ATOMIC_RELAXED, __HIP_MEMORY_SCOPE_AGENT); }
; __device__ __forceinline__ unsigned xb_add(unsigned* p, unsigned v) { return __hip_atomic_fetch_add(p, v, __ATOMIC_RELAXED, __HIP_MEMORY_SCOPE_AGENT); }
; #define XB_SPIN(cond, bar) do { unsigned _sp = 0; while (cond) { __builtin_amdgcn_s_sleep(1); \
;     if ((++_sp & 255u) == 0u) { if (xb_ld(&(bar)[XB_TMO])) break; if (_sp > XB_SPIN_CAP) { atomicAdd(&(bar)[XB_TMO], 1u); break; } } } } while (0)
; __device__ __forceinline__ void xcd_barrier(const XcdBarrier& b) {
;     ...
;     if (threadIdx.x == 0) {
;         unsigned* bar = b.bar;
;         __builtin_amdgcn_s_waitcnt(0);
;         unsigned nloc = b.st[0], nx = b.st[1];
;         if (nloc == 0u) { xcd_barrier_complete(bar, b.x, nloc, nx); b.st[0] = nloc; b.st[1] = nx; }
;         const unsigned old = xb_add(&bar[XB_XSUB(b.x)], 1u);
;         const unsigned gen = old / nloc;
;         if (old + 1u == (gen + 1u) * nloc) {
;             __builtin_amdgcn_fence(__ATOMIC_RELEASE, "agent");
;             asm volatile("s_waitcnt vmcnt(0)" ::: "memory");
;             const unsigned og = xb_add(&bar[XB_TOP], 1u);
;             const unsigned tg = og / nx;
;             if (og + 1u == (tg + 1u) * nx) xb_add(&bar[XB_TOPGEN], 1u);
;             else XB_SPIN(xb_ld(&bar[XB_TOPGEN]) == tg, bar);
;             __builtin_amdgcn_fence(__ATOMIC_ACQUIRE, "agent");
;             xb_add(&bar[XB_XGEN(b.x)], 1u);
;             asm volatile("s_waitcnt vmcnt(0)" ::: "memory");
;         } else {
;             XB_SPIN(xb_ld(&bar[XB_XGEN(b.x)]) == gen, bar);
.LBB0_274:
	s_mov_b64 s[20:21], exec
	v_mbcnt_lo_u32_b32 v1, s20, 0
	v_mbcnt_hi_u32_b32 v1, s21, v1
	v_cmp_eq_u32_e32 vcc, 0, v1
	s_and_saveexec_b64 s[18:19], vcc
	s_cbranch_execz .LBB0_276
	s_bcnt1_i32_b64 s0, s[20:21]
	v_mov_b32_e32 v3, s0
	v_readlane_b32 s0, v253, 8
	v_readlane_b32 s1, v253, 9
	s_nop 4
	global_atomic_add v3, v33, v3, s[0:1] sc0
	buffer_inv sc1
.LBB0_276:
	s_or_b64 exec, exec, s[18:19]
	v_cvt_f32_u32_e32 v4, v2
	s_waitcnt vmcnt(1)
	v_readfirstlane_b32 s0, v3
	v_sub_u32_e32 v3, 0, v2
	v_rcp_iflag_f32_e32 v4, v4
	v_add_u32_e32 v5, s0, v1
	v_mul_f32_e32 v4, 0x4f7ffffe, v4
	v_cvt_u32_f32_e32 v4, v4
	v_mul_lo_u32 v1, v3, v4
	v_mul_hi_u32 v1, v4, v1
	v_add_u32_e32 v1, v4, v1
	v_mul_hi_u32 v1, v5, v1
	v_mul_lo_u32 v3, v1, v2
	v_sub_u32_e32 v3, v5, v3
	v_add_u32_e32 v4, 1, v1
	v_cmp_ge_u32_e32 vcc, v3, v2
	s_nop 1
	v_cndmask_b32_e32 v1, v1, v4, vcc
	v_sub_u32_e32 v4, v3, v2
	v_cndmask_b32_e32 v3, v3, v4, vcc
	v_add_u32_e32 v4, 1, v1
	v_cmp_ge_u32_e32 vcc, v3, v2
	v_add_u32_e32 v3, 1, v5
	s_nop 0
	v_cndmask_b32_e32 v1, v1, v4, vcc
	v_mul_lo_u32 v4, v2, v1
	v_add_u32_e32 v2, v4, v2
	v_cmp_ne_u32_e32 vcc, v3, v2
	s_and_saveexec_b64 s[0:1], vcc
	s_xor_b64 s[20:21], exec, s[0:1]
	s_cbranch_execz .LBB0_290
	v_readlane_b32 s0, v253, 10
	v_readlane_b32 s1, v253, 11
	s_waitcnt lgkmcnt(0)
	s_nop 3
	global_load_dword v0, v33, s[0:1] sc1
	s_waitcnt vmcnt(0)
	v_cmp_eq_u32_e32 vcc, v0, v1
	s_and_saveexec_b64 s[18:19], vcc
	s_cbranch_execz .LBB0_289
	s_mov_b32 s0, 1
	s_mov_b64 s[22:23], 0
	s_branch .LBB0_280

; __device__ __forceinline__ unsigned xb_ld(unsigned* p)              { return __hip_atomic_load(p, __ATOMIC_RELAXED, __HIP_MEMORY_SCOPE_AGENT); }
; #define XB_SPIN(cond, bar) do { unsigned _sp = 0; while (cond) { __builtin_amdgcn_s_sleep(1); \
;     if ((++_sp & 255u) == 0u) { if (xb_ld(&(bar)[XB_TMO])) break; if (_sp > XB_SPIN_CAP) { atomicAdd(&(bar)[XB_TMO], 1u); break; } } } } while (0)
; __device__ __forceinline__ void xcd_barrier(const XcdBarrier& b) {
;     ...
;         } else {
;             XB_SPIN(xb_ld(&bar[XB_XGEN(b.x)]) == gen, bar);
;             __builtin_amdgcn_fence(__ATOMIC_ACQUIRE, "agent");
;             asm volatile("s_waitcnt vmcnt(0)" ::: "memory");
.LBB0_289:
	s_or_b64 exec, exec, s[18:19]
	s_waitcnt vmcnt(0)
	s_waitcnt vmcnt(0)

; __device__ __forceinline__ unsigned xb_ld(unsigned* p)              { return __hip_atomic_load(p, __ATOMIC_RELAXED, __HIP_MEMORY_SCOPE_AGENT); }
; __device__ __forceinline__ unsigned xb_add(unsigned* p, unsigned v) { return __hip_atomic_fetch_add(p, v, __ATOMIC_RELAXED, __HIP_MEMORY_SCOPE_AGENT); }
; #define XB_SPIN(cond, bar) do { unsigned _sp = 0; while (cond) { __builtin_amdgcn_s_sleep(1); \
;     if ((++_sp & 255u) == 0u) { if (xb_ld(&(bar)[XB_TMO])) break; if (_sp > XB_SPIN_CAP) { atomicAdd(&(bar)[XB_TMO], 1u); break; } } } } while (0)
; __device__ __forceinline__ void xcd_barrier(const XcdBarrier& b) {
;     ...
;             if (og + 1u == (tg + 1u) * nx) xb_add(&bar[XB_TOPGEN], 1u);
;             else XB_SPIN(xb_ld(&bar[XB_TOPGEN]) == tg, bar);
;             __builtin_amdgcn_fence(__ATOMIC_ACQUIRE, "agent");
;             xb_add(&bar[XB_XGEN(b.x)], 1u);
;             asm volatile("s_waitcnt vmcnt(0)" ::: "memory");
.LBB0_307:
	s_or_b64 exec, exec, s[18:19]
	s_mov_b64 s[18:19], exec
	v_mbcnt_lo_u32_b32 v0, s18, 0
	v_mbcnt_hi_u32_b32 v0, s19, v0
	v_cmp_eq_u32_e32 vcc, 0, v0
	s_waitcnt vmcnt(0)
	s_and_saveexec_b64 s[20:21], vcc
	s_cbranch_execz .LBB0_309
	s_bcnt1_i32_b64 s0, s[18:19]
	v_mov_b32_e32 v0, s0
	v_readlane_b32 s0, v253, 10
	v_readlane_b32 s1, v253, 11
	s_nop 4
	global_atomic_add v33, v0, s[0:1]

; __device__ __forceinline__ unsigned cvt_pk_bf16(float lo, float hi) { unsigned r; asm volatile("v_cvt_pk_bf16_f32 %0, %1, %2" : "=v"(r) : "v"(lo), "v"(hi)); return r; }
;     __device__ __forceinline__ void operator()(const f32x4 (&acc)[2][2][4][2], const Unit& u, int wr, int wc, int fr, int fq) const {
;         const int row0 = u.pm * BM + wr * 64 + fr, col0 = u.pn * BM + wc * 32 + 8 * fq;
;         bf16_t* ob = u.slab < 0 ? O : SL + (size_t)u.slab * (1024 * 1024) - (size_t)ML * 1024;
; #pragma unroll
;         for (int ai = 0; ai < 2; ++ai)
; #pragma unroll
;             for (int m = 0; m < 4; ++m) { bf16_t* rowp = ob + (size_t)(row0 + ai * HALF + m * 16) * 1024 + col0;
; #pragma unroll
;                 for (int bj = 0; bj < 2; ++bj) { const f32x4 v0 = acc[ai][bj][m][0], v1 = acc[ai][bj][m][1];
;                     u32x4 w; w.x = cvt_pk_bf16(v0[0], v0[1]); w.y = cvt_pk_bf16(v0[2], v0[3]); w.z = cvt_pk_bf16(v1[0], v1[1]); w.w = cvt_pk_bf16(v1[2], v1[3]);
;                     *(u32x4*)(rowp + bj * HALF) = w; } }
;     }
.LBB0_336:
	v_mov_b32_e32 v141, v142
	s_lshl_b32 s18, s62, 8
	v_ashrrev_i32_e32 v140, 1, v141
	v_and_b32_e32 v140, -8, v140
	s_or_b32 s18, s18, s56
	v_add_u32_e32 v140, s18, v140
	s_lshl_b64 s[18:19], s[8:9], 21
	s_add_u32 s18, s4, s18
	s_addc_u32 s19, s5, s19
	s_add_u32 s18, s18, 0xfe000000
	s_addc_u32 s19, s19, -1
	s_cmp_lt_i32 s8, 0
	v_and_or_b32 v141, v141, 15, s47
	s_cselect_b32 s8, s15, s19
	s_cselect_b32 s18, s14, s18
	v_lshl_add_u32 v148, s60, 8, v141
	v_mov_b32_e32 v146, s18
	v_mov_b32_e32 v147, s8
	v_ashrrev_i32_e32 v141, 31, v140
	v_ashrrev_i32_e32 v149, 31, v148
	v_lshl_add_u64 v[146:147], v[140:141], 1, v[146:147]
	v_lshlrev_b64 v[140:141], 11, v[148:149]
	v_lshl_add_u64 v[140:141], v[146:147], 0, v[140:141]
	v_cvt_pk_bf16_f32 v126, v126, v127
	v_cvt_pk_bf16_f32 v127, v128, v129
	v_cvt_pk_bf16_f32 v128, v122, v123
	v_cvt_pk_bf16_f32 v129, v124, v125
	global_store_dwordx4 v[140:141], v[126:129], off sc1
	v_cvt_pk_bf16_f32 v114, v114, v115
	v_cvt_pk_bf16_f32 v115, v116, v117
	v_cvt_pk_bf16_f32 v116, v106, v107
	v_or_b32_e32 v106, 16, v148
	v_ashrrev_i32_e32 v107, 31, v106
	v_lshlrev_b64 v[106:107], 11, v[106:107]
	v_cvt_pk_bf16_f32 v117, v108, v109
	global_store_dwordx4 v[140:141], v[114:117], off offset:256 sc1
	s_mov_b32 s8, 0x40000
	s_mov_b64 s[18:19], 0x40000
	v_lshl_add_u64 v[114:115], v[146:147], 0, v[106:107]
	v_cvt_pk_bf16_f32 v106, v118, v119
	v_cvt_pk_bf16_f32 v107, v120, v121
	v_cvt_pk_bf16_f32 v108, v110, v111
	v_cvt_pk_bf16_f32 v109, v112, v113
	global_store_dwordx4 v[114:115], v[106:109], off sc1
	v_cvt_pk_bf16_f32 v98, v98, v99
	v_cvt_pk_bf16_f32 v99, v100, v101
	v_cvt_pk_bf16_f32 v100, v90, v91
	v_or_b32_e32 v90, 32, v148
	v_ashrrev_i32_e32 v91, 31, v90
	v_lshlrev_b64 v[90:91], 11, v[90:91]
	v_cvt_pk_bf16_f32 v101, v92, v93
	global_store_dwordx4 v[114:115], v[98:101], off offset:256 sc1
	s_nop 1
	v_lshl_add_u64 v[98:99], v[146:147], 0, v[90:91]
	v_cvt_pk_bf16_f32 v90, v102, v103
	v_cvt_pk_bf16_f32 v91, v104, v105
	v_cvt_pk_bf16_f32 v92, v94, v95
	v_cvt_pk_bf16_f32 v93, v96, v97
	global_store_dwordx4 v[98:99], v[90:93], off sc1
	v_cvt_pk_bf16_f32 v82, v82, v83
	v_cvt_pk_bf16_f32 v83, v84, v85
	v_cvt_pk_bf16_f32 v84, v74, v75
	v_or_b32_e32 v74, 48, v148
	v_ashrrev_i32_e32 v75, 31, v74
	v_lshlrev_b64 v[74:75], 11, v[74:75]
	v_cvt_pk_bf16_f32 v85, v76, v77
	global_store_dwordx4 v[98:99], v[82:85], off offset:256 sc1
	s_nop 1
	v_lshl_add_u64 v[82:83], v[146:147], 0, v[74:75]
	v_cvt_pk_bf16_f32 v74, v86, v87
	v_cvt_pk_bf16_f32 v75, v88, v89
	v_cvt_pk_bf16_f32 v76, v78, v79
	v_cvt_pk_bf16_f32 v77, v80, v81
	global_store_dwordx4 v[82:83], v[74:77], off sc1
	v_cvt_pk_bf16_f32 v70, v70, v71
	v_cvt_pk_bf16_f32 v71, v72, v73
	v_cvt_pk_bf16_f32 v72, v66, v67
	v_cvt_pk_bf16_f32 v73, v68, v69
	global_store_dwordx4 v[82:83], v[70:73], off offset:256 sc1
	v_cvt_pk_bf16_f32 v62, v62, v63
	v_cvt_pk_bf16_f32 v63, v64, v65
	v_cvt_pk_bf16_f32 v64, v58, v59
	v_add_co_u32_e32 v58, vcc, s8, v140
	v_lshl_add_u64 v[66:67], v[140:141], 0, s[18:19]
	s_nop 0
	v_addc_co_u32_e32 v59, vcc, 0, v141, vcc
	v_cvt_pk_bf16_f32 v65, v60, v61
	global_store_dwordx4 v[58:59], v[62:65], off sc1
	v_cvt_pk_bf16_f32 v50, v50, v51
	v_cvt_pk_bf16_f32 v51, v52, v53
	v_cvt_pk_bf16_f32 v52, v42, v43
	v_cvt_pk_bf16_f32 v53, v44, v45
	global_store_dwordx4 v[66:67], v[50:53], off offset:256 sc1
	s_mov_b64 s[18:19], 0x48000
	v_cvt_pk_bf16_f32 v42, v54, v55
	v_cvt_pk_bf16_f32 v43, v56, v57
	v_cvt_pk_bf16_f32 v44, v46, v47
	v_add_co_u32_e32 v46, vcc, s93, v140
	v_lshl_add_u64 v[50:51], v[140:141], 0, s[18:19]
	s_nop 0
	v_addc_co_u32_e32 v47, vcc, 0, v141, vcc
	s_mov_b32 s8, 0x50000
	v_cvt_pk_bf16_f32 v45, v48, v49
	global_store_dwordx4 v[46:47], v[42:45], off sc1
	v_cvt_pk_bf16_f32 v34, v34, v35
	v_cvt_pk_bf16_f32 v35, v36, v37
	v_cvt_pk_bf16_f32 v36, v24, v25
	v_cvt_pk_bf16_f32 v37, v26, v27
	global_store_dwordx4 v[50:51], v[34:37], off offset:256 sc1
	s_mov_b64 s[18:19], 0x50000
	v_cvt_pk_bf16_f32 v24, v38, v39
	v_cvt_pk_bf16_f32 v25, v40, v41
	v_cvt_pk_bf16_f32 v26, v28, v29
	v_add_co_u32_e32 v28, vcc, s8, v140
	v_lshl_add_u64 v[34:35], v[140:141], 0, s[18:19]
	s_nop 0
	v_addc_co_u32_e32 v29, vcc, 0, v141, vcc
	s_mov_b32 s8, 0x58000
	v_cvt_pk_bf16_f32 v27, v30, v31
	global_store_dwordx4 v[28:29], v[24:27], off sc1
	v_cvt_pk_bf16_f32 v16, v16, v17
	v_cvt_pk_bf16_f32 v17, v18, v19
	v_cvt_pk_bf16_f32 v18, v8, v9
	v_cvt_pk_bf16_f32 v19, v10, v11
	global_store_dwordx4 v[34:35], v[16:19], off offset:256 sc1
	v_cvt_pk_bf16_f32 v8, v20, v21
	v_cvt_pk_bf16_f32 v9, v22, v23
	v_cvt_pk_bf16_f32 v10, v12, v13
	v_add_co_u32_e32 v12, vcc, s8, v140
	s_mov_b64 s[18:19], 0x58000
	s_nop 0
	v_addc_co_u32_e32 v13, vcc, 0, v141, vcc
	v_lshl_add_u64 v[16:17], v[140:141], 0, s[18:19]
	s_andn2_b64 vcc, exec, s[48:49]
	s_mov_b64 s[18:19], -1
	v_cvt_pk_bf16_f32 v11, v14, v15
	global_store_dwordx4 v[12:13], v[8:11], off sc1
	v_cvt_pk_bf16_f32 v4, v4, v5
	v_cvt_pk_bf16_f32 v5, v6, v7
	v_cvt_pk_bf16_f32 v6, v0, v1
	v_cvt_pk_bf16_f32 v7, v2, v3
	global_store_dwordx4 v[16:17], v[4:7], off offset:256 sc1
	s_cbranch_vccnz .LBB0_322
	s_andn2_b64 vcc, exec, s[16:17]
	s_cbranch_vccnz .LBB0_321
	s_barrier
	s_branch .LBB0_321

; __device__ __forceinline__ unsigned cvt_pk_bf16(float lo, float hi) { unsigned r; asm volatile("v_cvt_pk_bf16_f32 %0, %1, %2" : "=v"(r) : "v"(lo), "v"(hi)); return r; }
; __device__ __forceinline__ float bflo(unsigned w) { return __uint_as_float(w << 16); }
; __device__ __forceinline__ float bfhi(unsigned w) { return __uint_as_float(w & 0xffff0000u); }
;     __device__ __forceinline__ void operator()(const f32x4 (&acc)[2][2][4][2], const Unit& u, int wr, int wc, int fr, int fq) const {
;         const int row0 = u.pm * BM + wr * 64 + fr, col0 = u.pn * BM + wc * 32 + 8 * fq;
;         bf16_t* gout = u.slab < 0 ? G : SL + (size_t)u.slab * (1024 * 1024) - (size_t)ML * 1024;
; #pragma unroll
;         for (int ai = 0; ai < 2; ++ai)
; #pragma unroll
;             for (int m = 0; m < 4; ++m) { const size_t r = (size_t)(row0 + ai * HALF + m * 16);
; #pragma unroll
;                 for (int bj = 0; bj < 2; ++bj) { const u32x4 lb = *(const u32x4*)(GL + r * 2048 + 1024 + col0 + bj * HALF); float o[8];
; #pragma unroll
;                     for (int n = 0; n < 2; ++n)
; #pragma unroll
;                         for (int j = 0; j < 4; ++j) { const int e = n * 4 + j; const unsigned wb = lb[e >> 1]; const float b = (e & 1) ? bfhi(wb) : bflo(wb);
;                             o[e] = acc[ai][bj][m][n][j] * __builtin_amdgcn_rcpf(1.0f + __expf(-b)); }
;                     u32x4 w; w.x = cvt_pk_bf16(o[0], o[1]); w.y = cvt_pk_bf16(o[2], o[3]); w.z = cvt_pk_bf16(o[4], o[5]); w.w = cvt_pk_bf16(o[6], o[7]);
;                     *(u32x4*)(gout + r * 1024 + col0 + bj * HALF) = w; asm volatile("" ::: "memory"); } }
;     }
.LBB0_408:
	s_lshl_b64 s[0:1], s[8:9], 21
	v_readlane_b32 s22, v255, 26
	v_readlane_b32 s23, v255, 27
	s_add_u32 s0, s22, s0
	s_addc_u32 s1, s23, s1
	s_add_u32 s0, s0, 0xfe000000
	v_mov_b32_e32 v131, v167
	s_addc_u32 s1, s1, -1
	v_readlane_b32 s22, v255, 22
	s_cmp_lt_i32 s8, 0
	v_readlane_b32 s23, v255, 23
	s_cselect_b32 s1, s23, s1
	s_cselect_b32 s0, s22, s0
	v_ashrrev_i32_e32 v130, 1, v131
	s_lshl_b32 s22, s88, 8
	v_and_or_b32 v131, v131, 15, s4
	v_and_b32_e32 v130, -8, v130
	s_or_b32 s22, s22, s5
	v_lshl_add_u32 v134, s58, 8, v131
	v_add_u32_e32 v130, s22, v130
	v_ashrrev_i32_e32 v135, 31, v134
	v_ashrrev_i32_e32 v131, 31, v130
	v_lshlrev_b64 v[152:153], 12, v[134:135]
	v_lshlrev_b64 v[130:131], 1, v[130:131]
	v_lshl_add_u64 v[152:153], s[14:15], 0, v[152:153]
	v_lshl_add_u64 v[152:153], v[152:153], 0, v[130:131]
	global_load_dwordx4 v[154:157], v[152:153], off offset:2048
	v_lshlrev_b64 v[136:137], 11, v[134:135]
	v_lshl_add_u64 v[132:133], s[0:1], 0, v[130:131]
	v_lshl_add_u64 v[136:137], v[132:133], 0, v[136:137]
	s_mov_b64 s[22:23], -1
	s_andn2_b64 vcc, exec, s[20:21]
	s_waitcnt vmcnt(0)
	v_lshlrev_b32_e32 v135, 16, v154
	v_mul_f32_e32 v135, 0xbfb8aa3b, v135
	v_exp_f32_e32 v135, v135
	s_nop 0
	v_add_f32_e32 v135, 1.0, v135
	v_rcp_f32_e32 v135, v135
	s_nop 0
	v_mul_f32_e32 v0, v0, v135
	v_and_b32_e32 v135, 0xffff0000, v154
	v_mul_f32_e32 v135, 0xbfb8aa3b, v135
	v_exp_f32_e32 v135, v135
	s_nop 0
	v_add_f32_e32 v135, 1.0, v135
	v_rcp_f32_e32 v135, v135
	s_nop 0
	v_mul_f32_e32 v1, v1, v135
	v_lshlrev_b32_e32 v135, 16, v155
	v_mul_f32_e32 v135, 0xbfb8aa3b, v135
	v_exp_f32_e32 v135, v135
	v_cvt_pk_bf16_f32 v0, v0, v1
	s_nop 0
	v_add_f32_e32 v135, 1.0, v135
	v_rcp_f32_e32 v135, v135
	s_nop 0
	v_mul_f32_e32 v2, v2, v135
	v_and_b32_e32 v135, 0xffff0000, v155
	v_mul_f32_e32 v135, 0xbfb8aa3b, v135
	v_exp_f32_e32 v135, v135
	s_nop 0
	v_add_f32_e32 v135, 1.0, v135
	v_rcp_f32_e32 v135, v135
	s_nop 0
	v_mul_f32_e32 v3, v3, v135
	v_lshlrev_b32_e32 v135, 16, v156
	v_mul_f32_e32 v135, 0xbfb8aa3b, v135
	v_exp_f32_e32 v135, v135
	v_cvt_pk_bf16_f32 v1, v2, v3
	s_nop 0
	v_add_f32_e32 v135, 1.0, v135
	v_rcp_f32_e32 v135, v135
	s_nop 0
	v_mul_f32_e32 v4, v4, v135
	v_and_b32_e32 v135, 0xffff0000, v156
	v_mul_f32_e32 v135, 0xbfb8aa3b, v135
	v_exp_f32_e32 v135, v135
	s_nop 0
	v_add_f32_e32 v135, 1.0, v135
	v_rcp_f32_e32 v135, v135
	s_nop 0
	v_mul_f32_e32 v5, v5, v135
	v_lshlrev_b32_e32 v135, 16, v157
	v_mul_f32_e32 v135, 0xbfb8aa3b, v135
	v_exp_f32_e32 v135, v135
	v_cvt_pk_bf16_f32 v2, v4, v5
	s_nop 0
	v_add_f32_e32 v135, 1.0, v135
	v_rcp_f32_e32 v135, v135
	s_nop 0
	v_mul_f32_e32 v6, v6, v135
	v_and_b32_e32 v135, 0xffff0000, v157
	v_mul_f32_e32 v135, 0xbfb8aa3b, v135
	v_exp_f32_e32 v135, v135
	s_nop 0
	v_add_f32_e32 v135, 1.0, v135
	v_rcp_f32_e32 v135, v135
	s_nop 0
	v_mul_f32_e32 v7, v7, v135
	v_cvt_pk_bf16_f32 v3, v6, v7
	global_store_dwordx4 v[136:137], v[0:3], off sc1
	global_load_dwordx4 v[0:3], v[152:153], off offset:2304
	s_waitcnt vmcnt(0)
	v_lshlrev_b32_e32 v4, 16, v0
	v_and_b32_e32 v0, 0xffff0000, v0
	v_mul_f32_e32 v0, 0xbfb8aa3b, v0
	v_lshlrev_b32_e32 v5, 16, v1
	v_and_b32_e32 v1, 0xffff0000, v1
	v_lshlrev_b32_e32 v6, 16, v2
	v_and_b32_e32 v2, 0xffff0000, v2
	v_lshlrev_b32_e32 v7, 16, v3
	v_and_b32_e32 v3, 0xffff0000, v3
	v_mul_f32_e32 v4, 0xbfb8aa3b, v4
	v_exp_f32_e32 v0, v0
	v_mul_f32_e32 v1, 0xbfb8aa3b, v1
	v_mul_f32_e32 v2, 0xbfb8aa3b, v2
	v_mul_f32_e32 v3, 0xbfb8aa3b, v3
	v_exp_f32_e32 v4, v4
	v_mul_f32_e32 v5, 0xbfb8aa3b, v5
	v_exp_f32_e32 v1, v1
	v_mul_f32_e32 v6, 0xbfb8aa3b, v6
	v_exp_f32_e32 v2, v2
	v_mul_f32_e32 v7, 0xbfb8aa3b, v7
	v_exp_f32_e32 v3, v3
	v_exp_f32_e32 v5, v5
	v_exp_f32_e32 v6, v6
	v_exp_f32_e32 v7, v7
	v_add_f32_e32 v0, 1.0, v0
	v_add_f32_e32 v4, 1.0, v4
	v_rcp_f32_e32 v0, v0
	v_add_f32_e32 v1, 1.0, v1
	v_add_f32_e32 v2, 1.0, v2
	v_add_f32_e32 v3, 1.0, v3
	v_rcp_f32_e32 v4, v4
	v_add_f32_e32 v5, 1.0, v5
	v_rcp_f32_e32 v1, v1
	v_add_f32_e32 v6, 1.0, v6
	v_rcp_f32_e32 v2, v2
	v_add_f32_e32 v7, 1.0, v7
	v_rcp_f32_e32 v3, v3
	v_rcp_f32_e32 v5, v5
	v_rcp_f32_e32 v6, v6
	v_rcp_f32_e32 v7, v7
	v_mul_f32_e32 v0, v9, v0
	v_mul_f32_e32 v4, v8, v4
	v_mul_f32_e32 v1, v11, v1
	v_mul_f32_e32 v2, v13, v2
	v_mul_f32_e32 v3, v15, v3
	v_cvt_pk_bf16_f32 v0, v4, v0
	v_mul_f32_e32 v5, v10, v5
	v_mul_f32_e32 v6, v12, v6
	v_mul_f32_e32 v7, v14, v7
	v_cvt_pk_bf16_f32 v1, v5, v1
	v_cvt_pk_bf16_f32 v2, v6, v2
	v_cvt_pk_bf16_f32 v3, v7, v3
	global_store_dwordx4 v[136:137], v[0:3], off offset:256 sc1
	s_nop 1
	v_or_b32_e32 v0, 16, v134
	v_ashrrev_i32_e32 v1, 31, v0
	v_lshlrev_b64 v[2:3], 12, v[0:1]
	v_lshl_add_u64 v[2:3], s[14:15], 0, v[2:3]
	v_lshl_add_u64 v[2:3], v[2:3], 0, v[130:131]
	global_load_dwordx4 v[4:7], v[2:3], off offset:2048
	v_lshlrev_b64 v[0:1], 11, v[0:1]
	v_lshl_add_u64 v[0:1], v[132:133], 0, v[0:1]
	s_waitcnt vmcnt(0)
	v_lshlrev_b32_e32 v8, 16, v4
	v_and_b32_e32 v4, 0xffff0000, v4
	v_lshlrev_b32_e32 v9, 16, v5
	v_and_b32_e32 v5, 0xffff0000, v5
	v_lshlrev_b32_e32 v10, 16, v6
	v_and_b32_e32 v6, 0xffff0000, v6
	v_lshlrev_b32_e32 v11, 16, v7
	v_and_b32_e32 v7, 0xffff0000, v7
	v_mul_f32_e32 v4, 0xbfb8aa3b, v4
	v_mul_f32_e32 v5, 0xbfb8aa3b, v5
	v_mul_f32_e32 v6, 0xbfb8aa3b, v6
	v_mul_f32_e32 v7, 0xbfb8aa3b, v7
	v_mul_f32_e32 v8, 0xbfb8aa3b, v8
	v_exp_f32_e32 v4, v4
	v_mul_f32_e32 v9, 0xbfb8aa3b, v9
	v_exp_f32_e32 v5, v5
	v_mul_f32_e32 v10, 0xbfb8aa3b, v10
	v_exp_f32_e32 v6, v6
	v_mul_f32_e32 v11, 0xbfb8aa3b, v11
	v_exp_f32_e32 v7, v7
	v_exp_f32_e32 v8, v8
	v_exp_f32_e32 v9, v9
	v_exp_f32_e32 v10, v10
	v_exp_f32_e32 v11, v11
	v_add_f32_e32 v4, 1.0, v4
	v_add_f32_e32 v5, 1.0, v5
	v_add_f32_e32 v6, 1.0, v6
	v_add_f32_e32 v7, 1.0, v7
	v_add_f32_e32 v8, 1.0, v8
	v_rcp_f32_e32 v4, v4
	v_add_f32_e32 v9, 1.0, v9
	v_rcp_f32_e32 v5, v5
	v_add_f32_e32 v10, 1.0, v10
	v_rcp_f32_e32 v6, v6
	v_add_f32_e32 v11, 1.0, v11
	v_rcp_f32_e32 v7, v7
	v_rcp_f32_e32 v8, v8
	v_rcp_f32_e32 v9, v9
	v_rcp_f32_e32 v10, v10
	v_rcp_f32_e32 v11, v11
	v_mul_f32_e32 v4, v17, v4
	v_mul_f32_e32 v5, v19, v5
	v_mul_f32_e32 v6, v21, v6
	v_mul_f32_e32 v7, v23, v7
	v_mul_f32_e32 v8, v16, v8
	v_mul_f32_e32 v9, v18, v9
	v_mul_f32_e32 v10, v20, v10
	v_mul_f32_e32 v11, v22, v11
	v_cvt_pk_bf16_f32 v4, v8, v4
	v_cvt_pk_bf16_f32 v5, v9, v5
	v_cvt_pk_bf16_f32 v6, v10, v6
	v_cvt_pk_bf16_f32 v7, v11, v7
	global_store_dwordx4 v[0:1], v[4:7], off sc1
	global_load_dwordx4 v[2:5], v[2:3], off offset:2304
	s_waitcnt vmcnt(0)
; __device__ __forceinline__ unsigned cvt_pk_bf16(float lo, float hi) { unsigned r; asm volatile("v_cvt_pk_bf16_f32 %0, %1, %2" : "=v"(r) : "v"(lo), "v"(hi)); return r; }
; __device__ __forceinline__ float bflo(unsigned w) { return __uint_as_float(w << 16); }
; __device__ __forceinline__ float bfhi(unsigned w) { return __uint_as_float(w & 0xffff0000u); }
;     __device__ __forceinline__ void operator()(const f32x4 (&acc)[2][2][4][2], const Unit& u, int wr, int wc, int fr, int fq) const {
;         const int row0 = u.pm * BM + wr * 64 + fr, col0 = u.pn * BM + wc * 32 + 8 * fq;
;         bf16_t* gout = u.slab < 0 ? G : SL + (size_t)u.slab * (1024 * 1024) - (size_t)ML * 1024;
; #pragma unroll
;         for (int ai = 0; ai < 2; ++ai)
; #pragma unroll
;             for (int m = 0; m < 4; ++m) { const size_t r = (size_t)(row0 + ai * HALF + m * 16);
; #pragma unroll
;                 for (int bj = 0; bj < 2; ++bj) { const u32x4 lb = *(const u32x4*)(GL + r * 2048 + 1024 + col0 + bj * HALF); float o[8];
; #pragma unroll
;                     for (int n = 0; n < 2; ++n)
; #pragma unroll
;                         for (int j = 0; j < 4; ++j) { const int e = n * 4 + j; const unsigned wb = lb[e >> 1]; const float b = (e & 1) ? bfhi(wb) : bflo(wb);
;                             o[e] = acc[ai][bj][m][n][j] * __builtin_amdgcn_rcpf(1.0f + __expf(-b)); }
;                     u32x4 w; w.x = cvt_pk_bf16(o[0], o[1]); w.y = cvt_pk_bf16(o[2], o[3]); w.z = cvt_pk_bf16(o[4], o[5]); w.w = cvt_pk_bf16(o[6], o[7]);
;                     *(u32x4*)(gout + r * 1024 + col0 + bj * HALF) = w; asm volatile("" ::: "memory"); } }
;     }
	v_lshlrev_b32_e32 v8, 16, v4
	v_lshlrev_b32_e32 v6, 16, v2
	v_and_b32_e32 v2, 0xffff0000, v2
	v_lshlrev_b32_e32 v7, 16, v3
	v_and_b32_e32 v3, 0xffff0000, v3
	v_and_b32_e32 v4, 0xffff0000, v4
	v_lshlrev_b32_e32 v9, 16, v5
	v_and_b32_e32 v5, 0xffff0000, v5
	v_mul_f32_e32 v2, 0xbfb8aa3b, v2
	v_mul_f32_e32 v3, 0xbfb8aa3b, v3
	v_mul_f32_e32 v4, 0xbfb8aa3b, v4
	v_mul_f32_e32 v5, 0xbfb8aa3b, v5
	v_mul_f32_e32 v6, 0xbfb8aa3b, v6
	v_exp_f32_e32 v2, v2
	v_mul_f32_e32 v7, 0xbfb8aa3b, v7
	v_exp_f32_e32 v3, v3
	v_mul_f32_e32 v8, 0xbfb8aa3b, v8
	v_exp_f32_e32 v4, v4
	v_mul_f32_e32 v9, 0xbfb8aa3b, v9
	v_exp_f32_e32 v5, v5
	v_exp_f32_e32 v6, v6
	v_exp_f32_e32 v7, v7
	v_exp_f32_e32 v8, v8
	v_exp_f32_e32 v9, v9
	v_add_f32_e32 v2, 1.0, v2
	v_add_f32_e32 v3, 1.0, v3
	v_add_f32_e32 v4, 1.0, v4
	v_add_f32_e32 v5, 1.0, v5
	v_add_f32_e32 v6, 1.0, v6
	v_rcp_f32_e32 v2, v2
	v_add_f32_e32 v7, 1.0, v7
	v_rcp_f32_e32 v3, v3
	v_add_f32_e32 v8, 1.0, v8
	v_rcp_f32_e32 v4, v4
	v_add_f32_e32 v9, 1.0, v9
	v_rcp_f32_e32 v5, v5
	v_rcp_f32_e32 v6, v6
	v_rcp_f32_e32 v7, v7
	v_rcp_f32_e32 v8, v8
	v_rcp_f32_e32 v9, v9
	v_mul_f32_e32 v2, v25, v2
	v_mul_f32_e32 v3, v27, v3
	v_mul_f32_e32 v4, v29, v4
	v_mul_f32_e32 v5, v31, v5
	v_mul_f32_e32 v6, v24, v6
	v_mul_f32_e32 v7, v26, v7
	v_mul_f32_e32 v8, v28, v8
	v_mul_f32_e32 v9, v30, v9
	v_cvt_pk_bf16_f32 v2, v6, v2
	v_cvt_pk_bf16_f32 v3, v7, v3
	v_cvt_pk_bf16_f32 v4, v8, v4
	v_cvt_pk_bf16_f32 v5, v9, v5
	global_store_dwordx4 v[0:1], v[2:5], off offset:256 sc1
	v_or_b32_e32 v0, 32, v134
	v_ashrrev_i32_e32 v1, 31, v0
	v_lshlrev_b64 v[2:3], 12, v[0:1]
	v_lshl_add_u64 v[2:3], s[14:15], 0, v[2:3]
	v_lshl_add_u64 v[2:3], v[2:3], 0, v[130:131]
	global_load_dwordx4 v[4:7], v[2:3], off offset:2048
	v_lshlrev_b64 v[0:1], 11, v[0:1]
	v_lshl_add_u64 v[0:1], v[132:133], 0, v[0:1]
	s_waitcnt vmcnt(0)
	v_lshlrev_b32_e32 v8, 16, v4
	v_and_b32_e32 v4, 0xffff0000, v4
	v_lshlrev_b32_e32 v9, 16, v5
	v_and_b32_e32 v5, 0xffff0000, v5
	v_lshlrev_b32_e32 v10, 16, v6
	v_and_b32_e32 v6, 0xffff0000, v6
	v_lshlrev_b32_e32 v11, 16, v7
	v_and_b32_e32 v7, 0xffff0000, v7
	v_mul_f32_e32 v4, 0xbfb8aa3b, v4
	v_mul_f32_e32 v5, 0xbfb8aa3b, v5
	v_mul_f32_e32 v6, 0xbfb8aa3b, v6
	v_mul_f32_e32 v7, 0xbfb8aa3b, v7
	v_mul_f32_e32 v8, 0xbfb8aa3b, v8
	v_exp_f32_e32 v4, v4
	v_mul_f32_e32 v9, 0xbfb8aa3b, v9
	v_exp_f32_e32 v5, v5
	v_mul_f32_e32 v10, 0xbfb8aa3b, v10
	v_exp_f32_e32 v6, v6
	v_mul_f32_e32 v11, 0xbfb8aa3b, v11
	v_exp_f32_e32 v7, v7
	v_exp_f32_e32 v8, v8
	v_exp_f32_e32 v9, v9
	v_exp_f32_e32 v10, v10
	v_exp_f32_e32 v11, v11
	v_add_f32_e32 v4, 1.0, v4
	v_add_f32_e32 v5, 1.0, v5
	v_add_f32_e32 v6, 1.0, v6
	v_add_f32_e32 v7, 1.0, v7
	v_add_f32_e32 v8, 1.0, v8
	v_rcp_f32_e32 v4, v4
	v_add_f32_e32 v9, 1.0, v9
	v_rcp_f32_e32 v5, v5
	v_add_f32_e32 v10, 1.0, v10
	v_rcp_f32_e32 v6, v6
	v_add_f32_e32 v11, 1.0, v11
	v_rcp_f32_e32 v7, v7
	v_rcp_f32_e32 v8, v8
	v_rcp_f32_e32 v9, v9
	v_rcp_f32_e32 v10, v10
	v_rcp_f32_e32 v11, v11
	v_mul_f32_e32 v4, v47, v4
	v_mul_f32_e32 v5, v49, v5
	v_mul_f32_e32 v6, v51, v6
	v_mul_f32_e32 v7, v53, v7
	v_mul_f32_e32 v8, v46, v8
	v_mul_f32_e32 v9, v48, v9
	v_mul_f32_e32 v10, v50, v10
	v_mul_f32_e32 v11, v52, v11
	v_cvt_pk_bf16_f32 v4, v8, v4
	v_cvt_pk_bf16_f32 v5, v9, v5
	v_cvt_pk_bf16_f32 v6, v10, v6
	v_cvt_pk_bf16_f32 v7, v11, v7
	global_store_dwordx4 v[0:1], v[4:7], off sc1
	global_load_dwordx4 v[2:5], v[2:3], off offset:2304
	s_waitcnt vmcnt(0)
	v_lshlrev_b32_e32 v8, 16, v4
	v_lshlrev_b32_e32 v6, 16, v2
	v_and_b32_e32 v2, 0xffff0000, v2
	v_lshlrev_b32_e32 v7, 16, v3
	v_and_b32_e32 v3, 0xffff0000, v3
	v_and_b32_e32 v4, 0xffff0000, v4
	v_lshlrev_b32_e32 v9, 16, v5
	v_and_b32_e32 v5, 0xffff0000, v5
	v_mul_f32_e32 v2, 0xbfb8aa3b, v2
	v_mul_f32_e32 v3, 0xbfb8aa3b, v3
	v_mul_f32_e32 v4, 0xbfb8aa3b, v4
	v_mul_f32_e32 v5, 0xbfb8aa3b, v5
	v_mul_f32_e32 v6, 0xbfb8aa3b, v6
	v_exp_f32_e32 v2, v2
	v_mul_f32_e32 v7, 0xbfb8aa3b, v7
	v_exp_f32_e32 v3, v3
	v_mul_f32_e32 v8, 0xbfb8aa3b, v8
	v_exp_f32_e32 v4, v4
	v_mul_f32_e32 v9, 0xbfb8aa3b, v9
	v_exp_f32_e32 v5, v5
	v_exp_f32_e32 v6, v6
	v_exp_f32_e32 v7, v7
	v_exp_f32_e32 v8, v8
	v_exp_f32_e32 v9, v9
	v_add_f32_e32 v2, 1.0, v2
	v_add_f32_e32 v3, 1.0, v3
	v_add_f32_e32 v4, 1.0, v4
	v_add_f32_e32 v5, 1.0, v5
	v_add_f32_e32 v6, 1.0, v6
	v_rcp_f32_e32 v2, v2
	v_add_f32_e32 v7, 1.0, v7
	v_rcp_f32_e32 v3, v3
	v_add_f32_e32 v8, 1.0, v8
	v_rcp_f32_e32 v4, v4
	v_add_f32_e32 v9, 1.0, v9
	v_rcp_f32_e32 v5, v5
	v_rcp_f32_e32 v6, v6
	v_rcp_f32_e32 v7, v7
	v_rcp_f32_e32 v8, v8
	v_rcp_f32_e32 v9, v9
	v_mul_f32_e32 v2, v55, v2
	v_mul_f32_e32 v3, v57, v3
	v_mul_f32_e32 v4, v59, v4
	v_mul_f32_e32 v5, v61, v5
	v_mul_f32_e32 v6, v54, v6
	v_mul_f32_e32 v7, v56, v7
	v_mul_f32_e32 v8, v58, v8
	v_mul_f32_e32 v9, v60, v9
	v_cvt_pk_bf16_f32 v2, v6, v2
	v_cvt_pk_bf16_f32 v3, v7, v3
	v_cvt_pk_bf16_f32 v4, v8, v4
	v_cvt_pk_bf16_f32 v5, v9, v5
	global_store_dwordx4 v[0:1], v[2:5], off offset:256 sc1
	v_or_b32_e32 v0, 48, v134
	v_ashrrev_i32_e32 v1, 31, v0
	v_lshlrev_b64 v[2:3], 12, v[0:1]
	v_lshl_add_u64 v[2:3], s[14:15], 0, v[2:3]
	v_lshl_add_u64 v[2:3], v[2:3], 0, v[130:131]
	global_load_dwordx4 v[4:7], v[2:3], off offset:2048
	v_lshlrev_b64 v[0:1], 11, v[0:1]
	v_lshl_add_u64 v[0:1], v[132:133], 0, v[0:1]
	s_waitcnt vmcnt(0)
; __device__ __forceinline__ unsigned cvt_pk_bf16(float lo, float hi) { unsigned r; asm volatile("v_cvt_pk_bf16_f32 %0, %1, %2" : "=v"(r) : "v"(lo), "v"(hi)); return r; }
; __device__ __forceinline__ float bflo(unsigned w) { return __uint_as_float(w << 16); }
; __device__ __forceinline__ float bfhi(unsigned w) { return __uint_as_float(w & 0xffff0000u); }
;     __device__ __forceinline__ void operator()(const f32x4 (&acc)[2][2][4][2], const Unit& u, int wr, int wc, int fr, int fq) const {
;         const int row0 = u.pm * BM + wr * 64 + fr, col0 = u.pn * BM + wc * 32 + 8 * fq;
;         bf16_t* gout = u.slab < 0 ? G : SL + (size_t)u.slab * (1024 * 1024) - (size_t)ML * 1024;
; #pragma unroll
;         for (int ai = 0; ai < 2; ++ai)
; #pragma unroll
;             for (int m = 0; m < 4; ++m) { const size_t r = (size_t)(row0 + ai * HALF + m * 16);
; #pragma unroll
;                 for (int bj = 0; bj < 2; ++bj) { const u32x4 lb = *(const u32x4*)(GL + r * 2048 + 1024 + col0 + bj * HALF); float o[8];
; #pragma unroll
;                     for (int n = 0; n < 2; ++n)
; #pragma unroll
;                         for (int j = 0; j < 4; ++j) { const int e = n * 4 + j; const unsigned wb = lb[e >> 1]; const float b = (e & 1) ? bfhi(wb) : bflo(wb);
;                             o[e] = acc[ai][bj][m][n][j] * __builtin_amdgcn_rcpf(1.0f + __expf(-b)); }
;                     u32x4 w; w.x = cvt_pk_bf16(o[0], o[1]); w.y = cvt_pk_bf16(o[2], o[3]); w.z = cvt_pk_bf16(o[4], o[5]); w.w = cvt_pk_bf16(o[6], o[7]);
;                     *(u32x4*)(gout + r * 1024 + col0 + bj * HALF) = w; asm volatile("" ::: "memory"); } }
;     }
	v_lshlrev_b32_e32 v8, 16, v4
	v_and_b32_e32 v4, 0xffff0000, v4
	v_lshlrev_b32_e32 v9, 16, v5
	v_and_b32_e32 v5, 0xffff0000, v5
	v_lshlrev_b32_e32 v10, 16, v6
	v_and_b32_e32 v6, 0xffff0000, v6
	v_lshlrev_b32_e32 v11, 16, v7
	v_and_b32_e32 v7, 0xffff0000, v7
	v_mul_f32_e32 v4, 0xbfb8aa3b, v4
	v_mul_f32_e32 v5, 0xbfb8aa3b, v5
	v_mul_f32_e32 v6, 0xbfb8aa3b, v6
	v_mul_f32_e32 v7, 0xbfb8aa3b, v7
	v_mul_f32_e32 v8, 0xbfb8aa3b, v8
	v_exp_f32_e32 v4, v4
	v_mul_f32_e32 v9, 0xbfb8aa3b, v9
	v_exp_f32_e32 v5, v5
	v_mul_f32_e32 v10, 0xbfb8aa3b, v10
	v_exp_f32_e32 v6, v6
	v_mul_f32_e32 v11, 0xbfb8aa3b, v11
	v_exp_f32_e32 v7, v7
	v_exp_f32_e32 v8, v8
	v_exp_f32_e32 v9, v9
	v_exp_f32_e32 v10, v10
	v_exp_f32_e32 v11, v11
	v_add_f32_e32 v4, 1.0, v4
	v_add_f32_e32 v5, 1.0, v5
	v_add_f32_e32 v6, 1.0, v6
	v_add_f32_e32 v7, 1.0, v7
	v_add_f32_e32 v8, 1.0, v8
	v_rcp_f32_e32 v4, v4
	v_add_f32_e32 v9, 1.0, v9
	v_rcp_f32_e32 v5, v5
	v_add_f32_e32 v10, 1.0, v10
	v_rcp_f32_e32 v6, v6
	v_add_f32_e32 v11, 1.0, v11
	v_rcp_f32_e32 v7, v7
	v_rcp_f32_e32 v8, v8
	v_rcp_f32_e32 v9, v9
	v_rcp_f32_e32 v10, v10
	v_rcp_f32_e32 v11, v11
	v_mul_f32_e32 v4, v67, v4
	v_mul_f32_e32 v5, v69, v5
	v_mul_f32_e32 v6, v71, v6
	v_mul_f32_e32 v7, v73, v7
	v_mul_f32_e32 v8, v66, v8
	v_mul_f32_e32 v9, v68, v9
	v_mul_f32_e32 v10, v70, v10
	v_mul_f32_e32 v11, v72, v11
	v_cvt_pk_bf16_f32 v4, v8, v4
	v_cvt_pk_bf16_f32 v5, v9, v5
	v_cvt_pk_bf16_f32 v6, v10, v6
	v_cvt_pk_bf16_f32 v7, v11, v7
	global_store_dwordx4 v[0:1], v[4:7], off sc1
	global_load_dwordx4 v[2:5], v[2:3], off offset:2304
	s_waitcnt vmcnt(0)
	v_lshlrev_b32_e32 v8, 16, v4
	v_lshlrev_b32_e32 v6, 16, v2
	v_and_b32_e32 v2, 0xffff0000, v2
	v_lshlrev_b32_e32 v7, 16, v3
	v_and_b32_e32 v3, 0xffff0000, v3
	v_and_b32_e32 v4, 0xffff0000, v4
	v_lshlrev_b32_e32 v9, 16, v5
	v_and_b32_e32 v5, 0xffff0000, v5
	v_mul_f32_e32 v2, 0xbfb8aa3b, v2
	v_mul_f32_e32 v3, 0xbfb8aa3b, v3
	v_mul_f32_e32 v4, 0xbfb8aa3b, v4
	v_mul_f32_e32 v5, 0xbfb8aa3b, v5
	v_mul_f32_e32 v6, 0xbfb8aa3b, v6
	v_exp_f32_e32 v2, v2
	v_mul_f32_e32 v7, 0xbfb8aa3b, v7
	v_exp_f32_e32 v3, v3
	v_mul_f32_e32 v8, 0xbfb8aa3b, v8
	v_exp_f32_e32 v4, v4
	v_mul_f32_e32 v9, 0xbfb8aa3b, v9
	v_exp_f32_e32 v5, v5
	v_exp_f32_e32 v6, v6
	v_exp_f32_e32 v7, v7
	v_exp_f32_e32 v8, v8
	v_exp_f32_e32 v9, v9
	v_add_f32_e32 v2, 1.0, v2
	v_add_f32_e32 v3, 1.0, v3
	v_add_f32_e32 v4, 1.0, v4
	v_add_f32_e32 v5, 1.0, v5
	v_add_f32_e32 v6, 1.0, v6
	v_rcp_f32_e32 v2, v2
	v_add_f32_e32 v7, 1.0, v7
	v_rcp_f32_e32 v3, v3
	v_add_f32_e32 v8, 1.0, v8
	v_rcp_f32_e32 v4, v4
	v_add_f32_e32 v9, 1.0, v9
	v_rcp_f32_e32 v5, v5
	v_rcp_f32_e32 v6, v6
	v_rcp_f32_e32 v7, v7
	v_rcp_f32_e32 v8, v8
	v_rcp_f32_e32 v9, v9
	v_mul_f32_e32 v2, v75, v2
	v_mul_f32_e32 v3, v77, v3
	v_mul_f32_e32 v4, v79, v4
	v_mul_f32_e32 v5, v81, v5
	v_mul_f32_e32 v6, v74, v6
	v_mul_f32_e32 v7, v76, v7
	v_mul_f32_e32 v8, v78, v8
	v_mul_f32_e32 v9, v80, v9
	v_cvt_pk_bf16_f32 v2, v6, v2
	v_cvt_pk_bf16_f32 v3, v7, v3
	v_cvt_pk_bf16_f32 v4, v8, v4
	v_cvt_pk_bf16_f32 v5, v9, v5
	global_store_dwordx4 v[0:1], v[2:5], off offset:256 sc1
	v_add_u32_e32 v0, 0x80, v134
	v_ashrrev_i32_e32 v1, 31, v0
	v_lshlrev_b64 v[2:3], 12, v[0:1]
	v_lshl_add_u64 v[2:3], s[14:15], 0, v[2:3]
	v_lshl_add_u64 v[2:3], v[2:3], 0, v[130:131]
	global_load_dwordx4 v[4:7], v[2:3], off offset:2048
	v_lshlrev_b64 v[0:1], 11, v[0:1]
	v_lshl_add_u64 v[0:1], v[132:133], 0, v[0:1]
	s_waitcnt vmcnt(0)
	v_lshlrev_b32_e32 v8, 16, v4
	v_and_b32_e32 v4, 0xffff0000, v4
	v_lshlrev_b32_e32 v9, 16, v5
	v_and_b32_e32 v5, 0xffff0000, v5
	v_lshlrev_b32_e32 v10, 16, v6
	v_and_b32_e32 v6, 0xffff0000, v6
	v_lshlrev_b32_e32 v11, 16, v7
	v_and_b32_e32 v7, 0xffff0000, v7
	v_mul_f32_e32 v4, 0xbfb8aa3b, v4
	v_mul_f32_e32 v5, 0xbfb8aa3b, v5
	v_mul_f32_e32 v6, 0xbfb8aa3b, v6
	v_mul_f32_e32 v7, 0xbfb8aa3b, v7
	v_mul_f32_e32 v8, 0xbfb8aa3b, v8
	v_exp_f32_e32 v4, v4
	v_mul_f32_e32 v9, 0xbfb8aa3b, v9
	v_exp_f32_e32 v5, v5
	v_mul_f32_e32 v10, 0xbfb8aa3b, v10
	v_exp_f32_e32 v6, v6
	v_mul_f32_e32 v11, 0xbfb8aa3b, v11
	v_exp_f32_e32 v7, v7
	v_exp_f32_e32 v8, v8
	v_exp_f32_e32 v9, v9
	v_exp_f32_e32 v10, v10
	v_exp_f32_e32 v11, v11
	v_add_f32_e32 v4, 1.0, v4
	v_add_f32_e32 v5, 1.0, v5
	v_add_f32_e32 v6, 1.0, v6
	v_add_f32_e32 v7, 1.0, v7
	v_add_f32_e32 v8, 1.0, v8
	v_rcp_f32_e32 v4, v4
	v_add_f32_e32 v9, 1.0, v9
	v_rcp_f32_e32 v5, v5
	v_add_f32_e32 v10, 1.0, v10
	v_rcp_f32_e32 v6, v6
	v_add_f32_e32 v11, 1.0, v11
	v_rcp_f32_e32 v7, v7
	v_rcp_f32_e32 v8, v8
	v_rcp_f32_e32 v9, v9
	v_rcp_f32_e32 v10, v10
	v_rcp_f32_e32 v11, v11
	v_mul_f32_e32 v4, v83, v4
	v_mul_f32_e32 v5, v85, v5
	v_mul_f32_e32 v6, v87, v6
	v_mul_f32_e32 v7, v89, v7
	v_mul_f32_e32 v8, v82, v8
	v_mul_f32_e32 v9, v84, v9
	v_mul_f32_e32 v10, v86, v10
	v_mul_f32_e32 v11, v88, v11
	v_cvt_pk_bf16_f32 v4, v8, v4
	v_cvt_pk_bf16_f32 v5, v9, v5
	v_cvt_pk_bf16_f32 v6, v10, v6
	v_cvt_pk_bf16_f32 v7, v11, v7
	global_store_dwordx4 v[0:1], v[4:7], off sc1
	global_load_dwordx4 v[2:5], v[2:3], off offset:2304
	s_waitcnt vmcnt(0)
; __device__ __forceinline__ unsigned cvt_pk_bf16(float lo, float hi) { unsigned r; asm volatile("v_cvt_pk_bf16_f32 %0, %1, %2" : "=v"(r) : "v"(lo), "v"(hi)); return r; }
; __device__ __forceinline__ float bflo(unsigned w) { return __uint_as_float(w << 16); }
; __device__ __forceinline__ float bfhi(unsigned w) { return __uint_as_float(w & 0xffff0000u); }
;     __device__ __forceinline__ void operator()(const f32x4 (&acc)[2][2][4][2], const Unit& u, int wr, int wc, int fr, int fq) const {
;         const int row0 = u.pm * BM + wr * 64 + fr, col0 = u.pn * BM + wc * 32 + 8 * fq;
;         bf16_t* gout = u.slab < 0 ? G : SL + (size_t)u.slab * (1024 * 1024) - (size_t)ML * 1024;
; #pragma unroll
;         for (int ai = 0; ai < 2; ++ai)
; #pragma unroll
;             for (int m = 0; m < 4; ++m) { const size_t r = (size_t)(row0 + ai * HALF + m * 16);
; #pragma unroll
;                 for (int bj = 0; bj < 2; ++bj) { const u32x4 lb = *(const u32x4*)(GL + r * 2048 + 1024 + col0 + bj * HALF); float o[8];
; #pragma unroll
;                     for (int n = 0; n < 2; ++n)
; #pragma unroll
;                         for (int j = 0; j < 4; ++j) { const int e = n * 4 + j; const unsigned wb = lb[e >> 1]; const float b = (e & 1) ? bfhi(wb) : bflo(wb);
;                             o[e] = acc[ai][bj][m][n][j] * __builtin_amdgcn_rcpf(1.0f + __expf(-b)); }
;                     u32x4 w; w.x = cvt_pk_bf16(o[0], o[1]); w.y = cvt_pk_bf16(o[2], o[3]); w.z = cvt_pk_bf16(o[4], o[5]); w.w = cvt_pk_bf16(o[6], o[7]);
;                     *(u32x4*)(gout + r * 1024 + col0 + bj * HALF) = w; asm volatile("" ::: "memory"); } }
;     }
	v_lshlrev_b32_e32 v8, 16, v4
	v_lshlrev_b32_e32 v6, 16, v2
	v_and_b32_e32 v2, 0xffff0000, v2
	v_lshlrev_b32_e32 v7, 16, v3
	v_and_b32_e32 v3, 0xffff0000, v3
	v_and_b32_e32 v4, 0xffff0000, v4
	v_lshlrev_b32_e32 v9, 16, v5
	v_and_b32_e32 v5, 0xffff0000, v5
	v_mul_f32_e32 v2, 0xbfb8aa3b, v2
	v_mul_f32_e32 v3, 0xbfb8aa3b, v3
	v_mul_f32_e32 v4, 0xbfb8aa3b, v4
	v_mul_f32_e32 v5, 0xbfb8aa3b, v5
	v_mul_f32_e32 v6, 0xbfb8aa3b, v6
	v_exp_f32_e32 v2, v2
	v_mul_f32_e32 v7, 0xbfb8aa3b, v7
	v_exp_f32_e32 v3, v3
	v_mul_f32_e32 v8, 0xbfb8aa3b, v8
	v_exp_f32_e32 v4, v4
	v_mul_f32_e32 v9, 0xbfb8aa3b, v9
	v_exp_f32_e32 v5, v5
	v_exp_f32_e32 v6, v6
	v_exp_f32_e32 v7, v7
	v_exp_f32_e32 v8, v8
	v_exp_f32_e32 v9, v9
	v_add_f32_e32 v2, 1.0, v2
	v_add_f32_e32 v3, 1.0, v3
	v_add_f32_e32 v4, 1.0, v4
	v_add_f32_e32 v5, 1.0, v5
	v_add_f32_e32 v6, 1.0, v6
	v_rcp_f32_e32 v2, v2
	v_add_f32_e32 v7, 1.0, v7
	v_rcp_f32_e32 v3, v3
	v_add_f32_e32 v8, 1.0, v8
	v_rcp_f32_e32 v4, v4
	v_add_f32_e32 v9, 1.0, v9
	v_rcp_f32_e32 v5, v5
	v_rcp_f32_e32 v6, v6
	v_rcp_f32_e32 v7, v7
	v_rcp_f32_e32 v8, v8
	v_rcp_f32_e32 v9, v9
	v_mul_f32_e32 v2, v91, v2
	v_mul_f32_e32 v3, v93, v3
	v_mul_f32_e32 v4, v95, v4
	v_mul_f32_e32 v5, v97, v5
	v_mul_f32_e32 v6, v90, v6
	v_mul_f32_e32 v7, v92, v7
	v_mul_f32_e32 v8, v94, v8
	v_mul_f32_e32 v9, v96, v9
	v_cvt_pk_bf16_f32 v2, v6, v2
	v_cvt_pk_bf16_f32 v3, v7, v3
	v_cvt_pk_bf16_f32 v4, v8, v4
	v_cvt_pk_bf16_f32 v5, v9, v5
	global_store_dwordx4 v[0:1], v[2:5], off offset:256 sc1
	v_add_u32_e32 v0, 0x90, v134
	v_ashrrev_i32_e32 v1, 31, v0
	v_lshlrev_b64 v[2:3], 12, v[0:1]
	v_lshl_add_u64 v[2:3], s[14:15], 0, v[2:3]
	v_lshl_add_u64 v[2:3], v[2:3], 0, v[130:131]
	global_load_dwordx4 v[4:7], v[2:3], off offset:2048
	v_lshlrev_b64 v[0:1], 11, v[0:1]
	v_lshl_add_u64 v[0:1], v[132:133], 0, v[0:1]
	s_waitcnt vmcnt(0)
	v_lshlrev_b32_e32 v8, 16, v4
	v_and_b32_e32 v4, 0xffff0000, v4
	v_lshlrev_b32_e32 v9, 16, v5
	v_and_b32_e32 v5, 0xffff0000, v5
	v_lshlrev_b32_e32 v10, 16, v6
	v_and_b32_e32 v6, 0xffff0000, v6
	v_lshlrev_b32_e32 v11, 16, v7
	v_and_b32_e32 v7, 0xffff0000, v7
	v_mul_f32_e32 v4, 0xbfb8aa3b, v4
	v_mul_f32_e32 v5, 0xbfb8aa3b, v5
	v_mul_f32_e32 v6, 0xbfb8aa3b, v6
	v_mul_f32_e32 v7, 0xbfb8aa3b, v7
	v_mul_f32_e32 v8, 0xbfb8aa3b, v8
	v_exp_f32_e32 v4, v4
	v_mul_f32_e32 v9, 0xbfb8aa3b, v9
	v_exp_f32_e32 v5, v5
	v_mul_f32_e32 v10, 0xbfb8aa3b, v10
	v_exp_f32_e32 v6, v6
	v_mul_f32_e32 v11, 0xbfb8aa3b, v11
	v_exp_f32_e32 v7, v7
	v_exp_f32_e32 v8, v8
	v_exp_f32_e32 v9, v9
	v_exp_f32_e32 v10, v10
	v_exp_f32_e32 v11, v11
	v_add_f32_e32 v4, 1.0, v4
	v_add_f32_e32 v5, 1.0, v5
	v_add_f32_e32 v6, 1.0, v6
	v_add_f32_e32 v7, 1.0, v7
	v_add_f32_e32 v8, 1.0, v8
	v_rcp_f32_e32 v4, v4
	v_add_f32_e32 v9, 1.0, v9
	v_rcp_f32_e32 v5, v5
	v_add_f32_e32 v10, 1.0, v10
	v_rcp_f32_e32 v6, v6
	v_add_f32_e32 v11, 1.0, v11
	v_rcp_f32_e32 v7, v7
	v_rcp_f32_e32 v8, v8
	v_rcp_f32_e32 v9, v9
	v_rcp_f32_e32 v10, v10
	v_rcp_f32_e32 v11, v11
	v_mul_f32_e32 v4, v107, v4
	v_mul_f32_e32 v5, v109, v5
	v_mul_f32_e32 v6, v115, v6
	v_mul_f32_e32 v7, v117, v7
	v_mul_f32_e32 v8, v106, v8
	v_mul_f32_e32 v9, v108, v9
	v_mul_f32_e32 v10, v114, v10
	v_mul_f32_e32 v11, v116, v11
	v_cvt_pk_bf16_f32 v4, v8, v4
	v_cvt_pk_bf16_f32 v5, v9, v5
	v_cvt_pk_bf16_f32 v6, v10, v6
	v_cvt_pk_bf16_f32 v7, v11, v7
	global_store_dwordx4 v[0:1], v[4:7], off sc1
	global_load_dwordx4 v[2:5], v[2:3], off offset:2304
	s_waitcnt vmcnt(0)
	v_lshlrev_b32_e32 v8, 16, v4
	v_lshlrev_b32_e32 v6, 16, v2
	v_and_b32_e32 v2, 0xffff0000, v2
	v_lshlrev_b32_e32 v7, 16, v3
	v_and_b32_e32 v3, 0xffff0000, v3
	v_and_b32_e32 v4, 0xffff0000, v4
	v_lshlrev_b32_e32 v9, 16, v5
	v_and_b32_e32 v5, 0xffff0000, v5
	v_mul_f32_e32 v2, 0xbfb8aa3b, v2
	v_mul_f32_e32 v3, 0xbfb8aa3b, v3
	v_mul_f32_e32 v4, 0xbfb8aa3b, v4
	v_mul_f32_e32 v5, 0xbfb8aa3b, v5
	v_mul_f32_e32 v6, 0xbfb8aa3b, v6
	v_exp_f32_e32 v2, v2
	v_mul_f32_e32 v7, 0xbfb8aa3b, v7
	v_exp_f32_e32 v3, v3
	v_mul_f32_e32 v8, 0xbfb8aa3b, v8
	v_exp_f32_e32 v4, v4
	v_mul_f32_e32 v9, 0xbfb8aa3b, v9
	v_exp_f32_e32 v5, v5
	v_exp_f32_e32 v6, v6
	v_exp_f32_e32 v7, v7
	v_exp_f32_e32 v8, v8
	v_exp_f32_e32 v9, v9
	v_add_f32_e32 v2, 1.0, v2
	v_add_f32_e32 v3, 1.0, v3
	v_add_f32_e32 v4, 1.0, v4
	v_add_f32_e32 v5, 1.0, v5
	v_add_f32_e32 v6, 1.0, v6
	v_rcp_f32_e32 v2, v2
	v_add_f32_e32 v7, 1.0, v7
	v_rcp_f32_e32 v3, v3
	v_add_f32_e32 v8, 1.0, v8
	v_rcp_f32_e32 v4, v4
	v_add_f32_e32 v9, 1.0, v9
	v_rcp_f32_e32 v5, v5
	v_rcp_f32_e32 v6, v6
	v_rcp_f32_e32 v7, v7
	v_rcp_f32_e32 v8, v8
	v_rcp_f32_e32 v9, v9
	v_mul_f32_e32 v2, v119, v2
	v_mul_f32_e32 v3, v121, v3
	v_mul_f32_e32 v4, v123, v4
	v_mul_f32_e32 v5, v125, v5
	v_mul_f32_e32 v6, v118, v6
	v_mul_f32_e32 v7, v120, v7
	v_mul_f32_e32 v8, v122, v8
	v_mul_f32_e32 v9, v124, v9
	v_cvt_pk_bf16_f32 v2, v6, v2
	v_cvt_pk_bf16_f32 v3, v7, v3
	v_cvt_pk_bf16_f32 v4, v8, v4
	v_cvt_pk_bf16_f32 v5, v9, v5
	global_store_dwordx4 v[0:1], v[2:5], off offset:256 sc1
	v_add_u32_e32 v0, 0xa0, v134
	v_ashrrev_i32_e32 v1, 31, v0
	v_lshlrev_b64 v[2:3], 12, v[0:1]
	v_lshl_add_u64 v[2:3], s[14:15], 0, v[2:3]
	v_lshl_add_u64 v[2:3], v[2:3], 0, v[130:131]
	global_load_dwordx4 v[4:7], v[2:3], off offset:2048
	v_lshlrev_b64 v[0:1], 11, v[0:1]
	v_lshl_add_u64 v[0:1], v[132:133], 0, v[0:1]
	s_waitcnt vmcnt(0)
; __device__ __forceinline__ unsigned cvt_pk_bf16(float lo, float hi) { unsigned r; asm volatile("v_cvt_pk_bf16_f32 %0, %1, %2" : "=v"(r) : "v"(lo), "v"(hi)); return r; }
; __device__ __forceinline__ float bflo(unsigned w) { return __uint_as_float(w << 16); }
; __device__ __forceinline__ float bfhi(unsigned w) { return __uint_as_float(w & 0xffff0000u); }
;     __device__ __forceinline__ void operator()(const f32x4 (&acc)[2][2][4][2], const Unit& u, int wr, int wc, int fr, int fq) const {
;         const int row0 = u.pm * BM + wr * 64 + fr, col0 = u.pn * BM + wc * 32 + 8 * fq;
;         bf16_t* gout = u.slab < 0 ? G : SL + (size_t)u.slab * (1024 * 1024) - (size_t)ML * 1024;
; #pragma unroll
;         for (int ai = 0; ai < 2; ++ai)
; #pragma unroll
;             for (int m = 0; m < 4; ++m) { const size_t r = (size_t)(row0 + ai * HALF + m * 16);
; #pragma unroll
;                 for (int bj = 0; bj < 2; ++bj) { const u32x4 lb = *(const u32x4*)(GL + r * 2048 + 1024 + col0 + bj * HALF); float o[8];
; #pragma unroll
;                     for (int n = 0; n < 2; ++n)
; #pragma unroll
;                         for (int j = 0; j < 4; ++j) { const int e = n * 4 + j; const unsigned wb = lb[e >> 1]; const float b = (e & 1) ? bfhi(wb) : bflo(wb);
;                             o[e] = acc[ai][bj][m][n][j] * __builtin_amdgcn_rcpf(1.0f + __expf(-b)); }
;                     u32x4 w; w.x = cvt_pk_bf16(o[0], o[1]); w.y = cvt_pk_bf16(o[2], o[3]); w.z = cvt_pk_bf16(o[4], o[5]); w.w = cvt_pk_bf16(o[6], o[7]);
;                     *(u32x4*)(gout + r * 1024 + col0 + bj * HALF) = w; asm volatile("" ::: "memory"); } }
;     }
	v_lshlrev_b32_e32 v8, 16, v4
	v_and_b32_e32 v4, 0xffff0000, v4
	v_lshlrev_b32_e32 v9, 16, v5
	v_and_b32_e32 v5, 0xffff0000, v5
	v_lshlrev_b32_e32 v10, 16, v6
	v_and_b32_e32 v6, 0xffff0000, v6
	v_lshlrev_b32_e32 v11, 16, v7
	v_and_b32_e32 v7, 0xffff0000, v7
	v_mul_f32_e32 v4, 0xbfb8aa3b, v4
	v_mul_f32_e32 v5, 0xbfb8aa3b, v5
	v_mul_f32_e32 v6, 0xbfb8aa3b, v6
	v_mul_f32_e32 v7, 0xbfb8aa3b, v7
	v_mul_f32_e32 v8, 0xbfb8aa3b, v8
	v_exp_f32_e32 v4, v4
	v_mul_f32_e32 v9, 0xbfb8aa3b, v9
	v_exp_f32_e32 v5, v5
	v_mul_f32_e32 v10, 0xbfb8aa3b, v10
	v_exp_f32_e32 v6, v6
	v_mul_f32_e32 v11, 0xbfb8aa3b, v11
	v_exp_f32_e32 v7, v7
	v_exp_f32_e32 v8, v8
	v_exp_f32_e32 v9, v9
	v_exp_f32_e32 v10, v10
	v_exp_f32_e32 v11, v11
	v_add_f32_e32 v4, 1.0, v4
	v_add_f32_e32 v5, 1.0, v5
	v_add_f32_e32 v6, 1.0, v6
	v_add_f32_e32 v7, 1.0, v7
	v_add_f32_e32 v8, 1.0, v8
	v_rcp_f32_e32 v4, v4
	v_add_f32_e32 v9, 1.0, v9
	v_rcp_f32_e32 v5, v5
	v_add_f32_e32 v10, 1.0, v10
	v_rcp_f32_e32 v6, v6
	v_add_f32_e32 v11, 1.0, v11
	v_rcp_f32_e32 v7, v7
	v_rcp_f32_e32 v8, v8
	v_rcp_f32_e32 v9, v9
	v_rcp_f32_e32 v10, v10
	v_rcp_f32_e32 v11, v11
	v_mul_f32_e32 v4, v127, v4
	v_mul_f32_e32 v5, v129, v5
	v_mul_f32_e32 v6, v111, v6
	v_mul_f32_e32 v7, v113, v7
	v_mul_f32_e32 v8, v126, v8
	v_mul_f32_e32 v9, v128, v9
	v_mul_f32_e32 v10, v110, v10
	v_mul_f32_e32 v11, v112, v11
	v_cvt_pk_bf16_f32 v4, v8, v4
	v_cvt_pk_bf16_f32 v5, v9, v5
	v_cvt_pk_bf16_f32 v6, v10, v6
	v_cvt_pk_bf16_f32 v7, v11, v7
	global_store_dwordx4 v[0:1], v[4:7], off sc1
	global_load_dwordx4 v[2:5], v[2:3], off offset:2304
	s_waitcnt vmcnt(0)
	v_lshlrev_b32_e32 v8, 16, v4
	v_lshlrev_b32_e32 v6, 16, v2
	v_and_b32_e32 v2, 0xffff0000, v2
	v_lshlrev_b32_e32 v7, 16, v3
	v_and_b32_e32 v3, 0xffff0000, v3
	v_and_b32_e32 v4, 0xffff0000, v4
	v_lshlrev_b32_e32 v9, 16, v5
	v_and_b32_e32 v5, 0xffff0000, v5
	v_mul_f32_e32 v2, 0xbfb8aa3b, v2
	v_mul_f32_e32 v3, 0xbfb8aa3b, v3
	v_mul_f32_e32 v4, 0xbfb8aa3b, v4
	v_mul_f32_e32 v5, 0xbfb8aa3b, v5
	v_mul_f32_e32 v6, 0xbfb8aa3b, v6
	v_exp_f32_e32 v2, v2
	v_mul_f32_e32 v7, 0xbfb8aa3b, v7
	v_exp_f32_e32 v3, v3
	v_mul_f32_e32 v8, 0xbfb8aa3b, v8
	v_exp_f32_e32 v4, v4
	v_mul_f32_e32 v9, 0xbfb8aa3b, v9
	v_exp_f32_e32 v5, v5
	v_exp_f32_e32 v6, v6
	v_exp_f32_e32 v7, v7
	v_exp_f32_e32 v8, v8
	v_exp_f32_e32 v9, v9
	v_add_f32_e32 v2, 1.0, v2
	v_add_f32_e32 v3, 1.0, v3
	v_add_f32_e32 v4, 1.0, v4
	v_add_f32_e32 v5, 1.0, v5
	v_add_f32_e32 v6, 1.0, v6
	v_rcp_f32_e32 v2, v2
	v_add_f32_e32 v7, 1.0, v7
	v_rcp_f32_e32 v3, v3
	v_add_f32_e32 v8, 1.0, v8
	v_rcp_f32_e32 v4, v4
	v_add_f32_e32 v9, 1.0, v9
	v_rcp_f32_e32 v5, v5
	v_rcp_f32_e32 v6, v6
	v_rcp_f32_e32 v7, v7
	v_rcp_f32_e32 v8, v8
	v_rcp_f32_e32 v9, v9
	v_mul_f32_e32 v2, v103, v2
	v_mul_f32_e32 v3, v105, v3
	v_mul_f32_e32 v4, v99, v4
	v_mul_f32_e32 v5, v101, v5
	v_mul_f32_e32 v6, v102, v6
	v_mul_f32_e32 v7, v104, v7
	v_mul_f32_e32 v8, v98, v8
	v_mul_f32_e32 v9, v100, v9
	v_cvt_pk_bf16_f32 v2, v6, v2
	v_cvt_pk_bf16_f32 v3, v7, v3
	v_cvt_pk_bf16_f32 v4, v8, v4
	v_cvt_pk_bf16_f32 v5, v9, v5
	global_store_dwordx4 v[0:1], v[2:5], off offset:256 sc1
	v_add_u32_e32 v0, 0xb0, v134
	v_ashrrev_i32_e32 v1, 31, v0
	v_lshlrev_b64 v[2:3], 12, v[0:1]
	v_lshl_add_u64 v[2:3], s[14:15], 0, v[2:3]
	v_lshl_add_u64 v[2:3], v[2:3], 0, v[130:131]
	global_load_dwordx4 v[4:7], v[2:3], off offset:2048
	v_lshlrev_b64 v[0:1], 11, v[0:1]
	v_lshl_add_u64 v[0:1], v[132:133], 0, v[0:1]
	s_waitcnt vmcnt(0)
	v_lshlrev_b32_e32 v8, 16, v4
	v_and_b32_e32 v4, 0xffff0000, v4
	v_lshlrev_b32_e32 v9, 16, v5
	v_and_b32_e32 v5, 0xffff0000, v5
	v_lshlrev_b32_e32 v10, 16, v6
	v_and_b32_e32 v6, 0xffff0000, v6
	v_lshlrev_b32_e32 v11, 16, v7
	v_and_b32_e32 v7, 0xffff0000, v7
	v_mul_f32_e32 v4, 0xbfb8aa3b, v4
	v_mul_f32_e32 v5, 0xbfb8aa3b, v5
	v_mul_f32_e32 v6, 0xbfb8aa3b, v6
	v_mul_f32_e32 v7, 0xbfb8aa3b, v7
	v_mul_f32_e32 v8, 0xbfb8aa3b, v8
	v_exp_f32_e32 v4, v4
	v_mul_f32_e32 v9, 0xbfb8aa3b, v9
	v_exp_f32_e32 v5, v5
	v_mul_f32_e32 v10, 0xbfb8aa3b, v10
	v_exp_f32_e32 v6, v6
	v_mul_f32_e32 v11, 0xbfb8aa3b, v11
	v_exp_f32_e32 v7, v7
	v_exp_f32_e32 v8, v8
	v_exp_f32_e32 v9, v9
	v_exp_f32_e32 v10, v10
	v_exp_f32_e32 v11, v11
	v_add_f32_e32 v4, 1.0, v4
	v_add_f32_e32 v5, 1.0, v5
	v_add_f32_e32 v6, 1.0, v6
	v_add_f32_e32 v7, 1.0, v7
	v_add_f32_e32 v8, 1.0, v8
	v_rcp_f32_e32 v4, v4
	v_add_f32_e32 v9, 1.0, v9
	v_rcp_f32_e32 v5, v5
	v_add_f32_e32 v10, 1.0, v10
	v_rcp_f32_e32 v6, v6
	v_add_f32_e32 v11, 1.0, v11
	v_rcp_f32_e32 v7, v7
	v_rcp_f32_e32 v8, v8
	v_rcp_f32_e32 v9, v9
	v_rcp_f32_e32 v10, v10
	v_rcp_f32_e32 v11, v11
	v_mul_f32_e32 v4, v63, v4
	v_mul_f32_e32 v5, v65, v5
	v_mul_f32_e32 v6, v43, v6
	v_mul_f32_e32 v7, v45, v7
	v_mul_f32_e32 v8, v62, v8
	v_mul_f32_e32 v9, v64, v9
	v_mul_f32_e32 v10, v42, v10
	v_mul_f32_e32 v11, v44, v11
	v_cvt_pk_bf16_f32 v4, v8, v4
	v_cvt_pk_bf16_f32 v5, v9, v5
	v_cvt_pk_bf16_f32 v6, v10, v6
	v_cvt_pk_bf16_f32 v7, v11, v7
	global_store_dwordx4 v[0:1], v[4:7], off sc1
	global_load_dwordx4 v[2:5], v[2:3], off offset:2304
	s_waitcnt vmcnt(0)
	v_lshlrev_b32_e32 v8, 16, v4
	v_lshlrev_b32_e32 v6, 16, v2
	v_and_b32_e32 v2, 0xffff0000, v2
	v_lshlrev_b32_e32 v7, 16, v3
	v_and_b32_e32 v3, 0xffff0000, v3
	v_and_b32_e32 v4, 0xffff0000, v4
	v_lshlrev_b32_e32 v9, 16, v5
	v_and_b32_e32 v5, 0xffff0000, v5
	v_mul_f32_e32 v2, 0xbfb8aa3b, v2
	v_mul_f32_e32 v3, 0xbfb8aa3b, v3
	v_mul_f32_e32 v4, 0xbfb8aa3b, v4
	v_mul_f32_e32 v5, 0xbfb8aa3b, v5
	v_mul_f32_e32 v6, 0xbfb8aa3b, v6
	v_exp_f32_e32 v2, v2
	v_mul_f32_e32 v7, 0xbfb8aa3b, v7
	v_exp_f32_e32 v3, v3
	v_mul_f32_e32 v8, 0xbfb8aa3b, v8
	v_exp_f32_e32 v4, v4
	v_mul_f32_e32 v9, 0xbfb8aa3b, v9
	v_exp_f32_e32 v5, v5
	v_exp_f32_e32 v6, v6
	v_exp_f32_e32 v7, v7
	v_exp_f32_e32 v8, v8
	v_exp_f32_e32 v9, v9
	v_add_f32_e32 v2, 1.0, v2
	v_add_f32_e32 v3, 1.0, v3
	v_add_f32_e32 v4, 1.0, v4
	v_add_f32_e32 v5, 1.0, v5
	v_add_f32_e32 v6, 1.0, v6
	v_rcp_f32_e32 v2, v2
	v_add_f32_e32 v7, 1.0, v7
	v_rcp_f32_e32 v3, v3
	v_add_f32_e32 v8, 1.0, v8
	v_rcp_f32_e32 v4, v4
	v_add_f32_e32 v9, 1.0, v9
	v_rcp_f32_e32 v5, v5
	v_rcp_f32_e32 v6, v6
	v_rcp_f32_e32 v7, v7
	v_rcp_f32_e32 v8, v8
	v_rcp_f32_e32 v9, v9
	v_mul_f32_e32 v2, v39, v2
	v_mul_f32_e32 v3, v41, v3
	v_mul_f32_e32 v4, v35, v4
	v_mul_f32_e32 v5, v37, v5
	v_mul_f32_e32 v6, v38, v6
	v_mul_f32_e32 v7, v40, v7
	v_mul_f32_e32 v8, v34, v8
	v_mul_f32_e32 v9, v36, v9
	v_cvt_pk_bf16_f32 v2, v6, v2
	v_cvt_pk_bf16_f32 v3, v7, v3
	v_cvt_pk_bf16_f32 v4, v8, v4
	v_cvt_pk_bf16_f32 v5, v9, v5
	global_store_dwordx4 v[0:1], v[2:5], off offset:256 sc1
	s_cbranch_vccnz .LBB0_360
	s_and_b64 vcc, exec, s[42:43]
	s_cbranch_vccnz .LBB0_359
	s_barrier
	s_branch .LBB0_359

; __device__ __forceinline__ unsigned cvt_pk_bf16(float lo, float hi) { unsigned r; asm volatile("v_cvt_pk_bf16_f32 %0, %1, %2" : "=v"(r) : "v"(lo), "v"(hi)); return r; }
;     template <int LDC> __device__ __forceinline__ void store(const f32x4 (&acc)[2][2][4][2], bf16_t* base, int row0) const {
;         bf16_t* rp = base + (size_t)row0 * LDC;
; #pragma unroll
;         for (int ai = 0; ai < 2; ++ai)
; #pragma unroll
;             for (int m = 0; m < 4; ++m) { bf16_t* rowp = rp + (size_t)(ai * HALF + m * 16) * LDC;
; #pragma unroll
;                 for (int bj = 0; bj < 2; ++bj) { const f32x4 v0 = acc[ai][bj][m][0], v1 = acc[ai][bj][m][1];
;                     u32x4 w; w.x = cvt_pk_bf16(v0[0], v0[1]); w.y = cvt_pk_bf16(v0[2], v0[3]); w.z = cvt_pk_bf16(v1[0], v1[1]); w.w = cvt_pk_bf16(v1[2], v1[3]);
;                     *(u32x4*)(rowp + bj * HALF) = w; } }
;     }
;     __device__ __forceinline__ void operator()(const f32x4 (&acc)[2][2][4][2], const Unit& u, int wr, int wc, int fr, int fq) const {
;         const int pn = u.pn; const int row0 = u.pm * BM + wr * 64 + fr, col0 = wc * 32 + 8 * fq;
;         if (pn < 8) { bf16_t* base = (pn < 4 ? XR + pn * 256 : GR + (pn - 4) * 256) + col0; store<1024>(acc, base, row0); }
;         else if (pn < 12) { store_rope<1024>(acc, Q + (pn - 8) * 256 + col0, row0, wc, fq); }
;         else if (pn == 12) { store_rope<512>(acc, KV + col0, row0, wc, fq); }
;         else if (pn == 13) { store<512>(acc, KV + 256 + col0, row0); }
;         else { store<2048>(acc, GL + (pn - 14) * 256 + col0, row0); }
.LBB0_587:
	v_mov_b32_e32 v130, v156
	s_lshl_b32 s45, s64, 8
	s_add_i32 s45, s45, s22
	v_and_b32_e32 v159, 15, v130
	v_ashrrev_i32_e32 v167, 4, v130
	v_readlane_b32 s52, v255, 30
	v_or_b32_e32 v144, s45, v159
	v_lshl_add_u32 v146, v167, 3, s23
	s_cmp_gt_i32 s63, 7
	s_mov_b64 s[18:19], -1
	v_readlane_b32 s53, v255, 31
	s_cbranch_scc0 .LBB0_602
	s_cmp_gt_u32 s63, 11
	s_cbranch_scc0 .LBB0_598
	s_cmp_lt_i32 s63, 13
	s_cbranch_scc1 .LBB0_595
	s_cmp_lg_u32 s63, 13
	s_cbranch_scc0 .LBB0_592
	s_lshl_b32 s18, s63, 9
	s_add_u32 s18, s14, s18
	s_addc_u32 s19, s15, 0
	v_ashrrev_i32_e32 v147, 31, v146
	v_ashrrev_i32_e32 v145, 31, v144
	v_lshl_add_u64 v[130:131], v[146:147], 1, s[18:19]
	v_lshlrev_b64 v[132:133], 12, v[144:145]
	s_movk_i32 s18, 0xe400
	v_lshl_add_u64 v[130:131], v[130:131], 0, v[132:133]
	s_mov_b32 s19, -1
	v_lshl_add_u64 v[132:133], v[130:131], 0, s[18:19]
	s_movk_i32 s18, 0xf000
	v_add_co_u32_e32 v152, vcc, s18, v130
	v_cvt_pk_bf16_f32 v148, v126, v127
	v_cvt_pk_bf16_f32 v149, v128, v129
	v_cvt_pk_bf16_f32 v150, v122, v123
	v_cvt_pk_bf16_f32 v151, v124, v125
	s_nop 1
	v_addc_co_u32_e32 v153, vcc, -1, v131, vcc
	s_mov_b32 s18, 0xe000
	global_store_dwordx4 v[152:153], v[148:151], off offset:-3072 sc1
	s_nop 1
	v_cvt_pk_bf16_f32 v148, v114, v115
	v_cvt_pk_bf16_f32 v149, v116, v117
	v_cvt_pk_bf16_f32 v150, v106, v107
	v_cvt_pk_bf16_f32 v151, v108, v109
	global_store_dwordx4 v[132:133], v[148:151], off offset:256 sc1
	v_add_co_u32_e32 v132, vcc, s18, v130
	s_nop 0
	v_cvt_pk_bf16_f32 v148, v118, v119
	v_cvt_pk_bf16_f32 v149, v120, v121
	v_cvt_pk_bf16_f32 v150, v110, v111
	v_cvt_pk_bf16_f32 v151, v112, v113
	s_nop 0
	v_addc_co_u32_e32 v133, vcc, 0, v131, vcc
	global_store_dwordx4 v[132:133], v[148:151], off offset:1024 sc1
	s_mov_b32 s18, 0x2e000
	s_nop 0
	v_cvt_pk_bf16_f32 v148, v98, v99
	v_cvt_pk_bf16_f32 v149, v100, v101
	v_cvt_pk_bf16_f32 v150, v90, v91
	v_cvt_pk_bf16_f32 v151, v92, v93
	global_store_dwordx4 v[132:133], v[148:151], off offset:1280 sc1
	v_add_co_u32_e32 v132, vcc, s36, v130
	s_nop 0
	v_cvt_pk_bf16_f32 v148, v102, v103
	v_cvt_pk_bf16_f32 v149, v104, v105
	v_cvt_pk_bf16_f32 v150, v94, v95
	v_cvt_pk_bf16_f32 v151, v96, v97
	s_nop 0
	v_addc_co_u32_e32 v133, vcc, 0, v131, vcc
	global_store_dwordx4 v[132:133], v[148:151], off offset:1024 sc1
	s_nop 1
	v_cvt_pk_bf16_f32 v148, v82, v83
	v_cvt_pk_bf16_f32 v149, v84, v85
	v_cvt_pk_bf16_f32 v150, v74, v75
	v_cvt_pk_bf16_f32 v151, v76, v77
	global_store_dwordx4 v[132:133], v[148:151], off offset:1280 sc1
	v_add_co_u32_e32 v132, vcc, s18, v130
	s_nop 0
	v_cvt_pk_bf16_f32 v148, v86, v87
	v_cvt_pk_bf16_f32 v149, v88, v89
	v_cvt_pk_bf16_f32 v150, v78, v79
	v_cvt_pk_bf16_f32 v151, v80, v81
	s_nop 0
	v_addc_co_u32_e32 v133, vcc, 0, v131, vcc
	global_store_dwordx4 v[132:133], v[148:151], off offset:1024 sc1
	s_mov_b32 s18, 0x8e000
	s_nop 0
	v_cvt_pk_bf16_f32 v148, v70, v71
	v_cvt_pk_bf16_f32 v149, v72, v73
	v_cvt_pk_bf16_f32 v150, v66, v67
	v_cvt_pk_bf16_f32 v151, v68, v69
	global_store_dwordx4 v[132:133], v[148:151], off offset:1280 sc1
	v_add_co_u32_e32 v132, vcc, s81, v130
	s_nop 0
	v_cvt_pk_bf16_f32 v148, v62, v63
	v_cvt_pk_bf16_f32 v149, v64, v65
	v_cvt_pk_bf16_f32 v150, v58, v59
	v_cvt_pk_bf16_f32 v151, v60, v61
	s_nop 0
	v_addc_co_u32_e32 v133, vcc, 0, v131, vcc
	global_store_dwordx4 v[132:133], v[148:151], off offset:1024 sc1
	s_nop 1
	v_cvt_pk_bf16_f32 v148, v50, v51
	v_cvt_pk_bf16_f32 v149, v52, v53
	v_cvt_pk_bf16_f32 v150, v42, v43
	v_cvt_pk_bf16_f32 v151, v44, v45
	global_store_dwordx4 v[132:133], v[148:151], off offset:1280 sc1
	v_add_co_u32_e32 v132, vcc, s18, v130
	s_nop 0
	v_cvt_pk_bf16_f32 v148, v54, v55
	v_cvt_pk_bf16_f32 v149, v56, v57
	v_cvt_pk_bf16_f32 v150, v46, v47
	v_cvt_pk_bf16_f32 v151, v48, v49
	s_nop 0
	v_addc_co_u32_e32 v133, vcc, 0, v131, vcc
	s_mov_b32 s18, 0x9e000
	global_store_dwordx4 v[132:133], v[148:151], off offset:1024 sc1
	s_nop 1
	v_cvt_pk_bf16_f32 v148, v34, v35
	v_cvt_pk_bf16_f32 v149, v36, v37
	v_cvt_pk_bf16_f32 v150, v24, v25
	v_cvt_pk_bf16_f32 v151, v26, v27
	global_store_dwordx4 v[132:133], v[148:151], off offset:1280 sc1
	v_add_co_u32_e32 v132, vcc, s18, v130
	s_nop 0
	v_cvt_pk_bf16_f32 v148, v38, v39
	v_cvt_pk_bf16_f32 v149, v40, v41
	v_cvt_pk_bf16_f32 v150, v28, v29
	v_cvt_pk_bf16_f32 v151, v30, v31
	s_nop 0
	v_addc_co_u32_e32 v133, vcc, 0, v131, vcc
	v_add_co_u32_e32 v152, vcc, s82, v130
	global_store_dwordx4 v[132:133], v[148:151], off offset:1024 sc1
	s_nop 0
	v_addc_co_u32_e32 v153, vcc, 0, v131, vcc
	v_cvt_pk_bf16_f32 v148, v16, v17
	v_cvt_pk_bf16_f32 v149, v18, v19
	v_cvt_pk_bf16_f32 v150, v8, v9
	v_cvt_pk_bf16_f32 v151, v10, v11
	global_store_dwordx4 v[132:133], v[148:151], off offset:1280 sc1
	s_mov_b64 s[18:19], 0
	s_nop 0
	v_cvt_pk_bf16_f32 v148, v20, v21
	v_cvt_pk_bf16_f32 v149, v22, v23
	v_cvt_pk_bf16_f32 v150, v12, v13
	v_cvt_pk_bf16_f32 v151, v14, v15
	global_store_dwordx4 v[152:153], v[148:151], off offset:1024 sc1
	v_cvt_pk_bf16_f32 v130, v4, v5
	v_cvt_pk_bf16_f32 v131, v6, v7
	v_cvt_pk_bf16_f32 v132, v0, v1
	v_cvt_pk_bf16_f32 v133, v2, v3
	global_store_dwordx4 v[152:153], v[130:133], off offset:1280 sc1
; __device__ __forceinline__ unsigned cvt_pk_bf16(float lo, float hi) { unsigned r; asm volatile("v_cvt_pk_bf16_f32 %0, %1, %2" : "=v"(r) : "v"(lo), "v"(hi)); return r; }
;     template <int LDC> __device__ __forceinline__ void store(const f32x4 (&acc)[2][2][4][2], bf16_t* base, int row0) const {
;         bf16_t* rp = base + (size_t)row0 * LDC;
; #pragma unroll
;         for (int ai = 0; ai < 2; ++ai)
; #pragma unroll
;             for (int m = 0; m < 4; ++m) { bf16_t* rowp = rp + (size_t)(ai * HALF + m * 16) * LDC;
; #pragma unroll
;                 for (int bj = 0; bj < 2; ++bj) { const f32x4 v0 = acc[ai][bj][m][0], v1 = acc[ai][bj][m][1];
;                     u32x4 w; w.x = cvt_pk_bf16(v0[0], v0[1]); w.y = cvt_pk_bf16(v0[2], v0[3]); w.z = cvt_pk_bf16(v1[0], v1[1]); w.w = cvt_pk_bf16(v1[2], v1[3]);
;                     *(u32x4*)(rowp + bj * HALF) = w; } }
;     }
;     __device__ __forceinline__ void operator()(const f32x4 (&acc)[2][2][4][2], const Unit& u, int wr, int wc, int fr, int fq) const {
;     ...
;         else if (pn == 13) { store<512>(acc, KV + 256 + col0, row0); }
.LBB0_592:
	s_andn2_b64 vcc, exec, s[18:19]
	s_cbranch_vccnz .LBB0_594
	v_ashrrev_i32_e32 v147, 31, v146
	v_ashrrev_i32_e32 v145, 31, v144
	v_lshl_add_u64 v[130:131], v[146:147], 1, s[26:27]
	v_lshlrev_b64 v[132:133], 10, v[144:145]
	v_lshl_add_u64 v[130:131], v[130:131], 0, v[132:133]
	v_cvt_pk_bf16_f32 v148, v126, v127
	v_cvt_pk_bf16_f32 v149, v128, v129
	v_cvt_pk_bf16_f32 v150, v122, v123
	v_cvt_pk_bf16_f32 v151, v124, v125
	s_movk_i32 s18, 0x4000
	global_store_dwordx4 v[130:131], v[148:151], off sc1
	v_add_co_u32_e32 v132, vcc, s18, v130
	s_nop 0
	v_cvt_pk_bf16_f32 v148, v114, v115
	v_cvt_pk_bf16_f32 v149, v116, v117
	v_cvt_pk_bf16_f32 v150, v106, v107
	v_cvt_pk_bf16_f32 v151, v108, v109
	global_store_dwordx4 v[130:131], v[148:151], off offset:256 sc1
	v_addc_co_u32_e32 v133, vcc, 0, v131, vcc
	s_nop 0
	v_cvt_pk_bf16_f32 v148, v118, v119
	v_cvt_pk_bf16_f32 v149, v120, v121
	v_cvt_pk_bf16_f32 v150, v110, v111
	v_cvt_pk_bf16_f32 v151, v112, v113
	s_mov_b32 s18, 0x8000
	global_store_dwordx4 v[132:133], v[148:151], off sc1
	s_nop 1
	v_cvt_pk_bf16_f32 v148, v98, v99
	v_cvt_pk_bf16_f32 v149, v100, v101
	v_cvt_pk_bf16_f32 v150, v90, v91
	v_cvt_pk_bf16_f32 v151, v92, v93
	global_store_dwordx4 v[132:133], v[148:151], off offset:256 sc1
	v_add_co_u32_e32 v132, vcc, s18, v130
	s_nop 0
	v_cvt_pk_bf16_f32 v148, v102, v103
	v_cvt_pk_bf16_f32 v149, v104, v105
	v_cvt_pk_bf16_f32 v150, v94, v95
	v_cvt_pk_bf16_f32 v151, v96, v97
	s_nop 0
	v_addc_co_u32_e32 v133, vcc, 0, v131, vcc
	global_store_dwordx4 v[132:133], v[148:151], off sc1
	s_mov_b32 s18, 0x20000
	s_nop 0
	v_cvt_pk_bf16_f32 v148, v82, v83
	v_cvt_pk_bf16_f32 v149, v84, v85
	v_cvt_pk_bf16_f32 v150, v74, v75
	v_cvt_pk_bf16_f32 v151, v76, v77
	global_store_dwordx4 v[132:133], v[148:151], off offset:256 sc1
	v_add_co_u32_e32 v132, vcc, s95, v130
	s_nop 0
	v_cvt_pk_bf16_f32 v148, v86, v87
	v_cvt_pk_bf16_f32 v149, v88, v89
	v_cvt_pk_bf16_f32 v150, v78, v79
	v_cvt_pk_bf16_f32 v151, v80, v81
	s_nop 0
	v_addc_co_u32_e32 v133, vcc, 0, v131, vcc
	global_store_dwordx4 v[132:133], v[148:151], off sc1
	s_nop 1
	v_cvt_pk_bf16_f32 v148, v70, v71
	v_cvt_pk_bf16_f32 v149, v72, v73
	v_cvt_pk_bf16_f32 v150, v66, v67
	v_cvt_pk_bf16_f32 v151, v68, v69
	global_store_dwordx4 v[132:133], v[148:151], off offset:256 sc1
	v_add_co_u32_e32 v132, vcc, s18, v130
	s_nop 0
	v_cvt_pk_bf16_f32 v148, v62, v63
	v_cvt_pk_bf16_f32 v149, v64, v65
	v_cvt_pk_bf16_f32 v150, v58, v59
	v_cvt_pk_bf16_f32 v151, v60, v61
	s_nop 0
	v_addc_co_u32_e32 v133, vcc, 0, v131, vcc
	global_store_dwordx4 v[132:133], v[148:151], off sc1
	s_mov_b32 s18, 0x28000
	s_nop 0
	v_cvt_pk_bf16_f32 v148, v50, v51
	v_cvt_pk_bf16_f32 v149, v52, v53
	v_cvt_pk_bf16_f32 v150, v42, v43
	v_cvt_pk_bf16_f32 v151, v44, v45
	global_store_dwordx4 v[132:133], v[148:151], off offset:256 sc1
	v_add_co_u32_e32 v132, vcc, s83, v130
	s_nop 0
	v_cvt_pk_bf16_f32 v148, v54, v55
	v_cvt_pk_bf16_f32 v149, v56, v57
	v_cvt_pk_bf16_f32 v150, v46, v47
	v_cvt_pk_bf16_f32 v151, v48, v49
	s_nop 0
	v_addc_co_u32_e32 v133, vcc, 0, v131, vcc
	global_store_dwordx4 v[132:133], v[148:151], off sc1
	s_nop 1
	v_cvt_pk_bf16_f32 v148, v34, v35
	v_cvt_pk_bf16_f32 v149, v36, v37
	v_cvt_pk_bf16_f32 v150, v24, v25
	v_cvt_pk_bf16_f32 v151, v26, v27
	global_store_dwordx4 v[132:133], v[148:151], off offset:256 sc1
	v_add_co_u32_e32 v132, vcc, s18, v130
	s_mov_b32 s18, 0x2c000
	s_nop 0
	v_addc_co_u32_e32 v133, vcc, 0, v131, vcc
	v_cvt_pk_bf16_f32 v148, v38, v39
	v_cvt_pk_bf16_f32 v149, v40, v41
	v_cvt_pk_bf16_f32 v150, v28, v29
	v_cvt_pk_bf16_f32 v151, v30, v31
	v_add_co_u32_e32 v152, vcc, s18, v130
	global_store_dwordx4 v[132:133], v[148:151], off sc1
	s_nop 0
	v_addc_co_u32_e32 v153, vcc, 0, v131, vcc
	v_cvt_pk_bf16_f32 v148, v16, v17
	v_cvt_pk_bf16_f32 v149, v18, v19
	v_cvt_pk_bf16_f32 v150, v8, v9
	v_cvt_pk_bf16_f32 v151, v10, v11
	global_store_dwordx4 v[132:133], v[148:151], off offset:256 sc1
	s_nop 1
	v_cvt_pk_bf16_f32 v148, v20, v21
	v_cvt_pk_bf16_f32 v149, v22, v23
	v_cvt_pk_bf16_f32 v150, v12, v13
	v_cvt_pk_bf16_f32 v151, v14, v15
	global_store_dwordx4 v[152:153], v[148:151], off sc1
	v_cvt_pk_bf16_f32 v130, v4, v5
	v_cvt_pk_bf16_f32 v131, v6, v7
	v_cvt_pk_bf16_f32 v132, v0, v1
	v_cvt_pk_bf16_f32 v133, v2, v3
	global_store_dwordx4 v[152:153], v[130:133], off offset:256 sc1

; __device__ __forceinline__ unsigned cvt_pk_bf16(float lo, float hi) { unsigned r; asm volatile("v_cvt_pk_bf16_f32 %0, %1, %2" : "=v"(r) : "v"(lo), "v"(hi)); return r; }
;     template <int LDC> __device__ __forceinline__ void store_rope(const f32x4 (&acc)[2][2][4][2], bf16_t* base, int row0, int wc, int fq) const {
;         bf16_t* rp = base + (size_t)row0 * LDC; const int axis = wc >> 1, f0 = 16 * (wc & 1) + 4 * fq;
; #pragma unroll
;         for (int ai = 0; ai < 2; ++ai)
; #pragma unroll
;             for (int m = 0; m < 4; ++m) { const int row = row0 + ai * HALF + m * 16; bf16_t* rowp = rp + (size_t)(ai * HALF + m * 16) * LDC;
;                 const int t = row & (SEQ - 1), pos = axis ? (t & 63) : (t >> 6);
;                 f32x4 cs0 = *(const f32x4*)(TAB + (pos * 32 + f0) * 2), cs1 = *(const f32x4*)(TAB + (pos * 32 + f0) * 2 + 4);
;                 if (row >= ML) { cs0 = (f32x4){1.f, 0.f, 1.f, 0.f}; cs1 = cs0; }
; #pragma unroll
;                 for (int bj = 0; bj < 2; ++bj) { const f32x4 x1 = acc[ai][bj][m][0], x2 = acc[ai][bj][m][1];
;                     u32x4 w;
;                     w.x = cvt_pk_bf16(x1[0] * cs0[0] - x2[0] * cs0[1], x1[1] * cs0[2] - x2[1] * cs0[3]);
;                     w.y = cvt_pk_bf16(x1[2] * cs1[0] - x2[2] * cs1[1], x1[3] * cs1[2] - x2[3] * cs1[3]);
;                     w.z = cvt_pk_bf16(x2[0] * cs0[0] + x1[0] * cs0[1], x2[1] * cs0[2] + x1[1] * cs0[3]);
;                     w.w = cvt_pk_bf16(x2[2] * cs1[0] + x1[2] * cs1[1], x2[3] * cs1[2] + x1[3] * cs1[3]);
;                     *(u32x4*)(rowp + bj * HALF) = w; } }
;     }
.LBB0_595:
	s_andn2_b64 vcc, exec, s[18:19]
	s_cbranch_vccnz .LBB0_597
	v_ashrrev_i32_e32 v147, 31, v146
	v_ashrrev_i32_e32 v145, 31, v144
	s_lshr_b32 s18, s45, 6
	v_lshl_add_u64 v[130:131], v[146:147], 1, s[52:53]
	v_lshlrev_b64 v[132:133], 10, v[144:145]
	v_mov_b32_e32 v147, s18
	v_lshl_add_u64 v[148:149], v[130:131], 0, v[132:133]
	v_cndmask_b32_e64 v130, v159, v147, s[40:41]
	v_lshlrev_b32_e32 v130, 5, v130
	v_lshl_add_u32 v145, v167, 2, s39
	v_and_b32_e32 v130, 0x7e0, v130
	v_add_lshl_u32 v130, v130, v145, 1
	v_ashrrev_i32_e32 v131, 31, v130
	v_lshl_add_u64 v[130:131], v[130:131], 2, s[20:21]
	global_load_dwordx4 v[176:179], v[130:131], off offset:16
	s_nop 0
	global_load_dwordx4 v[130:133], v[130:131], off
	s_movk_i32 s18, 0x3fff
	v_cmp_lt_i32_e32 vcc, s18, v144
	v_mov_b32_e32 v161, v108
	s_movk_i32 s18, 0x3fef
	v_mov_b32_e32 v163, v56
	s_waitcnt vmcnt(0)
	v_cndmask_b32_e64 v153, v177, 0, vcc
	v_cndmask_b32_e64 v155, v131, 0, vcc
	v_cndmask_b32_e64 v154, v130, 1.0, vcc
	v_mov_b32_e32 v130, v126
	v_mov_b32_e32 v131, v122
	v_pk_mul_f32 v[130:131], v[130:131], v[154:155]
	v_cndmask_b32_e64 v133, v133, 0, vcc
	v_cndmask_b32_e64 v132, v132, 1.0, vcc
	v_sub_f32_e32 v160, v130, v131
	v_mov_b32_e32 v130, v127
	v_mov_b32_e32 v131, v123
	v_pk_mul_f32 v[130:131], v[130:131], v[132:133]
	v_cndmask_b32_e64 v152, v176, 1.0, vcc
	v_sub_f32_e32 v130, v130, v131
	v_cvt_pk_bf16_f32 v176, v160, v130
	v_mov_b32_e32 v130, v128
	v_mov_b32_e32 v131, v124
	v_pk_mul_f32 v[130:131], v[130:131], v[152:153]
	v_cndmask_b32_e64 v151, v179, 0, vcc
	v_cndmask_b32_e64 v150, v178, 1.0, vcc
	v_sub_f32_e32 v160, v130, v131
	v_mov_b32_e32 v130, v129
	v_mov_b32_e32 v131, v125
	v_pk_mul_f32 v[130:131], v[130:131], v[150:151]
	v_cmp_lt_i32_e32 vcc, s18, v144
	v_sub_f32_e32 v130, v130, v131
	v_cvt_pk_bf16_f32 v177, v160, v130
	v_mov_b32_e32 v130, v122
	v_mov_b32_e32 v131, v126
	v_pk_mul_f32 v[130:131], v[130:131], v[154:155]
	s_movk_i32 s18, 0x4000
	v_add_f32_e32 v160, v131, v130
	v_mov_b32_e32 v130, v123
	v_mov_b32_e32 v131, v127
	v_pk_mul_f32 v[130:131], v[130:131], v[132:133]
	s_nop 0
	v_add_f32_e32 v130, v131, v130
	v_cvt_pk_bf16_f32 v178, v160, v130
	v_mov_b32_e32 v130, v124
	v_mov_b32_e32 v131, v128
	v_pk_mul_f32 v[130:131], v[130:131], v[152:153]
	s_nop 0
	v_add_f32_e32 v160, v131, v130
	v_mov_b32_e32 v130, v125
	v_mov_b32_e32 v131, v129
	v_pk_mul_f32 v[130:131], v[130:131], v[150:151]
	s_nop 0
	v_add_f32_e32 v130, v131, v130
	v_cvt_pk_bf16_f32 v179, v160, v130
	v_mov_b32_e32 v130, v114
	v_mov_b32_e32 v131, v106
	v_pk_mul_f32 v[130:131], v[130:131], v[154:155]
	global_store_dwordx4 v[148:149], v[176:179], off sc1
	v_sub_f32_e32 v160, v130, v131
	v_mov_b32_e32 v130, v115
	v_mov_b32_e32 v131, v107
	v_pk_mul_f32 v[130:131], v[130:131], v[132:133]
	s_nop 0
	v_sub_f32_e32 v130, v130, v131
	v_cvt_pk_bf16_f32 v130, v160, v130
	v_mov_b32_e32 v160, v116
	v_pk_mul_f32 v[160:161], v[160:161], v[152:153]
	s_nop 0
	v_sub_f32_e32 v131, v160, v161
	v_mov_b32_e32 v160, v117
	v_mov_b32_e32 v161, v109
	v_pk_mul_f32 v[160:161], v[160:161], v[150:151]
	s_nop 0
	v_sub_f32_e32 v160, v160, v161
	v_cvt_pk_bf16_f32 v131, v131, v160
	v_mov_b32_e32 v160, v106
	v_mov_b32_e32 v161, v114
	v_pk_mul_f32 v[154:155], v[160:161], v[154:155]
	v_mov_b32_e32 v161, v90
	v_add_f32_e32 v160, v155, v154
	v_mov_b32_e32 v154, v107
	v_mov_b32_e32 v155, v115
	v_pk_mul_f32 v[132:133], v[154:155], v[132:133]
	v_mov_b32_e32 v154, v108
	v_mov_b32_e32 v155, v116
	v_pk_mul_f32 v[152:153], v[154:155], v[152:153]
	v_add_f32_e32 v132, v133, v132
	v_add_f32_e32 v133, v153, v152
	v_mov_b32_e32 v152, v109
	v_mov_b32_e32 v153, v117
	v_pk_mul_f32 v[150:151], v[152:153], v[150:151]
	v_cvt_pk_bf16_f32 v132, v160, v132
	v_mov_b32_e32 v154, v118
	v_add_f32_e32 v150, v151, v150
	v_cvt_pk_bf16_f32 v133, v133, v150
	global_store_dwordx4 v[148:149], v[130:133], off offset:256 sc1
	v_mov_b32_e32 v155, v110
	s_nop 0
	v_or_b32_e32 v130, 16, v144
	v_cndmask_b32_e64 v130, v130, v147, s[40:41]
	v_lshlrev_b32_e32 v130, 5, v130
	v_and_b32_e32 v130, 0x7e0, v130
	v_add_lshl_u32 v130, v130, v145, 1
	v_ashrrev_i32_e32 v131, 31, v130
	v_lshl_add_u64 v[130:131], v[130:131], 2, s[20:21]
	global_load_dwordx4 v[176:179], v[130:131], off offset:16
	s_nop 0
	global_load_dwordx4 v[130:133], v[130:131], off
	s_waitcnt vmcnt(1)
	v_cndmask_b32_e64 v151, v177, 0, vcc
	s_waitcnt vmcnt(0)
; __device__ __forceinline__ unsigned cvt_pk_bf16(float lo, float hi) { unsigned r; asm volatile("v_cvt_pk_bf16_f32 %0, %1, %2" : "=v"(r) : "v"(lo), "v"(hi)); return r; }
;     template <int LDC> __device__ __forceinline__ void store_rope(const f32x4 (&acc)[2][2][4][2], bf16_t* base, int row0, int wc, int fq) const {
;         bf16_t* rp = base + (size_t)row0 * LDC; const int axis = wc >> 1, f0 = 16 * (wc & 1) + 4 * fq;
; #pragma unroll
;         for (int ai = 0; ai < 2; ++ai)
; #pragma unroll
;             for (int m = 0; m < 4; ++m) { const int row = row0 + ai * HALF + m * 16; bf16_t* rowp = rp + (size_t)(ai * HALF + m * 16) * LDC;
;                 const int t = row & (SEQ - 1), pos = axis ? (t & 63) : (t >> 6);
;                 f32x4 cs0 = *(const f32x4*)(TAB + (pos * 32 + f0) * 2), cs1 = *(const f32x4*)(TAB + (pos * 32 + f0) * 2 + 4);
;                 if (row >= ML) { cs0 = (f32x4){1.f, 0.f, 1.f, 0.f}; cs1 = cs0; }
; #pragma unroll
;                 for (int bj = 0; bj < 2; ++bj) { const f32x4 x1 = acc[ai][bj][m][0], x2 = acc[ai][bj][m][1];
;                     u32x4 w;
;                     w.x = cvt_pk_bf16(x1[0] * cs0[0] - x2[0] * cs0[1], x1[1] * cs0[2] - x2[1] * cs0[3]);
;                     w.y = cvt_pk_bf16(x1[2] * cs1[0] - x2[2] * cs1[1], x1[3] * cs1[2] - x2[3] * cs1[3]);
;                     w.z = cvt_pk_bf16(x2[0] * cs0[0] + x1[0] * cs0[1], x2[1] * cs0[2] + x1[1] * cs0[3]);
;                     w.w = cvt_pk_bf16(x2[2] * cs1[0] + x1[2] * cs1[1], x2[3] * cs1[2] + x1[3] * cs1[3]);
;                     *(u32x4*)(rowp + bj * HALF) = w; } }
;     }
	v_cndmask_b32_e64 v153, v131, 0, vcc
	v_cndmask_b32_e64 v152, v130, 1.0, vcc
	v_pk_mul_f32 v[154:155], v[154:155], v[152:153]
	v_cndmask_b32_e64 v133, v133, 0, vcc
	v_cndmask_b32_e64 v132, v132, 1.0, vcc
	v_sub_f32_e32 v160, v154, v155
	v_mov_b32_e32 v154, v119
	v_mov_b32_e32 v155, v111
	v_pk_mul_f32 v[154:155], v[154:155], v[132:133]
	v_cndmask_b32_e64 v150, v176, 1.0, vcc
	v_sub_f32_e32 v154, v154, v155
	v_cvt_pk_bf16_f32 v176, v160, v154
	v_mov_b32_e32 v154, v120
	v_mov_b32_e32 v155, v112
	v_pk_mul_f32 v[154:155], v[154:155], v[150:151]
	v_cndmask_b32_e64 v131, v179, 0, vcc
	v_cndmask_b32_e64 v130, v178, 1.0, vcc
	v_sub_f32_e32 v160, v154, v155
	v_mov_b32_e32 v154, v121
	v_mov_b32_e32 v155, v113
	v_pk_mul_f32 v[154:155], v[154:155], v[130:131]
	s_nop 0
	v_sub_f32_e32 v154, v154, v155
	v_cvt_pk_bf16_f32 v177, v160, v154
	v_mov_b32_e32 v154, v110
	v_mov_b32_e32 v155, v118
	v_pk_mul_f32 v[154:155], v[154:155], v[152:153]
	s_nop 0
	v_add_f32_e32 v160, v155, v154
	v_mov_b32_e32 v154, v111
	v_mov_b32_e32 v155, v119
	v_pk_mul_f32 v[154:155], v[154:155], v[132:133]
	s_nop 0
	v_add_f32_e32 v154, v155, v154
	v_cvt_pk_bf16_f32 v178, v160, v154
	v_mov_b32_e32 v154, v112
	v_mov_b32_e32 v155, v120
	v_pk_mul_f32 v[154:155], v[154:155], v[150:151]
	s_nop 0
	v_add_f32_e32 v160, v155, v154
	v_mov_b32_e32 v154, v113
	v_mov_b32_e32 v155, v121
	v_pk_mul_f32 v[154:155], v[154:155], v[130:131]
	s_nop 0
	v_add_f32_e32 v154, v155, v154
	v_cvt_pk_bf16_f32 v179, v160, v154
	v_mov_b32_e32 v160, v98
	v_pk_mul_f32 v[160:161], v[160:161], v[152:153]
	v_add_co_u32_e32 v154, vcc, s18, v148
	v_sub_f32_e32 v162, v160, v161
	v_mov_b32_e32 v160, v99
	v_mov_b32_e32 v161, v91
	v_pk_mul_f32 v[160:161], v[160:161], v[132:133]
	v_addc_co_u32_e32 v155, vcc, 0, v149, vcc
	v_sub_f32_e32 v160, v160, v161
	global_store_dwordx4 v[154:155], v[176:179], off sc1
	v_mov_b32_e32 v161, v92
	s_movk_i32 s18, 0x3fdf
	v_cvt_pk_bf16_f32 v176, v162, v160
	v_mov_b32_e32 v160, v100
	v_pk_mul_f32 v[160:161], v[160:161], v[150:151]
	v_cmp_lt_i32_e32 vcc, s18, v144
	v_sub_f32_e32 v162, v160, v161
	v_mov_b32_e32 v160, v101
	v_mov_b32_e32 v161, v93
	v_pk_mul_f32 v[160:161], v[160:161], v[130:131]
	s_mov_b32 s18, 0x8000
	v_sub_f32_e32 v160, v160, v161
	v_cvt_pk_bf16_f32 v177, v162, v160
	v_mov_b32_e32 v160, v90
	v_mov_b32_e32 v161, v98
	v_pk_mul_f32 v[152:153], v[160:161], v[152:153]
	v_mov_b32_e32 v161, v74
	v_add_f32_e32 v160, v153, v152
	v_mov_b32_e32 v152, v91
	v_mov_b32_e32 v153, v99
	v_pk_mul_f32 v[132:133], v[152:153], v[132:133]
	s_nop 0
	v_add_f32_e32 v132, v133, v132
	v_cvt_pk_bf16_f32 v178, v160, v132
	v_mov_b32_e32 v132, v92
	v_mov_b32_e32 v133, v100
	v_pk_mul_f32 v[132:133], v[132:133], v[150:151]
	s_nop 0
	v_add_f32_e32 v150, v133, v132
	v_mov_b32_e32 v132, v93
	v_mov_b32_e32 v133, v101
	v_pk_mul_f32 v[130:131], v[132:133], v[130:131]
	s_nop 0
	v_add_f32_e32 v130, v131, v130
	v_cvt_pk_bf16_f32 v179, v150, v130
	v_or_b32_e32 v130, 32, v144
	v_cndmask_b32_e64 v130, v130, v147, s[40:41]
	v_lshlrev_b32_e32 v130, 5, v130
	v_and_b32_e32 v130, 0x7e0, v130
	v_add_lshl_u32 v130, v130, v145, 1
	v_ashrrev_i32_e32 v131, 31, v130
	global_store_dwordx4 v[154:155], v[176:179], off offset:256 sc1
	v_lshl_add_u64 v[130:131], v[130:131], 2, s[20:21]
	global_load_dwordx4 v[176:179], v[130:131], off offset:16
	s_nop 0
	global_load_dwordx4 v[130:133], v[130:131], off
	v_mov_b32_e32 v154, v102
	v_mov_b32_e32 v155, v94
	s_waitcnt vmcnt(1)
	v_cndmask_b32_e64 v151, v177, 0, vcc
	s_waitcnt vmcnt(0)
	v_cndmask_b32_e64 v153, v131, 0, vcc
	v_cndmask_b32_e64 v152, v130, 1.0, vcc
	v_pk_mul_f32 v[154:155], v[154:155], v[152:153]
	v_cndmask_b32_e64 v133, v133, 0, vcc
	v_cndmask_b32_e64 v132, v132, 1.0, vcc
	v_sub_f32_e32 v160, v154, v155
	v_mov_b32_e32 v154, v103
	v_mov_b32_e32 v155, v95
	v_pk_mul_f32 v[154:155], v[154:155], v[132:133]
	v_cndmask_b32_e64 v150, v176, 1.0, vcc
	v_sub_f32_e32 v154, v154, v155
	v_cvt_pk_bf16_f32 v176, v160, v154
	v_mov_b32_e32 v154, v104
	v_mov_b32_e32 v155, v96
	v_pk_mul_f32 v[154:155], v[154:155], v[150:151]
	v_cndmask_b32_e64 v131, v179, 0, vcc
	v_cndmask_b32_e64 v130, v178, 1.0, vcc
	v_sub_f32_e32 v160, v154, v155
	v_mov_b32_e32 v154, v105
	v_mov_b32_e32 v155, v97
	v_pk_mul_f32 v[154:155], v[154:155], v[130:131]
	s_nop 0
	v_sub_f32_e32 v154, v154, v155
	v_cvt_pk_bf16_f32 v177, v160, v154
	v_mov_b32_e32 v154, v94
	v_mov_b32_e32 v155, v102
	v_pk_mul_f32 v[154:155], v[154:155], v[152:153]
	s_nop 0
	v_add_f32_e32 v160, v155, v154
	v_mov_b32_e32 v154, v95
	v_mov_b32_e32 v155, v103
	v_pk_mul_f32 v[154:155], v[154:155], v[132:133]
	s_nop 0
	v_add_f32_e32 v154, v155, v154
	v_cvt_pk_bf16_f32 v178, v160, v154
	v_mov_b32_e32 v154, v96
	v_mov_b32_e32 v155, v104
	v_pk_mul_f32 v[154:155], v[154:155], v[150:151]
	s_nop 0
	v_add_f32_e32 v160, v155, v154
	v_mov_b32_e32 v154, v97
	v_mov_b32_e32 v155, v105
	v_pk_mul_f32 v[154:155], v[154:155], v[130:131]
	s_nop 0
	v_add_f32_e32 v154, v155, v154
	v_cvt_pk_bf16_f32 v179, v160, v154
	v_mov_b32_e32 v160, v82
	v_pk_mul_f32 v[160:161], v[160:161], v[152:153]
	v_add_co_u32_e32 v154, vcc, s18, v148
	v_sub_f32_e32 v162, v160, v161
	v_mov_b32_e32 v160, v83
	v_mov_b32_e32 v161, v75
	v_pk_mul_f32 v[160:161], v[160:161], v[132:133]
	v_addc_co_u32_e32 v155, vcc, 0, v149, vcc
	v_sub_f32_e32 v160, v160, v161
	global_store_dwordx4 v[154:155], v[176:179], off sc1
	v_mov_b32_e32 v161, v76
	s_movk_i32 s18, 0x3fcf
	v_cvt_pk_bf16_f32 v176, v162, v160
	v_mov_b32_e32 v160, v84
	v_pk_mul_f32 v[160:161], v[160:161], v[150:151]
	v_cmp_lt_i32_e32 vcc, s18, v144
	v_sub_f32_e32 v162, v160, v161
	v_mov_b32_e32 v160, v85
	v_mov_b32_e32 v161, v77
	v_pk_mul_f32 v[160:161], v[160:161], v[130:131]
	s_add_i32 s18, s45, 0x80
	v_sub_f32_e32 v160, v160, v161
	v_cvt_pk_bf16_f32 v177, v162, v160
	v_mov_b32_e32 v160, v74
	v_mov_b32_e32 v161, v82
	v_pk_mul_f32 v[152:153], v[160:161], v[152:153]
	v_mov_b32_e32 v161, v66
	v_add_f32_e32 v160, v153, v152
	v_mov_b32_e32 v152, v75
	v_mov_b32_e32 v153, v83
	v_pk_mul_f32 v[132:133], v[152:153], v[132:133]
	s_lshr_b32 s18, s18, 6
	v_add_f32_e32 v132, v133, v132
	v_cvt_pk_bf16_f32 v178, v160, v132
	v_mov_b32_e32 v132, v76
	v_mov_b32_e32 v133, v84
	v_pk_mul_f32 v[132:133], v[132:133], v[150:151]
	v_mov_b32_e32 v160, v70
	v_add_f32_e32 v150, v133, v132
	v_mov_b32_e32 v132, v77
	v_mov_b32_e32 v133, v85
	v_pk_mul_f32 v[130:131], v[132:133], v[130:131]
	v_mov_b32_e32 v162, v48
	v_add_f32_e32 v130, v131, v130
	v_cvt_pk_bf16_f32 v179, v150, v130
	v_or_b32_e32 v130, 48, v144
	v_cndmask_b32_e64 v130, v130, v147, s[40:41]
	v_lshlrev_b32_e32 v130, 5, v130
	v_and_b32_e32 v130, 0x7e0, v130
	v_add_lshl_u32 v130, v130, v145, 1
	v_ashrrev_i32_e32 v131, 31, v130
	global_store_dwordx4 v[154:155], v[176:179], off offset:256 sc1
	v_lshl_add_u64 v[130:131], v[130:131], 2, s[20:21]
	global_load_dwordx4 v[176:179], v[130:131], off offset:16
	s_nop 0
	global_load_dwordx4 v[130:133], v[130:131], off
	v_mov_b32_e32 v154, v86
	v_mov_b32_e32 v155, v78
	s_waitcnt vmcnt(1)
; __device__ __forceinline__ unsigned cvt_pk_bf16(float lo, float hi) { unsigned r; asm volatile("v_cvt_pk_bf16_f32 %0, %1, %2" : "=v"(r) : "v"(lo), "v"(hi)); return r; }
;     template <int LDC> __device__ __forceinline__ void store_rope(const f32x4 (&acc)[2][2][4][2], bf16_t* base, int row0, int wc, int fq) const {
;         bf16_t* rp = base + (size_t)row0 * LDC; const int axis = wc >> 1, f0 = 16 * (wc & 1) + 4 * fq;
; #pragma unroll
;         for (int ai = 0; ai < 2; ++ai)
; #pragma unroll
;             for (int m = 0; m < 4; ++m) { const int row = row0 + ai * HALF + m * 16; bf16_t* rowp = rp + (size_t)(ai * HALF + m * 16) * LDC;
;                 const int t = row & (SEQ - 1), pos = axis ? (t & 63) : (t >> 6);
;                 f32x4 cs0 = *(const f32x4*)(TAB + (pos * 32 + f0) * 2), cs1 = *(const f32x4*)(TAB + (pos * 32 + f0) * 2 + 4);
;                 if (row >= ML) { cs0 = (f32x4){1.f, 0.f, 1.f, 0.f}; cs1 = cs0; }
; #pragma unroll
;                 for (int bj = 0; bj < 2; ++bj) { const f32x4 x1 = acc[ai][bj][m][0], x2 = acc[ai][bj][m][1];
;                     u32x4 w;
;                     w.x = cvt_pk_bf16(x1[0] * cs0[0] - x2[0] * cs0[1], x1[1] * cs0[2] - x2[1] * cs0[3]);
;                     w.y = cvt_pk_bf16(x1[2] * cs1[0] - x2[2] * cs1[1], x1[3] * cs1[2] - x2[3] * cs1[3]);
;                     w.z = cvt_pk_bf16(x2[0] * cs0[0] + x1[0] * cs0[1], x2[1] * cs0[2] + x1[1] * cs0[3]);
;                     w.w = cvt_pk_bf16(x2[2] * cs1[0] + x1[2] * cs1[1], x2[3] * cs1[2] + x1[3] * cs1[3]);
;                     *(u32x4*)(rowp + bj * HALF) = w; } }
;     }
	v_cndmask_b32_e64 v151, v177, 0, vcc
	s_waitcnt vmcnt(0)
	v_cndmask_b32_e64 v153, v131, 0, vcc
	v_cndmask_b32_e64 v152, v130, 1.0, vcc
	v_pk_mul_f32 v[154:155], v[154:155], v[152:153]
	v_cndmask_b32_e64 v133, v133, 0, vcc
	v_cndmask_b32_e64 v132, v132, 1.0, vcc
	v_sub_f32_e32 v147, v154, v155
	v_mov_b32_e32 v154, v87
	v_mov_b32_e32 v155, v79
	v_pk_mul_f32 v[154:155], v[154:155], v[132:133]
	v_cndmask_b32_e64 v150, v176, 1.0, vcc
	v_sub_f32_e32 v154, v154, v155
	v_cvt_pk_bf16_f32 v176, v147, v154
	v_mov_b32_e32 v154, v88
	v_mov_b32_e32 v155, v80
	v_pk_mul_f32 v[154:155], v[154:155], v[150:151]
	v_cndmask_b32_e64 v131, v179, 0, vcc
	v_cndmask_b32_e64 v130, v178, 1.0, vcc
	v_sub_f32_e32 v147, v154, v155
	v_mov_b32_e32 v154, v89
	v_mov_b32_e32 v155, v81
	v_pk_mul_f32 v[154:155], v[154:155], v[130:131]
	v_pk_mul_f32 v[160:161], v[160:161], v[152:153]
	v_sub_f32_e32 v154, v154, v155
	v_cvt_pk_bf16_f32 v177, v147, v154
	v_mov_b32_e32 v154, v78
	v_mov_b32_e32 v155, v86
	v_pk_mul_f32 v[154:155], v[154:155], v[152:153]
	s_nop 0
	v_add_f32_e32 v147, v155, v154
	v_mov_b32_e32 v154, v79
	v_mov_b32_e32 v155, v87
	v_pk_mul_f32 v[154:155], v[154:155], v[132:133]
	s_nop 0
	v_add_f32_e32 v154, v155, v154
	v_cvt_pk_bf16_f32 v178, v147, v154
	v_mov_b32_e32 v154, v80
	v_mov_b32_e32 v155, v88
	v_pk_mul_f32 v[154:155], v[154:155], v[150:151]
	s_nop 0
	v_add_f32_e32 v147, v155, v154
	v_mov_b32_e32 v154, v81
	v_mov_b32_e32 v155, v89
	v_pk_mul_f32 v[154:155], v[154:155], v[130:131]
	s_nop 0
	v_add_f32_e32 v154, v155, v154
	v_cvt_pk_bf16_f32 v179, v147, v154
	v_sub_f32_e32 v147, v160, v161
	v_mov_b32_e32 v160, v71
	v_mov_b32_e32 v161, v67
	v_add_co_u32_e32 v154, vcc, s95, v148
	v_pk_mul_f32 v[160:161], v[160:161], v[132:133]
	s_nop 0
	v_addc_co_u32_e32 v155, vcc, 0, v149, vcc
	v_sub_f32_e32 v160, v160, v161
	global_store_dwordx4 v[154:155], v[176:179], off sc1
	v_mov_b32_e32 v161, v68
	s_nop 0
	v_cvt_pk_bf16_f32 v176, v147, v160
	v_mov_b32_e32 v160, v72
	v_pk_mul_f32 v[160:161], v[160:161], v[150:151]
	s_nop 0
	v_sub_f32_e32 v147, v160, v161
	v_mov_b32_e32 v160, v73
	v_mov_b32_e32 v161, v69
	v_pk_mul_f32 v[160:161], v[160:161], v[130:131]
	s_nop 0
	v_sub_f32_e32 v160, v160, v161
	v_cvt_pk_bf16_f32 v177, v147, v160
	v_mov_b32_e32 v160, v66
	v_mov_b32_e32 v161, v70
	v_pk_mul_f32 v[152:153], v[160:161], v[152:153]
	v_mov_b32_e32 v160, v50
	v_add_f32_e32 v147, v153, v152
	v_mov_b32_e32 v152, v67
	v_mov_b32_e32 v153, v71
	v_pk_mul_f32 v[132:133], v[152:153], v[132:133]
	v_mov_b32_e32 v161, v42
	v_add_f32_e32 v132, v133, v132
	v_cvt_pk_bf16_f32 v178, v147, v132
	v_mov_b32_e32 v132, v68
	v_mov_b32_e32 v133, v72
	v_pk_mul_f32 v[132:133], v[132:133], v[150:151]
	s_nop 0
	v_add_f32_e32 v147, v133, v132
	v_mov_b32_e32 v132, v69
	v_mov_b32_e32 v133, v73
	v_pk_mul_f32 v[130:131], v[132:133], v[130:131]
	s_nop 0
	v_add_f32_e32 v130, v131, v130
	v_cvt_pk_bf16_f32 v179, v147, v130
	v_mov_b32_e32 v130, s18
	v_cndmask_b32_e64 v130, v159, v130, s[40:41]
	v_lshlrev_b32_e32 v130, 5, v130
	v_and_b32_e32 v130, 0x7e0, v130
	v_add_lshl_u32 v130, v130, v145, 1
	v_ashrrev_i32_e32 v131, 31, v130
	global_store_dwordx4 v[154:155], v[176:179], off offset:256 sc1
	v_lshl_add_u64 v[130:131], v[130:131], 2, s[20:21]
	global_load_dwordx4 v[176:179], v[130:131], off offset:16
	s_nop 0
	global_load_dwordx4 v[130:133], v[130:131], off
	s_movk_i32 s18, 0x3f7f
	v_cmp_lt_i32_e32 vcc, s18, v144
	v_mov_b32_e32 v154, v62
	v_mov_b32_e32 v155, v58
	s_mov_b32 s18, 0x20000
	s_waitcnt vmcnt(1)
	v_cndmask_b32_e64 v151, v177, 0, vcc
	s_waitcnt vmcnt(0)
	v_cndmask_b32_e64 v153, v131, 0, vcc
	v_cndmask_b32_e64 v152, v130, 1.0, vcc
	v_pk_mul_f32 v[154:155], v[154:155], v[152:153]
	v_cndmask_b32_e64 v133, v133, 0, vcc
	v_cndmask_b32_e64 v132, v132, 1.0, vcc
	v_sub_f32_e32 v147, v154, v155
	v_mov_b32_e32 v154, v63
	v_mov_b32_e32 v155, v59
	v_pk_mul_f32 v[154:155], v[154:155], v[132:133]
	v_cndmask_b32_e64 v150, v176, 1.0, vcc
	v_sub_f32_e32 v154, v154, v155
	v_cvt_pk_bf16_f32 v176, v147, v154
	v_mov_b32_e32 v154, v64
	v_mov_b32_e32 v155, v60
	v_pk_mul_f32 v[154:155], v[154:155], v[150:151]
	v_cndmask_b32_e64 v131, v179, 0, vcc
	v_cndmask_b32_e64 v130, v178, 1.0, vcc
	v_sub_f32_e32 v147, v154, v155
	v_mov_b32_e32 v154, v65
	v_mov_b32_e32 v155, v61
	v_pk_mul_f32 v[154:155], v[154:155], v[130:131]
	v_pk_mul_f32 v[160:161], v[160:161], v[152:153]
	v_sub_f32_e32 v154, v154, v155
	v_cvt_pk_bf16_f32 v177, v147, v154
	v_mov_b32_e32 v154, v58
	v_mov_b32_e32 v155, v62
	v_pk_mul_f32 v[154:155], v[154:155], v[152:153]
	s_nop 0
	v_add_f32_e32 v147, v155, v154
	v_mov_b32_e32 v154, v59
	v_mov_b32_e32 v155, v63
	v_pk_mul_f32 v[154:155], v[154:155], v[132:133]
	s_nop 0
	v_add_f32_e32 v154, v155, v154
	v_cvt_pk_bf16_f32 v178, v147, v154
	v_mov_b32_e32 v154, v60
	v_mov_b32_e32 v155, v64
	v_pk_mul_f32 v[154:155], v[154:155], v[150:151]
	s_nop 0
	v_add_f32_e32 v147, v155, v154
	v_mov_b32_e32 v154, v61
	v_mov_b32_e32 v155, v65
	v_pk_mul_f32 v[154:155], v[154:155], v[130:131]
	s_nop 0
	v_add_f32_e32 v154, v155, v154
	v_cvt_pk_bf16_f32 v179, v147, v154
	v_sub_f32_e32 v147, v160, v161
	v_mov_b32_e32 v160, v51
	v_mov_b32_e32 v161, v43
	v_add_co_u32_e32 v154, vcc, s18, v148
	v_pk_mul_f32 v[160:161], v[160:161], v[132:133]
	s_nop 0
	v_addc_co_u32_e32 v155, vcc, 0, v149, vcc
	v_sub_f32_e32 v160, v160, v161
	global_store_dwordx4 v[154:155], v[176:179], off sc1
	v_mov_b32_e32 v161, v44
	s_movk_i32 s18, 0x3f6f
	v_cvt_pk_bf16_f32 v176, v147, v160
	v_mov_b32_e32 v160, v52
	v_pk_mul_f32 v[160:161], v[160:161], v[150:151]
	v_cmp_lt_i32_e32 vcc, s18, v144
	v_sub_f32_e32 v147, v160, v161
	v_mov_b32_e32 v160, v53
	v_mov_b32_e32 v161, v45
	v_pk_mul_f32 v[160:161], v[160:161], v[130:131]
	s_movk_i32 s18, 0x3f5f
	v_sub_f32_e32 v160, v160, v161
	v_cvt_pk_bf16_f32 v177, v147, v160
	v_mov_b32_e32 v160, v42
	v_mov_b32_e32 v161, v50
	v_pk_mul_f32 v[152:153], v[160:161], v[152:153]
	s_nop 0
	v_add_f32_e32 v147, v153, v152
	v_mov_b32_e32 v152, v43
	v_mov_b32_e32 v153, v51
	v_pk_mul_f32 v[132:133], v[152:153], v[132:133]
	s_nop 0
	v_add_f32_e32 v132, v133, v132
	v_cvt_pk_bf16_f32 v178, v147, v132
	v_mov_b32_e32 v132, v44
	v_mov_b32_e32 v133, v52
	v_pk_mul_f32 v[132:133], v[132:133], v[150:151]
	s_nop 0
	v_add_f32_e32 v147, v133, v132
	v_mov_b32_e32 v132, v45
	v_mov_b32_e32 v133, v53
	v_pk_mul_f32 v[130:131], v[132:133], v[130:131]
	s_nop 0
	v_add_f32_e32 v130, v131, v130
	v_cvt_pk_bf16_f32 v179, v147, v130
	v_add_u32_e32 v130, 0x90, v144
	v_lshrrev_b32_e32 v131, 6, v130
	v_cndmask_b32_e64 v130, v130, v131, s[40:41]
	v_lshlrev_b32_e32 v130, 5, v130
	v_and_b32_e32 v130, 0x7e0, v130
	v_add_lshl_u32 v130, v130, v145, 1
	v_ashrrev_i32_e32 v131, 31, v130
	global_store_dwordx4 v[154:155], v[176:179], off offset:256 sc1
	v_lshl_add_u64 v[150:151], v[130:131], 2, s[20:21]
	global_load_dwordx4 v[130:133], v[150:151], off offset:16
	s_nop 0
	global_load_dwordx4 v[150:153], v[150:151], off
	s_waitcnt vmcnt(1)
; __device__ __forceinline__ unsigned cvt_pk_bf16(float lo, float hi) { unsigned r; asm volatile("v_cvt_pk_bf16_f32 %0, %1, %2" : "=v"(r) : "v"(lo), "v"(hi)); return r; }
;     template <int LDC> __device__ __forceinline__ void store_rope(const f32x4 (&acc)[2][2][4][2], bf16_t* base, int row0, int wc, int fq) const {
;         bf16_t* rp = base + (size_t)row0 * LDC; const int axis = wc >> 1, f0 = 16 * (wc & 1) + 4 * fq;
; #pragma unroll
;         for (int ai = 0; ai < 2; ++ai)
; #pragma unroll
;             for (int m = 0; m < 4; ++m) { const int row = row0 + ai * HALF + m * 16; bf16_t* rowp = rp + (size_t)(ai * HALF + m * 16) * LDC;
;                 const int t = row & (SEQ - 1), pos = axis ? (t & 63) : (t >> 6);
;                 f32x4 cs0 = *(const f32x4*)(TAB + (pos * 32 + f0) * 2), cs1 = *(const f32x4*)(TAB + (pos * 32 + f0) * 2 + 4);
;                 if (row >= ML) { cs0 = (f32x4){1.f, 0.f, 1.f, 0.f}; cs1 = cs0; }
; #pragma unroll
;                 for (int bj = 0; bj < 2; ++bj) { const f32x4 x1 = acc[ai][bj][m][0], x2 = acc[ai][bj][m][1];
;                     u32x4 w;
;                     w.x = cvt_pk_bf16(x1[0] * cs0[0] - x2[0] * cs0[1], x1[1] * cs0[2] - x2[1] * cs0[3]);
;                     w.y = cvt_pk_bf16(x1[2] * cs1[0] - x2[2] * cs1[1], x1[3] * cs1[2] - x2[3] * cs1[3]);
;                     w.z = cvt_pk_bf16(x2[0] * cs0[0] + x1[0] * cs0[1], x2[1] * cs0[2] + x1[1] * cs0[3]);
;                     w.w = cvt_pk_bf16(x2[2] * cs1[0] + x1[2] * cs1[1], x2[3] * cs1[2] + x1[3] * cs1[3]);
;                     *(u32x4*)(rowp + bj * HALF) = w; } }
;     }
	v_cndmask_b32_e64 v161, v131, 0, vcc
	s_waitcnt vmcnt(0)
	v_cndmask_b32_e64 v151, v151, 0, vcc
	v_cndmask_b32_e64 v150, v150, 1.0, vcc
	v_cndmask_b32_e64 v160, v130, 1.0, vcc
	v_mov_b32_e32 v130, v54
	v_mov_b32_e32 v131, v46
	v_pk_mul_f32 v[130:131], v[130:131], v[150:151]
	v_cndmask_b32_e64 v153, v153, 0, vcc
	v_cndmask_b32_e64 v152, v152, 1.0, vcc
	v_cndmask_b32_e64 v154, v132, 1.0, vcc
	v_sub_f32_e32 v132, v130, v131
	v_mov_b32_e32 v130, v55
	v_mov_b32_e32 v131, v47
	v_pk_mul_f32 v[130:131], v[130:131], v[152:153]
	v_cndmask_b32_e64 v155, v133, 0, vcc
	v_sub_f32_e32 v130, v130, v131
	v_cvt_pk_bf16_f32 v130, v132, v130
	v_mov_b32_e32 v132, v56
	v_mov_b32_e32 v133, v48
	v_pk_mul_f32 v[132:133], v[132:133], v[160:161]
	v_pk_mul_f32 v[162:163], v[162:163], v[160:161]
	v_sub_f32_e32 v131, v132, v133
	v_mov_b32_e32 v132, v57
	v_mov_b32_e32 v133, v49
	v_pk_mul_f32 v[132:133], v[132:133], v[154:155]
	s_nop 0
	v_sub_f32_e32 v132, v132, v133
	v_cvt_pk_bf16_f32 v131, v131, v132
	v_mov_b32_e32 v132, v46
	v_mov_b32_e32 v133, v54
	v_pk_mul_f32 v[132:133], v[132:133], v[150:151]
	s_nop 0
	v_add_f32_e32 v147, v133, v132
	v_mov_b32_e32 v132, v47
	v_mov_b32_e32 v133, v55
	v_pk_mul_f32 v[132:133], v[132:133], v[152:153]
	s_nop 0
	v_add_f32_e32 v132, v133, v132
	v_add_f32_e32 v133, v163, v162
	v_mov_b32_e32 v162, v49
	v_mov_b32_e32 v163, v57
	v_pk_mul_f32 v[162:163], v[162:163], v[154:155]
	v_cvt_pk_bf16_f32 v132, v147, v132
	s_nop 0
	v_add_f32_e32 v147, v163, v162
	v_add_co_u32_e32 v162, vcc, s83, v148
	v_cvt_pk_bf16_f32 v133, v133, v147
	s_nop 1
	v_addc_co_u32_e32 v163, vcc, 0, v149, vcc
	global_store_dwordx4 v[162:163], v[130:133], off sc1
	v_cmp_lt_i32_e32 vcc, s18, v144
	s_mov_b32 s18, 0x28000
	v_mov_b32_e32 v130, v34
	v_mov_b32_e32 v131, v24
	v_pk_mul_f32 v[130:131], v[130:131], v[150:151]
	v_mov_b32_e32 v133, v26
	v_sub_f32_e32 v132, v130, v131
	v_mov_b32_e32 v130, v35
	v_mov_b32_e32 v131, v25
	v_pk_mul_f32 v[130:131], v[130:131], v[152:153]
	s_nop 0
	v_sub_f32_e32 v130, v130, v131
	v_cvt_pk_bf16_f32 v130, v132, v130
	v_mov_b32_e32 v132, v36
	v_pk_mul_f32 v[132:133], v[132:133], v[160:161]
	s_nop 0
	v_sub_f32_e32 v131, v132, v133
	v_mov_b32_e32 v132, v37
	v_mov_b32_e32 v133, v27
	v_pk_mul_f32 v[132:133], v[132:133], v[154:155]
	s_nop 0
	v_sub_f32_e32 v132, v132, v133
	v_cvt_pk_bf16_f32 v131, v131, v132
	v_mov_b32_e32 v132, v24
	v_mov_b32_e32 v133, v34
	v_pk_mul_f32 v[132:133], v[132:133], v[150:151]
	v_mov_b32_e32 v150, v26
	v_add_f32_e32 v147, v133, v132
	v_mov_b32_e32 v132, v25
	v_mov_b32_e32 v133, v35
	v_mov_b32_e32 v151, v36
	v_pk_mul_f32 v[132:133], v[132:133], v[152:153]
	v_pk_mul_f32 v[150:151], v[150:151], v[160:161]
	v_add_f32_e32 v132, v133, v132
	v_add_f32_e32 v133, v151, v150
	v_mov_b32_e32 v150, v27
	v_mov_b32_e32 v151, v37
	v_pk_mul_f32 v[150:151], v[150:151], v[154:155]
	v_cvt_pk_bf16_f32 v132, v147, v132
	s_nop 0
	v_add_f32_e32 v147, v151, v150
	v_cvt_pk_bf16_f32 v133, v133, v147
	global_store_dwordx4 v[162:163], v[130:133], off offset:256 sc1
	v_mov_b32_e32 v162, v30
	v_mov_b32_e32 v163, v40
	v_add_u32_e32 v130, 0xa0, v144
	v_lshrrev_b32_e32 v131, 6, v130
	v_cndmask_b32_e64 v130, v130, v131, s[40:41]
	v_lshlrev_b32_e32 v130, 5, v130
	v_and_b32_e32 v130, 0x7e0, v130
	v_add_lshl_u32 v130, v130, v145, 1
	v_ashrrev_i32_e32 v131, 31, v130
	v_lshl_add_u64 v[150:151], v[130:131], 2, s[20:21]
	global_load_dwordx4 v[130:133], v[150:151], off offset:16
	s_nop 0
	global_load_dwordx4 v[150:153], v[150:151], off
	s_waitcnt vmcnt(1)
	v_cndmask_b32_e64 v161, v131, 0, vcc
	s_waitcnt vmcnt(0)
; __device__ __forceinline__ unsigned cvt_pk_bf16(float lo, float hi) { unsigned r; asm volatile("v_cvt_pk_bf16_f32 %0, %1, %2" : "=v"(r) : "v"(lo), "v"(hi)); return r; }
;     template <int LDC> __device__ __forceinline__ void store_rope(const f32x4 (&acc)[2][2][4][2], bf16_t* base, int row0, int wc, int fq) const {
;         bf16_t* rp = base + (size_t)row0 * LDC; const int axis = wc >> 1, f0 = 16 * (wc & 1) + 4 * fq;
; #pragma unroll
;         for (int ai = 0; ai < 2; ++ai)
; #pragma unroll
;             for (int m = 0; m < 4; ++m) { const int row = row0 + ai * HALF + m * 16; bf16_t* rowp = rp + (size_t)(ai * HALF + m * 16) * LDC;
;                 const int t = row & (SEQ - 1), pos = axis ? (t & 63) : (t >> 6);
;                 f32x4 cs0 = *(const f32x4*)(TAB + (pos * 32 + f0) * 2), cs1 = *(const f32x4*)(TAB + (pos * 32 + f0) * 2 + 4);
;                 if (row >= ML) { cs0 = (f32x4){1.f, 0.f, 1.f, 0.f}; cs1 = cs0; }
; #pragma unroll
;                 for (int bj = 0; bj < 2; ++bj) { const f32x4 x1 = acc[ai][bj][m][0], x2 = acc[ai][bj][m][1];
;                     u32x4 w;
;                     w.x = cvt_pk_bf16(x1[0] * cs0[0] - x2[0] * cs0[1], x1[1] * cs0[2] - x2[1] * cs0[3]);
;                     w.y = cvt_pk_bf16(x1[2] * cs1[0] - x2[2] * cs1[1], x1[3] * cs1[2] - x2[3] * cs1[3]);
;                     w.z = cvt_pk_bf16(x2[0] * cs0[0] + x1[0] * cs0[1], x2[1] * cs0[2] + x1[1] * cs0[3]);
;                     w.w = cvt_pk_bf16(x2[2] * cs1[0] + x1[2] * cs1[1], x2[3] * cs1[2] + x1[3] * cs1[3]);
;                     *(u32x4*)(rowp + bj * HALF) = w; } }
;     }
	v_cndmask_b32_e64 v151, v151, 0, vcc
	v_cndmask_b32_e64 v150, v150, 1.0, vcc
	v_cndmask_b32_e64 v160, v130, 1.0, vcc
	v_mov_b32_e32 v130, v38
	v_mov_b32_e32 v131, v28
	v_pk_mul_f32 v[130:131], v[130:131], v[150:151]
	v_cndmask_b32_e64 v153, v153, 0, vcc
	v_cndmask_b32_e64 v152, v152, 1.0, vcc
	v_cndmask_b32_e64 v154, v132, 1.0, vcc
	v_sub_f32_e32 v132, v130, v131
	v_mov_b32_e32 v130, v39
	v_mov_b32_e32 v131, v29
	v_pk_mul_f32 v[130:131], v[130:131], v[152:153]
	v_cndmask_b32_e64 v155, v133, 0, vcc
	v_sub_f32_e32 v130, v130, v131
	v_cvt_pk_bf16_f32 v130, v132, v130
	v_mov_b32_e32 v132, v40
	v_mov_b32_e32 v133, v30
	v_pk_mul_f32 v[132:133], v[132:133], v[160:161]
	v_pk_mul_f32 v[162:163], v[162:163], v[160:161]
	v_sub_f32_e32 v131, v132, v133
	v_mov_b32_e32 v132, v41
	v_mov_b32_e32 v133, v31
	v_pk_mul_f32 v[132:133], v[132:133], v[154:155]
	s_nop 0
	v_sub_f32_e32 v132, v132, v133
	v_cvt_pk_bf16_f32 v131, v131, v132
	v_mov_b32_e32 v132, v28
	v_mov_b32_e32 v133, v38
	v_pk_mul_f32 v[132:133], v[132:133], v[150:151]
	s_nop 0
	v_add_f32_e32 v147, v133, v132
	v_mov_b32_e32 v132, v29
	v_mov_b32_e32 v133, v39
	v_pk_mul_f32 v[132:133], v[132:133], v[152:153]
	s_nop 0
	v_add_f32_e32 v132, v133, v132
	v_add_f32_e32 v133, v163, v162
	v_mov_b32_e32 v162, v31
	v_mov_b32_e32 v163, v41
	v_pk_mul_f32 v[162:163], v[162:163], v[154:155]
	v_cvt_pk_bf16_f32 v132, v147, v132
	s_nop 0
	v_add_f32_e32 v147, v163, v162
	v_add_co_u32_e32 v162, vcc, s18, v148
	v_cvt_pk_bf16_f32 v133, v133, v147
	s_movk_i32 s18, 0x3f4f
	s_nop 0
	v_addc_co_u32_e32 v163, vcc, 0, v149, vcc
	global_store_dwordx4 v[162:163], v[130:133], off sc1
	v_cmp_lt_i32_e32 vcc, s18, v144
	s_mov_b32 s18, 0x2c000
	v_mov_b32_e32 v130, v16
	v_mov_b32_e32 v131, v8
	v_pk_mul_f32 v[130:131], v[130:131], v[150:151]
	v_mov_b32_e32 v133, v10
	v_sub_f32_e32 v132, v130, v131
	v_mov_b32_e32 v130, v17
	v_mov_b32_e32 v131, v9
	v_pk_mul_f32 v[130:131], v[130:131], v[152:153]
	s_nop 0
	v_sub_f32_e32 v130, v130, v131
	v_cvt_pk_bf16_f32 v130, v132, v130
	v_mov_b32_e32 v132, v18
	v_pk_mul_f32 v[132:133], v[132:133], v[160:161]
	s_nop 0
	v_sub_f32_e32 v131, v132, v133
	v_mov_b32_e32 v132, v19
	v_mov_b32_e32 v133, v11
	v_pk_mul_f32 v[132:133], v[132:133], v[154:155]
	s_nop 0
	v_sub_f32_e32 v132, v132, v133
	v_cvt_pk_bf16_f32 v131, v131, v132
	v_mov_b32_e32 v132, v8
	v_mov_b32_e32 v133, v16
	v_pk_mul_f32 v[132:133], v[132:133], v[150:151]
	v_mov_b32_e32 v150, v10
	v_add_f32_e32 v147, v133, v132
	v_mov_b32_e32 v132, v9
	v_mov_b32_e32 v133, v17
	v_mov_b32_e32 v151, v18
	v_pk_mul_f32 v[132:133], v[132:133], v[152:153]
	v_pk_mul_f32 v[150:151], v[150:151], v[160:161]
	v_add_f32_e32 v132, v133, v132
	v_add_f32_e32 v133, v151, v150
	v_mov_b32_e32 v150, v11
	v_mov_b32_e32 v151, v19
	v_pk_mul_f32 v[150:151], v[150:151], v[154:155]
	v_cvt_pk_bf16_f32 v132, v147, v132
	s_nop 0
	v_add_f32_e32 v147, v151, v150
	v_cvt_pk_bf16_f32 v133, v133, v147
	global_store_dwordx4 v[162:163], v[130:133], off offset:256 sc1
	v_mov_b32_e32 v162, v14
	v_mov_b32_e32 v163, v22
	v_add_u32_e32 v130, 0xb0, v144
	v_lshrrev_b32_e32 v131, 6, v130
	v_cndmask_b32_e64 v130, v130, v131, s[40:41]
	v_lshlrev_b32_e32 v130, 5, v130
	v_and_b32_e32 v130, 0x7e0, v130
	v_add_lshl_u32 v130, v130, v145, 1
	v_ashrrev_i32_e32 v131, 31, v130
	v_lshl_add_u64 v[150:151], v[130:131], 2, s[20:21]
	global_load_dwordx4 v[130:133], v[150:151], off offset:16
	s_nop 0
	global_load_dwordx4 v[150:153], v[150:151], off
	s_waitcnt vmcnt(1)
	v_cndmask_b32_e64 v161, v131, 0, vcc
	s_waitcnt vmcnt(0)
	v_cndmask_b32_e64 v151, v151, 0, vcc
	v_cndmask_b32_e64 v150, v150, 1.0, vcc
	v_cndmask_b32_e64 v160, v130, 1.0, vcc
	v_mov_b32_e32 v130, v20
	v_mov_b32_e32 v131, v12
	v_pk_mul_f32 v[130:131], v[130:131], v[150:151]
	v_cndmask_b32_e64 v153, v153, 0, vcc
	v_cndmask_b32_e64 v152, v152, 1.0, vcc
	v_cndmask_b32_e64 v154, v132, 1.0, vcc
	v_sub_f32_e32 v132, v130, v131
	v_mov_b32_e32 v130, v21
	v_mov_b32_e32 v131, v13
	v_pk_mul_f32 v[130:131], v[130:131], v[152:153]
	v_cndmask_b32_e64 v155, v133, 0, vcc
	v_sub_f32_e32 v130, v130, v131
	v_cvt_pk_bf16_f32 v130, v132, v130
	v_mov_b32_e32 v132, v22
	v_mov_b32_e32 v133, v14
	v_pk_mul_f32 v[132:133], v[132:133], v[160:161]
	v_pk_mul_f32 v[162:163], v[162:163], v[160:161]
	v_sub_f32_e32 v131, v132, v133
	v_mov_b32_e32 v132, v23
	v_mov_b32_e32 v133, v15
	v_pk_mul_f32 v[132:133], v[132:133], v[154:155]
	v_add_co_u32_e32 v148, vcc, s18, v148
	v_sub_f32_e32 v132, v132, v133
	v_cvt_pk_bf16_f32 v131, v131, v132
	v_mov_b32_e32 v132, v12
	v_mov_b32_e32 v133, v20
	v_pk_mul_f32 v[132:133], v[132:133], v[150:151]
	v_addc_co_u32_e32 v149, vcc, 0, v149, vcc
	v_add_f32_e32 v145, v133, v132
	v_mov_b32_e32 v132, v13
	v_mov_b32_e32 v133, v21
	v_pk_mul_f32 v[132:133], v[132:133], v[152:153]
	s_nop 0
	v_add_f32_e32 v132, v133, v132
	v_add_f32_e32 v133, v163, v162
	v_mov_b32_e32 v162, v15
	v_mov_b32_e32 v163, v23
	v_pk_mul_f32 v[162:163], v[162:163], v[154:155]
	v_cvt_pk_bf16_f32 v132, v145, v132
	s_nop 0
	v_add_f32_e32 v145, v163, v162
	v_cvt_pk_bf16_f32 v133, v133, v145
	global_store_dwordx4 v[148:149], v[130:133], off sc1
	s_nop 1
	v_mov_b32_e32 v130, v4
	v_mov_b32_e32 v131, v0
	v_pk_mul_f32 v[130:131], v[130:131], v[150:151]
	v_mov_b32_e32 v133, v2
	v_sub_f32_e32 v132, v130, v131
	v_mov_b32_e32 v130, v5
	v_mov_b32_e32 v131, v1
	v_pk_mul_f32 v[130:131], v[130:131], v[152:153]
	s_nop 0
	v_sub_f32_e32 v130, v130, v131
	v_cvt_pk_bf16_f32 v130, v132, v130
	v_mov_b32_e32 v132, v6
	v_pk_mul_f32 v[132:133], v[132:133], v[160:161]
	s_nop 0
	v_sub_f32_e32 v131, v132, v133
	v_mov_b32_e32 v132, v7
	v_mov_b32_e32 v133, v3
	v_pk_mul_f32 v[132:133], v[132:133], v[154:155]
	s_nop 0
	v_sub_f32_e32 v132, v132, v133
	v_cvt_pk_bf16_f32 v131, v131, v132
	v_mov_b32_e32 v132, v0
	v_mov_b32_e32 v133, v4
	v_pk_mul_f32 v[132:133], v[132:133], v[150:151]
	v_mov_b32_e32 v150, v2
	v_add_f32_e32 v145, v133, v132
	v_mov_b32_e32 v132, v1
	v_mov_b32_e32 v133, v5
	v_mov_b32_e32 v151, v6
	v_pk_mul_f32 v[132:133], v[132:133], v[152:153]
	v_pk_mul_f32 v[150:151], v[150:151], v[160:161]
	v_add_f32_e32 v132, v133, v132
	v_add_f32_e32 v133, v151, v150
	v_mov_b32_e32 v150, v3
	v_mov_b32_e32 v151, v7
	v_pk_mul_f32 v[150:151], v[150:151], v[154:155]
	v_cvt_pk_bf16_f32 v132, v145, v132
	s_nop 0
	v_add_f32_e32 v145, v151, v150
	v_cvt_pk_bf16_f32 v133, v133, v145
	global_store_dwordx4 v[148:149], v[130:133], off offset:256 sc1

; __device__ __forceinline__ unsigned cvt_pk_bf16(float lo, float hi) { unsigned r; asm volatile("v_cvt_pk_bf16_f32 %0, %1, %2" : "=v"(r) : "v"(lo), "v"(hi)); return r; }
;     template <int LDC> __device__ __forceinline__ void store_rope(const f32x4 (&acc)[2][2][4][2], bf16_t* base, int row0, int wc, int fq) const {
;         bf16_t* rp = base + (size_t)row0 * LDC; const int axis = wc >> 1, f0 = 16 * (wc & 1) + 4 * fq;
; #pragma unroll
;         for (int ai = 0; ai < 2; ++ai)
; #pragma unroll
;             for (int m = 0; m < 4; ++m) { const int row = row0 + ai * HALF + m * 16; bf16_t* rowp = rp + (size_t)(ai * HALF + m * 16) * LDC;
;                 const int t = row & (SEQ - 1), pos = axis ? (t & 63) : (t >> 6);
;                 f32x4 cs0 = *(const f32x4*)(TAB + (pos * 32 + f0) * 2), cs1 = *(const f32x4*)(TAB + (pos * 32 + f0) * 2 + 4);
;                 if (row >= ML) { cs0 = (f32x4){1.f, 0.f, 1.f, 0.f}; cs1 = cs0; }
; #pragma unroll
;                 for (int bj = 0; bj < 2; ++bj) { const f32x4 x1 = acc[ai][bj][m][0], x2 = acc[ai][bj][m][1];
;                     u32x4 w;
;                     w.x = cvt_pk_bf16(x1[0] * cs0[0] - x2[0] * cs0[1], x1[1] * cs0[2] - x2[1] * cs0[3]);
;                     w.y = cvt_pk_bf16(x1[2] * cs1[0] - x2[2] * cs1[1], x1[3] * cs1[2] - x2[3] * cs1[3]);
;                     w.z = cvt_pk_bf16(x2[0] * cs0[0] + x1[0] * cs0[1], x2[1] * cs0[2] + x1[1] * cs0[3]);
;                     w.w = cvt_pk_bf16(x2[2] * cs1[0] + x1[2] * cs1[1], x2[3] * cs1[2] + x1[3] * cs1[3]);
;                     *(u32x4*)(rowp + bj * HALF) = w; } }
;     }
;     __device__ __forceinline__ void operator()(const f32x4 (&acc)[2][2][4][2], const Unit& u, int wr, int wc, int fr, int fq) const {
;     ...
;         else if (pn < 12) { store_rope<1024>(acc, Q + (pn - 8) * 256 + col0, row0, wc, fq); }
.LBB0_598:
	s_and_b64 vcc, exec, s[18:19]
	s_cbranch_vccz .LBB0_600
	s_lshl_b32 s18, s63, 9
	s_add_u32 s18, s16, s18
	s_addc_u32 s19, s17, 0
	v_ashrrev_i32_e32 v147, 31, v146
	v_lshl_add_u64 v[130:131], v[146:147], 1, s[18:19]
	v_ashrrev_i32_e32 v145, 31, v144
	s_lshr_b32 s18, s45, 6
	v_lshlrev_b64 v[132:133], 11, v[144:145]
	v_mov_b32_e32 v147, s18
	v_lshl_add_u64 v[148:149], v[130:131], 0, v[132:133]
	v_cndmask_b32_e64 v130, v159, v147, s[40:41]
	v_lshlrev_b32_e32 v130, 5, v130
	v_lshl_add_u32 v145, v167, 2, s39
	v_and_b32_e32 v130, 0x7e0, v130
	v_add_lshl_u32 v130, v130, v145, 1
	v_ashrrev_i32_e32 v131, 31, v130
	v_lshl_add_u64 v[130:131], v[130:131], 2, s[20:21]
	global_load_dwordx4 v[176:179], v[130:131], off offset:16
	s_nop 0
	global_load_dwordx4 v[130:133], v[130:131], off
	s_movk_i32 s18, 0x3fff
	v_cmp_lt_i32_e32 vcc, s18, v144
	v_mov_b32_e32 v161, v108
	s_movk_i32 s18, 0x3fef
	s_addk_i32 s45, 0x80
	v_mov_b32_e32 v163, v56
	s_waitcnt vmcnt(0)
	v_cndmask_b32_e64 v153, v177, 0, vcc
	v_cndmask_b32_e64 v155, v131, 0, vcc
	v_cndmask_b32_e64 v154, v130, 1.0, vcc
	v_mov_b32_e32 v130, v126
	v_mov_b32_e32 v131, v122
	v_pk_mul_f32 v[130:131], v[130:131], v[154:155]
	v_cndmask_b32_e64 v133, v133, 0, vcc
	v_cndmask_b32_e64 v132, v132, 1.0, vcc
	v_sub_f32_e32 v160, v130, v131
	v_mov_b32_e32 v130, v127
	v_mov_b32_e32 v131, v123
	v_pk_mul_f32 v[130:131], v[130:131], v[132:133]
	v_cndmask_b32_e64 v152, v176, 1.0, vcc
	v_sub_f32_e32 v130, v130, v131
	v_cvt_pk_bf16_f32 v176, v160, v130
	v_mov_b32_e32 v130, v128
	v_mov_b32_e32 v131, v124
	v_pk_mul_f32 v[130:131], v[130:131], v[152:153]
	v_cndmask_b32_e64 v151, v179, 0, vcc
	v_cndmask_b32_e64 v150, v178, 1.0, vcc
	v_sub_f32_e32 v160, v130, v131
	v_mov_b32_e32 v130, v129
	v_mov_b32_e32 v131, v125
	v_pk_mul_f32 v[130:131], v[130:131], v[150:151]
	v_cmp_lt_i32_e32 vcc, s18, v144
	v_sub_f32_e32 v130, v130, v131
	v_cvt_pk_bf16_f32 v177, v160, v130
	v_mov_b32_e32 v130, v122
	v_mov_b32_e32 v131, v126
	v_pk_mul_f32 v[130:131], v[130:131], v[154:155]
	s_movk_i32 s18, 0x7000
	v_add_f32_e32 v160, v131, v130
	v_mov_b32_e32 v130, v123
	v_mov_b32_e32 v131, v127
	v_pk_mul_f32 v[130:131], v[130:131], v[132:133]
	s_nop 0
	v_add_f32_e32 v130, v131, v130
	v_cvt_pk_bf16_f32 v178, v160, v130
	v_mov_b32_e32 v130, v124
	v_mov_b32_e32 v131, v128
	v_pk_mul_f32 v[130:131], v[130:131], v[152:153]
	s_nop 0
	v_add_f32_e32 v160, v131, v130
	v_mov_b32_e32 v130, v125
	v_mov_b32_e32 v131, v129
	v_pk_mul_f32 v[130:131], v[130:131], v[150:151]
	s_nop 0
	v_add_f32_e32 v130, v131, v130
	v_cvt_pk_bf16_f32 v179, v160, v130
	v_mov_b32_e32 v130, v114
	v_mov_b32_e32 v131, v106
	v_pk_mul_f32 v[130:131], v[130:131], v[154:155]
	global_store_dwordx4 v[148:149], v[176:179], off offset:-4096 sc1
	v_sub_f32_e32 v160, v130, v131
	v_mov_b32_e32 v130, v115
	v_mov_b32_e32 v131, v107
	v_pk_mul_f32 v[130:131], v[130:131], v[132:133]
	s_nop 0
	v_sub_f32_e32 v130, v130, v131
	v_cvt_pk_bf16_f32 v130, v160, v130
	v_mov_b32_e32 v160, v116
	v_pk_mul_f32 v[160:161], v[160:161], v[152:153]
	s_nop 0
	v_sub_f32_e32 v131, v160, v161
	v_mov_b32_e32 v160, v117
	v_mov_b32_e32 v161, v109
	v_pk_mul_f32 v[160:161], v[160:161], v[150:151]
	s_nop 0
	v_sub_f32_e32 v160, v160, v161
	v_cvt_pk_bf16_f32 v131, v131, v160
	v_mov_b32_e32 v160, v106
	v_mov_b32_e32 v161, v114
	v_pk_mul_f32 v[154:155], v[160:161], v[154:155]
	v_mov_b32_e32 v161, v90
	v_add_f32_e32 v160, v155, v154
	v_mov_b32_e32 v154, v107
	v_mov_b32_e32 v155, v115
	v_pk_mul_f32 v[132:133], v[154:155], v[132:133]
	v_mov_b32_e32 v154, v108
	v_mov_b32_e32 v155, v116
	v_pk_mul_f32 v[152:153], v[154:155], v[152:153]
	v_add_f32_e32 v132, v133, v132
	v_add_f32_e32 v133, v153, v152
	v_mov_b32_e32 v152, v109
	v_mov_b32_e32 v153, v117
	v_pk_mul_f32 v[150:151], v[152:153], v[150:151]
	v_cvt_pk_bf16_f32 v132, v160, v132
	v_mov_b32_e32 v154, v118
	v_add_f32_e32 v150, v151, v150
	v_cvt_pk_bf16_f32 v133, v133, v150
	global_store_dwordx4 v[148:149], v[130:133], off offset:-3840 sc1
	v_mov_b32_e32 v155, v110
	s_nop 0
	v_or_b32_e32 v130, 16, v144
	v_cndmask_b32_e64 v130, v130, v147, s[40:41]
	v_lshlrev_b32_e32 v130, 5, v130
	v_and_b32_e32 v130, 0x7e0, v130
	v_add_lshl_u32 v130, v130, v145, 1
	v_ashrrev_i32_e32 v131, 31, v130
	v_lshl_add_u64 v[130:131], v[130:131], 2, s[20:21]
	global_load_dwordx4 v[176:179], v[130:131], off offset:16
	s_nop 0
	global_load_dwordx4 v[130:133], v[130:131], off
	s_waitcnt vmcnt(1)
	v_cndmask_b32_e64 v151, v177, 0, vcc
	s_waitcnt vmcnt(0)
; __device__ __forceinline__ unsigned cvt_pk_bf16(float lo, float hi) { unsigned r; asm volatile("v_cvt_pk_bf16_f32 %0, %1, %2" : "=v"(r) : "v"(lo), "v"(hi)); return r; }
;     template <int LDC> __device__ __forceinline__ void store_rope(const f32x4 (&acc)[2][2][4][2], bf16_t* base, int row0, int wc, int fq) const {
;         bf16_t* rp = base + (size_t)row0 * LDC; const int axis = wc >> 1, f0 = 16 * (wc & 1) + 4 * fq;
; #pragma unroll
;         for (int ai = 0; ai < 2; ++ai)
; #pragma unroll
;             for (int m = 0; m < 4; ++m) { const int row = row0 + ai * HALF + m * 16; bf16_t* rowp = rp + (size_t)(ai * HALF + m * 16) * LDC;
;                 const int t = row & (SEQ - 1), pos = axis ? (t & 63) : (t >> 6);
;                 f32x4 cs0 = *(const f32x4*)(TAB + (pos * 32 + f0) * 2), cs1 = *(const f32x4*)(TAB + (pos * 32 + f0) * 2 + 4);
;                 if (row >= ML) { cs0 = (f32x4){1.f, 0.f, 1.f, 0.f}; cs1 = cs0; }
; #pragma unroll
;                 for (int bj = 0; bj < 2; ++bj) { const f32x4 x1 = acc[ai][bj][m][0], x2 = acc[ai][bj][m][1];
;                     u32x4 w;
;                     w.x = cvt_pk_bf16(x1[0] * cs0[0] - x2[0] * cs0[1], x1[1] * cs0[2] - x2[1] * cs0[3]);
;                     w.y = cvt_pk_bf16(x1[2] * cs1[0] - x2[2] * cs1[1], x1[3] * cs1[2] - x2[3] * cs1[3]);
;                     w.z = cvt_pk_bf16(x2[0] * cs0[0] + x1[0] * cs0[1], x2[1] * cs0[2] + x1[1] * cs0[3]);
;                     w.w = cvt_pk_bf16(x2[2] * cs1[0] + x1[2] * cs1[1], x2[3] * cs1[2] + x1[3] * cs1[3]);
;                     *(u32x4*)(rowp + bj * HALF) = w; } }
;     }
	v_cndmask_b32_e64 v153, v131, 0, vcc
	v_cndmask_b32_e64 v152, v130, 1.0, vcc
	v_pk_mul_f32 v[154:155], v[154:155], v[152:153]
	v_cndmask_b32_e64 v133, v133, 0, vcc
	v_cndmask_b32_e64 v132, v132, 1.0, vcc
	v_sub_f32_e32 v160, v154, v155
	v_mov_b32_e32 v154, v119
	v_mov_b32_e32 v155, v111
	v_pk_mul_f32 v[154:155], v[154:155], v[132:133]
	v_cndmask_b32_e64 v150, v176, 1.0, vcc
	v_sub_f32_e32 v154, v154, v155
	v_cvt_pk_bf16_f32 v176, v160, v154
	v_mov_b32_e32 v154, v120
	v_mov_b32_e32 v155, v112
	v_pk_mul_f32 v[154:155], v[154:155], v[150:151]
	v_cndmask_b32_e64 v131, v179, 0, vcc
	v_cndmask_b32_e64 v130, v178, 1.0, vcc
	v_sub_f32_e32 v160, v154, v155
	v_mov_b32_e32 v154, v121
	v_mov_b32_e32 v155, v113
	v_pk_mul_f32 v[154:155], v[154:155], v[130:131]
	s_nop 0
	v_sub_f32_e32 v154, v154, v155
	v_cvt_pk_bf16_f32 v177, v160, v154
	v_mov_b32_e32 v154, v110
	v_mov_b32_e32 v155, v118
	v_pk_mul_f32 v[154:155], v[154:155], v[152:153]
	s_nop 0
	v_add_f32_e32 v160, v155, v154
	v_mov_b32_e32 v154, v111
	v_mov_b32_e32 v155, v119
	v_pk_mul_f32 v[154:155], v[154:155], v[132:133]
	s_nop 0
	v_add_f32_e32 v154, v155, v154
	v_cvt_pk_bf16_f32 v178, v160, v154
	v_mov_b32_e32 v154, v112
	v_mov_b32_e32 v155, v120
	v_pk_mul_f32 v[154:155], v[154:155], v[150:151]
	s_nop 0
	v_add_f32_e32 v160, v155, v154
	v_mov_b32_e32 v154, v113
	v_mov_b32_e32 v155, v121
	v_pk_mul_f32 v[154:155], v[154:155], v[130:131]
	s_nop 0
	v_add_f32_e32 v154, v155, v154
	v_cvt_pk_bf16_f32 v179, v160, v154
	v_mov_b32_e32 v160, v98
	v_pk_mul_f32 v[160:161], v[160:161], v[152:153]
	v_add_co_u32_e32 v154, vcc, s18, v148
	v_sub_f32_e32 v162, v160, v161
	v_mov_b32_e32 v160, v99
	v_mov_b32_e32 v161, v91
	v_pk_mul_f32 v[160:161], v[160:161], v[132:133]
	v_addc_co_u32_e32 v155, vcc, 0, v149, vcc
	v_sub_f32_e32 v160, v160, v161
	global_store_dwordx4 v[154:155], v[176:179], off sc1
	v_mov_b32_e32 v161, v92
	s_movk_i32 s18, 0x3fdf
	v_cvt_pk_bf16_f32 v176, v162, v160
	v_mov_b32_e32 v160, v100
	v_pk_mul_f32 v[160:161], v[160:161], v[150:151]
	v_cmp_lt_i32_e32 vcc, s18, v144
	v_sub_f32_e32 v162, v160, v161
	v_mov_b32_e32 v160, v101
	v_mov_b32_e32 v161, v93
	v_pk_mul_f32 v[160:161], v[160:161], v[130:131]
	s_mov_b32 s18, 0xf000
	v_sub_f32_e32 v160, v160, v161
	v_cvt_pk_bf16_f32 v177, v162, v160
	v_mov_b32_e32 v160, v90
	v_mov_b32_e32 v161, v98
	v_pk_mul_f32 v[152:153], v[160:161], v[152:153]
	v_mov_b32_e32 v161, v74
	v_add_f32_e32 v160, v153, v152
	v_mov_b32_e32 v152, v91
	v_mov_b32_e32 v153, v99
	v_pk_mul_f32 v[132:133], v[152:153], v[132:133]
	s_nop 0
	v_add_f32_e32 v132, v133, v132
	v_cvt_pk_bf16_f32 v178, v160, v132
	v_mov_b32_e32 v132, v92
	v_mov_b32_e32 v133, v100
	v_pk_mul_f32 v[132:133], v[132:133], v[150:151]
	s_nop 0
	v_add_f32_e32 v150, v133, v132
	v_mov_b32_e32 v132, v93
	v_mov_b32_e32 v133, v101
	v_pk_mul_f32 v[130:131], v[132:133], v[130:131]
	s_nop 0
	v_add_f32_e32 v130, v131, v130
	v_cvt_pk_bf16_f32 v179, v150, v130
	v_or_b32_e32 v130, 32, v144
	v_cndmask_b32_e64 v130, v130, v147, s[40:41]
	v_lshlrev_b32_e32 v130, 5, v130
	v_and_b32_e32 v130, 0x7e0, v130
	v_add_lshl_u32 v130, v130, v145, 1
	v_ashrrev_i32_e32 v131, 31, v130
	global_store_dwordx4 v[154:155], v[176:179], off offset:256 sc1
	v_lshl_add_u64 v[130:131], v[130:131], 2, s[20:21]
	global_load_dwordx4 v[176:179], v[130:131], off offset:16
	s_nop 0
	global_load_dwordx4 v[130:133], v[130:131], off
	v_mov_b32_e32 v154, v102
	v_mov_b32_e32 v155, v94
	s_waitcnt vmcnt(1)
	v_cndmask_b32_e64 v151, v177, 0, vcc
	s_waitcnt vmcnt(0)
	v_cndmask_b32_e64 v153, v131, 0, vcc
	v_cndmask_b32_e64 v152, v130, 1.0, vcc
	v_pk_mul_f32 v[154:155], v[154:155], v[152:153]
	v_cndmask_b32_e64 v133, v133, 0, vcc
	v_cndmask_b32_e64 v132, v132, 1.0, vcc
	v_sub_f32_e32 v160, v154, v155
	v_mov_b32_e32 v154, v103
	v_mov_b32_e32 v155, v95
	v_pk_mul_f32 v[154:155], v[154:155], v[132:133]
	v_cndmask_b32_e64 v150, v176, 1.0, vcc
	v_sub_f32_e32 v154, v154, v155
	v_cvt_pk_bf16_f32 v176, v160, v154
	v_mov_b32_e32 v154, v104
	v_mov_b32_e32 v155, v96
	v_pk_mul_f32 v[154:155], v[154:155], v[150:151]
	v_cndmask_b32_e64 v131, v179, 0, vcc
	v_cndmask_b32_e64 v130, v178, 1.0, vcc
	v_sub_f32_e32 v160, v154, v155
	v_mov_b32_e32 v154, v105
	v_mov_b32_e32 v155, v97
	v_pk_mul_f32 v[154:155], v[154:155], v[130:131]
	s_nop 0
	v_sub_f32_e32 v154, v154, v155
	v_cvt_pk_bf16_f32 v177, v160, v154
	v_mov_b32_e32 v154, v94
	v_mov_b32_e32 v155, v102
	v_pk_mul_f32 v[154:155], v[154:155], v[152:153]
	s_nop 0
	v_add_f32_e32 v160, v155, v154
	v_mov_b32_e32 v154, v95
	v_mov_b32_e32 v155, v103
	v_pk_mul_f32 v[154:155], v[154:155], v[132:133]
	s_nop 0
	v_add_f32_e32 v154, v155, v154
	v_cvt_pk_bf16_f32 v178, v160, v154
	v_mov_b32_e32 v154, v96
	v_mov_b32_e32 v155, v104
	v_pk_mul_f32 v[154:155], v[154:155], v[150:151]
	s_nop 0
	v_add_f32_e32 v160, v155, v154
	v_mov_b32_e32 v154, v97
	v_mov_b32_e32 v155, v105
	v_pk_mul_f32 v[154:155], v[154:155], v[130:131]
	s_nop 0
	v_add_f32_e32 v154, v155, v154
	v_cvt_pk_bf16_f32 v179, v160, v154
	v_mov_b32_e32 v160, v82
	v_pk_mul_f32 v[160:161], v[160:161], v[152:153]
	v_add_co_u32_e32 v154, vcc, s18, v148
	v_sub_f32_e32 v162, v160, v161
	v_mov_b32_e32 v160, v83
	v_mov_b32_e32 v161, v75
	v_pk_mul_f32 v[160:161], v[160:161], v[132:133]
	v_addc_co_u32_e32 v155, vcc, 0, v149, vcc
	v_sub_f32_e32 v160, v160, v161
	global_store_dwordx4 v[154:155], v[176:179], off sc1
	v_mov_b32_e32 v161, v76
	s_movk_i32 s18, 0x3fcf
	v_cvt_pk_bf16_f32 v176, v162, v160
	v_mov_b32_e32 v160, v84
	v_pk_mul_f32 v[160:161], v[160:161], v[150:151]
	v_cmp_lt_i32_e32 vcc, s18, v144
	v_sub_f32_e32 v162, v160, v161
	v_mov_b32_e32 v160, v85
	v_mov_b32_e32 v161, v77
	v_pk_mul_f32 v[160:161], v[160:161], v[130:131]
	s_mov_b32 s18, 0x17000
	v_sub_f32_e32 v160, v160, v161
	v_cvt_pk_bf16_f32 v177, v162, v160
	v_mov_b32_e32 v160, v74
	v_mov_b32_e32 v161, v82
	v_pk_mul_f32 v[152:153], v[160:161], v[152:153]
	v_mov_b32_e32 v161, v66
	v_add_f32_e32 v160, v153, v152
	v_mov_b32_e32 v152, v75
	v_mov_b32_e32 v153, v83
	v_pk_mul_f32 v[132:133], v[152:153], v[132:133]
	v_mov_b32_e32 v162, v48
	v_add_f32_e32 v132, v133, v132
	v_cvt_pk_bf16_f32 v178, v160, v132
	v_mov_b32_e32 v132, v76
	v_mov_b32_e32 v133, v84
	v_pk_mul_f32 v[132:133], v[132:133], v[150:151]
	v_mov_b32_e32 v160, v70
	v_add_f32_e32 v150, v133, v132
	v_mov_b32_e32 v132, v77
	v_mov_b32_e32 v133, v85
	v_pk_mul_f32 v[130:131], v[132:133], v[130:131]
	s_nop 0
	v_add_f32_e32 v130, v131, v130
	v_cvt_pk_bf16_f32 v179, v150, v130
	v_or_b32_e32 v130, 48, v144
	v_cndmask_b32_e64 v130, v130, v147, s[40:41]
	v_lshlrev_b32_e32 v130, 5, v130
	v_and_b32_e32 v130, 0x7e0, v130
	v_add_lshl_u32 v130, v130, v145, 1
	v_ashrrev_i32_e32 v131, 31, v130
	global_store_dwordx4 v[154:155], v[176:179], off offset:256 sc1
	v_lshl_add_u64 v[130:131], v[130:131], 2, s[20:21]
	global_load_dwordx4 v[176:179], v[130:131], off offset:16
	s_nop 0
	global_load_dwordx4 v[130:133], v[130:131], off
	v_mov_b32_e32 v154, v86
	v_mov_b32_e32 v155, v78
	s_waitcnt vmcnt(1)
; __device__ __forceinline__ unsigned cvt_pk_bf16(float lo, float hi) { unsigned r; asm volatile("v_cvt_pk_bf16_f32 %0, %1, %2" : "=v"(r) : "v"(lo), "v"(hi)); return r; }
;     template <int LDC> __device__ __forceinline__ void store_rope(const f32x4 (&acc)[2][2][4][2], bf16_t* base, int row0, int wc, int fq) const {
;         bf16_t* rp = base + (size_t)row0 * LDC; const int axis = wc >> 1, f0 = 16 * (wc & 1) + 4 * fq;
; #pragma unroll
;         for (int ai = 0; ai < 2; ++ai)
; #pragma unroll
;             for (int m = 0; m < 4; ++m) { const int row = row0 + ai * HALF + m * 16; bf16_t* rowp = rp + (size_t)(ai * HALF + m * 16) * LDC;
;                 const int t = row & (SEQ - 1), pos = axis ? (t & 63) : (t >> 6);
;                 f32x4 cs0 = *(const f32x4*)(TAB + (pos * 32 + f0) * 2), cs1 = *(const f32x4*)(TAB + (pos * 32 + f0) * 2 + 4);
;                 if (row >= ML) { cs0 = (f32x4){1.f, 0.f, 1.f, 0.f}; cs1 = cs0; }
; #pragma unroll
;                 for (int bj = 0; bj < 2; ++bj) { const f32x4 x1 = acc[ai][bj][m][0], x2 = acc[ai][bj][m][1];
;                     u32x4 w;
;                     w.x = cvt_pk_bf16(x1[0] * cs0[0] - x2[0] * cs0[1], x1[1] * cs0[2] - x2[1] * cs0[3]);
;                     w.y = cvt_pk_bf16(x1[2] * cs1[0] - x2[2] * cs1[1], x1[3] * cs1[2] - x2[3] * cs1[3]);
;                     w.z = cvt_pk_bf16(x2[0] * cs0[0] + x1[0] * cs0[1], x2[1] * cs0[2] + x1[1] * cs0[3]);
;                     w.w = cvt_pk_bf16(x2[2] * cs1[0] + x1[2] * cs1[1], x2[3] * cs1[2] + x1[3] * cs1[3]);
;                     *(u32x4*)(rowp + bj * HALF) = w; } }
;     }
	v_cndmask_b32_e64 v151, v177, 0, vcc
	s_waitcnt vmcnt(0)
	v_cndmask_b32_e64 v153, v131, 0, vcc
	v_cndmask_b32_e64 v152, v130, 1.0, vcc
	v_pk_mul_f32 v[154:155], v[154:155], v[152:153]
	v_cndmask_b32_e64 v133, v133, 0, vcc
	v_cndmask_b32_e64 v132, v132, 1.0, vcc
	v_sub_f32_e32 v147, v154, v155
	v_mov_b32_e32 v154, v87
	v_mov_b32_e32 v155, v79
	v_pk_mul_f32 v[154:155], v[154:155], v[132:133]
	v_cndmask_b32_e64 v150, v176, 1.0, vcc
	v_sub_f32_e32 v154, v154, v155
	v_cvt_pk_bf16_f32 v176, v147, v154
	v_mov_b32_e32 v154, v88
	v_mov_b32_e32 v155, v80
	v_pk_mul_f32 v[154:155], v[154:155], v[150:151]
	v_cndmask_b32_e64 v131, v179, 0, vcc
	v_cndmask_b32_e64 v130, v178, 1.0, vcc
	v_sub_f32_e32 v147, v154, v155
	v_mov_b32_e32 v154, v89
	v_mov_b32_e32 v155, v81
	v_pk_mul_f32 v[154:155], v[154:155], v[130:131]
	v_pk_mul_f32 v[160:161], v[160:161], v[152:153]
	v_sub_f32_e32 v154, v154, v155
	v_cvt_pk_bf16_f32 v177, v147, v154
	v_mov_b32_e32 v154, v78
	v_mov_b32_e32 v155, v86
	v_pk_mul_f32 v[154:155], v[154:155], v[152:153]
	s_nop 0
	v_add_f32_e32 v147, v155, v154
	v_mov_b32_e32 v154, v79
	v_mov_b32_e32 v155, v87
	v_pk_mul_f32 v[154:155], v[154:155], v[132:133]
	s_nop 0
	v_add_f32_e32 v154, v155, v154
	v_cvt_pk_bf16_f32 v178, v147, v154
	v_mov_b32_e32 v154, v80
	v_mov_b32_e32 v155, v88
	v_pk_mul_f32 v[154:155], v[154:155], v[150:151]
	s_nop 0
	v_add_f32_e32 v147, v155, v154
	v_mov_b32_e32 v154, v81
	v_mov_b32_e32 v155, v89
	v_pk_mul_f32 v[154:155], v[154:155], v[130:131]
	s_nop 0
	v_add_f32_e32 v154, v155, v154
	v_cvt_pk_bf16_f32 v179, v147, v154
	v_sub_f32_e32 v147, v160, v161
	v_mov_b32_e32 v160, v71
	v_mov_b32_e32 v161, v67
	v_add_co_u32_e32 v154, vcc, s18, v148
	v_pk_mul_f32 v[160:161], v[160:161], v[132:133]
	s_nop 0
	v_addc_co_u32_e32 v155, vcc, 0, v149, vcc
	v_sub_f32_e32 v160, v160, v161
	global_store_dwordx4 v[154:155], v[176:179], off sc1
	v_mov_b32_e32 v161, v68
	s_lshr_b32 s18, s45, 6
	v_cvt_pk_bf16_f32 v176, v147, v160
	v_mov_b32_e32 v160, v72
	v_pk_mul_f32 v[160:161], v[160:161], v[150:151]
	s_nop 0
	v_sub_f32_e32 v147, v160, v161
	v_mov_b32_e32 v160, v73
	v_mov_b32_e32 v161, v69
	v_pk_mul_f32 v[160:161], v[160:161], v[130:131]
	s_nop 0
	v_sub_f32_e32 v160, v160, v161
	v_cvt_pk_bf16_f32 v177, v147, v160
	v_mov_b32_e32 v160, v66
	v_mov_b32_e32 v161, v70
	v_pk_mul_f32 v[152:153], v[160:161], v[152:153]
	v_mov_b32_e32 v160, v50
	v_add_f32_e32 v147, v153, v152
	v_mov_b32_e32 v152, v67
	v_mov_b32_e32 v153, v71
	v_pk_mul_f32 v[132:133], v[152:153], v[132:133]
	v_mov_b32_e32 v161, v42
	v_add_f32_e32 v132, v133, v132
	v_cvt_pk_bf16_f32 v178, v147, v132
	v_mov_b32_e32 v132, v68
	v_mov_b32_e32 v133, v72
	v_pk_mul_f32 v[132:133], v[132:133], v[150:151]
	s_nop 0
	v_add_f32_e32 v147, v133, v132
	v_mov_b32_e32 v132, v69
	v_mov_b32_e32 v133, v73
	v_pk_mul_f32 v[130:131], v[132:133], v[130:131]
	s_nop 0
	v_add_f32_e32 v130, v131, v130
	v_cvt_pk_bf16_f32 v179, v147, v130
	v_mov_b32_e32 v130, s18
	v_cndmask_b32_e64 v130, v159, v130, s[40:41]
	v_lshlrev_b32_e32 v130, 5, v130
	v_and_b32_e32 v130, 0x7e0, v130
	v_add_lshl_u32 v130, v130, v145, 1
	v_ashrrev_i32_e32 v131, 31, v130
	global_store_dwordx4 v[154:155], v[176:179], off offset:256 sc1
	v_lshl_add_u64 v[130:131], v[130:131], 2, s[20:21]
	global_load_dwordx4 v[176:179], v[130:131], off offset:16
	s_nop 0
	global_load_dwordx4 v[130:133], v[130:131], off
	s_movk_i32 s18, 0x3f7f
	v_cmp_lt_i32_e32 vcc, s18, v144
	v_mov_b32_e32 v154, v62
	v_mov_b32_e32 v155, v58
	s_mov_b32 s18, 0x3f000
	s_waitcnt vmcnt(1)
	v_cndmask_b32_e64 v151, v177, 0, vcc
	s_waitcnt vmcnt(0)
	v_cndmask_b32_e64 v153, v131, 0, vcc
	v_cndmask_b32_e64 v152, v130, 1.0, vcc
	v_pk_mul_f32 v[154:155], v[154:155], v[152:153]
	v_cndmask_b32_e64 v133, v133, 0, vcc
	v_cndmask_b32_e64 v132, v132, 1.0, vcc
	v_sub_f32_e32 v147, v154, v155
	v_mov_b32_e32 v154, v63
	v_mov_b32_e32 v155, v59
	v_pk_mul_f32 v[154:155], v[154:155], v[132:133]
	v_cndmask_b32_e64 v150, v176, 1.0, vcc
	v_sub_f32_e32 v154, v154, v155
	v_cvt_pk_bf16_f32 v176, v147, v154
	v_mov_b32_e32 v154, v64
	v_mov_b32_e32 v155, v60
	v_pk_mul_f32 v[154:155], v[154:155], v[150:151]
	v_cndmask_b32_e64 v131, v179, 0, vcc
	v_cndmask_b32_e64 v130, v178, 1.0, vcc
	v_sub_f32_e32 v147, v154, v155
	v_mov_b32_e32 v154, v65
	v_mov_b32_e32 v155, v61
	v_pk_mul_f32 v[154:155], v[154:155], v[130:131]
	v_pk_mul_f32 v[160:161], v[160:161], v[152:153]
	v_sub_f32_e32 v154, v154, v155
	v_cvt_pk_bf16_f32 v177, v147, v154
	v_mov_b32_e32 v154, v58
	v_mov_b32_e32 v155, v62
	v_pk_mul_f32 v[154:155], v[154:155], v[152:153]
	s_nop 0
	v_add_f32_e32 v147, v155, v154
	v_mov_b32_e32 v154, v59
	v_mov_b32_e32 v155, v63
	v_pk_mul_f32 v[154:155], v[154:155], v[132:133]
	s_nop 0
	v_add_f32_e32 v154, v155, v154
	v_cvt_pk_bf16_f32 v178, v147, v154
	v_mov_b32_e32 v154, v60
	v_mov_b32_e32 v155, v64
	v_pk_mul_f32 v[154:155], v[154:155], v[150:151]
	s_nop 0
	v_add_f32_e32 v147, v155, v154
	v_mov_b32_e32 v154, v61
	v_mov_b32_e32 v155, v65
	v_pk_mul_f32 v[154:155], v[154:155], v[130:131]
	s_nop 0
	v_add_f32_e32 v154, v155, v154
	v_cvt_pk_bf16_f32 v179, v147, v154
	v_sub_f32_e32 v147, v160, v161
	v_mov_b32_e32 v160, v51
	v_mov_b32_e32 v161, v43
	v_pk_mul_f32 v[160:161], v[160:161], v[132:133]
	v_add_co_u32_e32 v154, vcc, s18, v148
	v_sub_f32_e32 v159, v160, v161
	v_mov_b32_e32 v160, v52
	v_mov_b32_e32 v161, v44
	v_addc_co_u32_e32 v155, vcc, 0, v149, vcc
	v_pk_mul_f32 v[160:161], v[160:161], v[150:151]
	global_store_dwordx4 v[154:155], v[176:179], off sc1
	s_movk_i32 s18, 0x3f6f
	v_cmp_lt_i32_e32 vcc, s18, v144
	v_cvt_pk_bf16_f32 v176, v147, v159
	v_sub_f32_e32 v147, v160, v161
	v_mov_b32_e32 v160, v53
	v_mov_b32_e32 v161, v45
	v_pk_mul_f32 v[160:161], v[160:161], v[130:131]
	s_mov_b32 s18, 0x47000
	v_sub_f32_e32 v159, v160, v161
	v_mov_b32_e32 v160, v42
	v_mov_b32_e32 v161, v50
	v_pk_mul_f32 v[152:153], v[160:161], v[152:153]
	v_cvt_pk_bf16_f32 v177, v147, v159
	s_nop 0
	v_add_f32_e32 v147, v153, v152
	v_mov_b32_e32 v152, v43
	v_mov_b32_e32 v153, v51
	v_pk_mul_f32 v[132:133], v[152:153], v[132:133]
	s_nop 0
	v_add_f32_e32 v132, v133, v132
	v_cvt_pk_bf16_f32 v178, v147, v132
	v_mov_b32_e32 v132, v44
	v_mov_b32_e32 v133, v52
	v_pk_mul_f32 v[132:133], v[132:133], v[150:151]
	s_nop 0
	v_add_f32_e32 v147, v133, v132
	v_mov_b32_e32 v132, v45
	v_mov_b32_e32 v133, v53
	v_pk_mul_f32 v[130:131], v[132:133], v[130:131]
	s_nop 0
	v_add_f32_e32 v130, v131, v130
	v_cvt_pk_bf16_f32 v179, v147, v130
	v_add_u32_e32 v130, 0x90, v144
	v_lshrrev_b32_e32 v131, 6, v130
	v_cndmask_b32_e64 v130, v130, v131, s[40:41]
	v_lshlrev_b32_e32 v130, 5, v130
	v_and_b32_e32 v130, 0x7e0, v130
	v_add_lshl_u32 v130, v130, v145, 1
	v_ashrrev_i32_e32 v131, 31, v130
	global_store_dwordx4 v[154:155], v[176:179], off offset:256 sc1
	v_lshl_add_u64 v[150:151], v[130:131], 2, s[20:21]
	global_load_dwordx4 v[130:133], v[150:151], off offset:16
	s_nop 0
	global_load_dwordx4 v[150:153], v[150:151], off
	s_waitcnt vmcnt(1)
; __device__ __forceinline__ unsigned cvt_pk_bf16(float lo, float hi) { unsigned r; asm volatile("v_cvt_pk_bf16_f32 %0, %1, %2" : "=v"(r) : "v"(lo), "v"(hi)); return r; }
;     template <int LDC> __device__ __forceinline__ void store_rope(const f32x4 (&acc)[2][2][4][2], bf16_t* base, int row0, int wc, int fq) const {
;         bf16_t* rp = base + (size_t)row0 * LDC; const int axis = wc >> 1, f0 = 16 * (wc & 1) + 4 * fq;
; #pragma unroll
;         for (int ai = 0; ai < 2; ++ai)
; #pragma unroll
;             for (int m = 0; m < 4; ++m) { const int row = row0 + ai * HALF + m * 16; bf16_t* rowp = rp + (size_t)(ai * HALF + m * 16) * LDC;
;                 const int t = row & (SEQ - 1), pos = axis ? (t & 63) : (t >> 6);
;                 f32x4 cs0 = *(const f32x4*)(TAB + (pos * 32 + f0) * 2), cs1 = *(const f32x4*)(TAB + (pos * 32 + f0) * 2 + 4);
;                 if (row >= ML) { cs0 = (f32x4){1.f, 0.f, 1.f, 0.f}; cs1 = cs0; }
; #pragma unroll
;                 for (int bj = 0; bj < 2; ++bj) { const f32x4 x1 = acc[ai][bj][m][0], x2 = acc[ai][bj][m][1];
;                     u32x4 w;
;                     w.x = cvt_pk_bf16(x1[0] * cs0[0] - x2[0] * cs0[1], x1[1] * cs0[2] - x2[1] * cs0[3]);
;                     w.y = cvt_pk_bf16(x1[2] * cs1[0] - x2[2] * cs1[1], x1[3] * cs1[2] - x2[3] * cs1[3]);
;                     w.z = cvt_pk_bf16(x2[0] * cs0[0] + x1[0] * cs0[1], x2[1] * cs0[2] + x1[1] * cs0[3]);
;                     w.w = cvt_pk_bf16(x2[2] * cs1[0] + x1[2] * cs1[1], x2[3] * cs1[2] + x1[3] * cs1[3]);
;                     *(u32x4*)(rowp + bj * HALF) = w; } }
	v_cndmask_b32_e64 v161, v131, 0, vcc
	s_waitcnt vmcnt(0)
	v_cndmask_b32_e64 v151, v151, 0, vcc
	v_cndmask_b32_e64 v150, v150, 1.0, vcc
	v_cndmask_b32_e64 v160, v130, 1.0, vcc
	v_mov_b32_e32 v130, v54
	v_mov_b32_e32 v131, v46
	v_pk_mul_f32 v[130:131], v[130:131], v[150:151]
	v_cndmask_b32_e64 v153, v153, 0, vcc
	v_cndmask_b32_e64 v152, v152, 1.0, vcc
	v_cndmask_b32_e64 v154, v132, 1.0, vcc
	v_sub_f32_e32 v132, v130, v131
	v_mov_b32_e32 v130, v55
	v_mov_b32_e32 v131, v47
	v_pk_mul_f32 v[130:131], v[130:131], v[152:153]
	v_cndmask_b32_e64 v155, v133, 0, vcc
	v_sub_f32_e32 v130, v130, v131
	v_cvt_pk_bf16_f32 v130, v132, v130
	v_mov_b32_e32 v132, v56
	v_mov_b32_e32 v133, v48
	v_pk_mul_f32 v[132:133], v[132:133], v[160:161]
	v_pk_mul_f32 v[162:163], v[162:163], v[160:161]
	v_sub_f32_e32 v131, v132, v133
	v_mov_b32_e32 v132, v57
	v_mov_b32_e32 v133, v49
	v_pk_mul_f32 v[132:133], v[132:133], v[154:155]
	s_nop 0
	v_sub_f32_e32 v132, v132, v133
	v_cvt_pk_bf16_f32 v131, v131, v132
	v_mov_b32_e32 v132, v46
	v_mov_b32_e32 v133, v54
	v_pk_mul_f32 v[132:133], v[132:133], v[150:151]
	s_nop 0
	v_add_f32_e32 v147, v133, v132
	v_mov_b32_e32 v132, v47
	v_mov_b32_e32 v133, v55
	v_pk_mul_f32 v[132:133], v[132:133], v[152:153]
	s_nop 0
	v_add_f32_e32 v132, v133, v132
	v_add_f32_e32 v133, v163, v162
	v_mov_b32_e32 v162, v49
	v_mov_b32_e32 v163, v57
	v_pk_mul_f32 v[162:163], v[162:163], v[154:155]
	v_cvt_pk_bf16_f32 v132, v147, v132
	s_nop 0
	v_add_f32_e32 v147, v163, v162
	v_add_co_u32_e32 v162, vcc, s18, v148
	v_cvt_pk_bf16_f32 v133, v133, v147
	s_movk_i32 s18, 0x3f5f
	s_nop 0
	v_addc_co_u32_e32 v163, vcc, 0, v149, vcc
	global_store_dwordx4 v[162:163], v[130:133], off sc1
	v_cmp_lt_i32_e32 vcc, s18, v144
	s_mov_b32 s18, 0x4f000
	v_mov_b32_e32 v130, v34
	v_mov_b32_e32 v131, v24
	v_pk_mul_f32 v[130:131], v[130:131], v[150:151]
	v_mov_b32_e32 v133, v26
	v_sub_f32_e32 v132, v130, v131
	v_mov_b32_e32 v130, v35
	v_mov_b32_e32 v131, v25
	v_pk_mul_f32 v[130:131], v[130:131], v[152:153]
	s_nop 0
	v_sub_f32_e32 v130, v130, v131
	v_cvt_pk_bf16_f32 v130, v132, v130
	v_mov_b32_e32 v132, v36
	v_pk_mul_f32 v[132:133], v[132:133], v[160:161]
	s_nop 0
	v_sub_f32_e32 v131, v132, v133
	v_mov_b32_e32 v132, v37
	v_mov_b32_e32 v133, v27
	v_pk_mul_f32 v[132:133], v[132:133], v[154:155]
	s_nop 0
	v_sub_f32_e32 v132, v132, v133
	v_cvt_pk_bf16_f32 v131, v131, v132
	v_mov_b32_e32 v132, v24
	v_mov_b32_e32 v133, v34
	v_pk_mul_f32 v[132:133], v[132:133], v[150:151]
	v_mov_b32_e32 v150, v26
	v_add_f32_e32 v147, v133, v132
	v_mov_b32_e32 v132, v25
	v_mov_b32_e32 v133, v35
	v_mov_b32_e32 v151, v36
	v_pk_mul_f32 v[132:133], v[132:133], v[152:153]
	v_pk_mul_f32 v[150:151], v[150:151], v[160:161]
	v_add_f32_e32 v132, v133, v132
	v_add_f32_e32 v133, v151, v150
	v_mov_b32_e32 v150, v27
	v_mov_b32_e32 v151, v37
	v_pk_mul_f32 v[150:151], v[150:151], v[154:155]
	v_cvt_pk_bf16_f32 v132, v147, v132
	s_nop 0
	v_add_f32_e32 v147, v151, v150
	v_cvt_pk_bf16_f32 v133, v133, v147
	global_store_dwordx4 v[162:163], v[130:133], off offset:256 sc1
	v_mov_b32_e32 v162, v30
	v_mov_b32_e32 v163, v40
	v_add_u32_e32 v130, 0xa0, v144
	v_lshrrev_b32_e32 v131, 6, v130
	v_cndmask_b32_e64 v130, v130, v131, s[40:41]
	v_lshlrev_b32_e32 v130, 5, v130
	v_and_b32_e32 v130, 0x7e0, v130
	v_add_lshl_u32 v130, v130, v145, 1
	v_ashrrev_i32_e32 v131, 31, v130
	v_lshl_add_u64 v[150:151], v[130:131], 2, s[20:21]
	global_load_dwordx4 v[130:133], v[150:151], off offset:16
	s_nop 0
	global_load_dwordx4 v[150:153], v[150:151], off
	s_waitcnt vmcnt(1)
	v_cndmask_b32_e64 v161, v131, 0, vcc
	s_waitcnt vmcnt(0)
; __device__ __forceinline__ unsigned cvt_pk_bf16(float lo, float hi) { unsigned r; asm volatile("v_cvt_pk_bf16_f32 %0, %1, %2" : "=v"(r) : "v"(lo), "v"(hi)); return r; }
;     template <int LDC> __device__ __forceinline__ void store_rope(const f32x4 (&acc)[2][2][4][2], bf16_t* base, int row0, int wc, int fq) const {
;         bf16_t* rp = base + (size_t)row0 * LDC; const int axis = wc >> 1, f0 = 16 * (wc & 1) + 4 * fq;
; #pragma unroll
;         for (int ai = 0; ai < 2; ++ai)
; #pragma unroll
;             for (int m = 0; m < 4; ++m) { const int row = row0 + ai * HALF + m * 16; bf16_t* rowp = rp + (size_t)(ai * HALF + m * 16) * LDC;
;                 const int t = row & (SEQ - 1), pos = axis ? (t & 63) : (t >> 6);
;                 f32x4 cs0 = *(const f32x4*)(TAB + (pos * 32 + f0) * 2), cs1 = *(const f32x4*)(TAB + (pos * 32 + f0) * 2 + 4);
;                 if (row >= ML) { cs0 = (f32x4){1.f, 0.f, 1.f, 0.f}; cs1 = cs0; }
; #pragma unroll
;                 for (int bj = 0; bj < 2; ++bj) { const f32x4 x1 = acc[ai][bj][m][0], x2 = acc[ai][bj][m][1];
;                     u32x4 w;
;                     w.x = cvt_pk_bf16(x1[0] * cs0[0] - x2[0] * cs0[1], x1[1] * cs0[2] - x2[1] * cs0[3]);
;                     w.y = cvt_pk_bf16(x1[2] * cs1[0] - x2[2] * cs1[1], x1[3] * cs1[2] - x2[3] * cs1[3]);
;                     w.z = cvt_pk_bf16(x2[0] * cs0[0] + x1[0] * cs0[1], x2[1] * cs0[2] + x1[1] * cs0[3]);
;                     w.w = cvt_pk_bf16(x2[2] * cs1[0] + x1[2] * cs1[1], x2[3] * cs1[2] + x1[3] * cs1[3]);
;                     *(u32x4*)(rowp + bj * HALF) = w; } }
	v_cndmask_b32_e64 v151, v151, 0, vcc
	v_cndmask_b32_e64 v150, v150, 1.0, vcc
	v_cndmask_b32_e64 v160, v130, 1.0, vcc
	v_mov_b32_e32 v130, v38
	v_mov_b32_e32 v131, v28
	v_pk_mul_f32 v[130:131], v[130:131], v[150:151]
	v_cndmask_b32_e64 v153, v153, 0, vcc
	v_cndmask_b32_e64 v152, v152, 1.0, vcc
	v_cndmask_b32_e64 v154, v132, 1.0, vcc
	v_sub_f32_e32 v132, v130, v131
	v_mov_b32_e32 v130, v39
	v_mov_b32_e32 v131, v29
	v_pk_mul_f32 v[130:131], v[130:131], v[152:153]
	v_cndmask_b32_e64 v155, v133, 0, vcc
	v_sub_f32_e32 v130, v130, v131
	v_cvt_pk_bf16_f32 v130, v132, v130
	v_mov_b32_e32 v132, v40
	v_mov_b32_e32 v133, v30
	v_pk_mul_f32 v[132:133], v[132:133], v[160:161]
	v_pk_mul_f32 v[162:163], v[162:163], v[160:161]
	v_sub_f32_e32 v131, v132, v133
	v_mov_b32_e32 v132, v41
	v_mov_b32_e32 v133, v31
	v_pk_mul_f32 v[132:133], v[132:133], v[154:155]
	s_nop 0
	v_sub_f32_e32 v132, v132, v133
	v_cvt_pk_bf16_f32 v131, v131, v132
	v_mov_b32_e32 v132, v28
	v_mov_b32_e32 v133, v38
	v_pk_mul_f32 v[132:133], v[132:133], v[150:151]
	s_nop 0
	v_add_f32_e32 v147, v133, v132
	v_mov_b32_e32 v132, v29
	v_mov_b32_e32 v133, v39
	v_pk_mul_f32 v[132:133], v[132:133], v[152:153]
	s_nop 0
	v_add_f32_e32 v132, v133, v132
	v_add_f32_e32 v133, v163, v162
	v_mov_b32_e32 v162, v31
	v_mov_b32_e32 v163, v41
	v_pk_mul_f32 v[162:163], v[162:163], v[154:155]
	v_cvt_pk_bf16_f32 v132, v147, v132
	s_nop 0
	v_add_f32_e32 v147, v163, v162
	v_add_co_u32_e32 v162, vcc, s18, v148
	v_cvt_pk_bf16_f32 v133, v133, v147
	s_movk_i32 s18, 0x3f4f
	s_nop 0
	v_addc_co_u32_e32 v163, vcc, 0, v149, vcc
	global_store_dwordx4 v[162:163], v[130:133], off sc1
	v_cmp_lt_i32_e32 vcc, s18, v144
	s_mov_b32 s18, 0x57000
	v_mov_b32_e32 v130, v16
	v_mov_b32_e32 v131, v8
	v_pk_mul_f32 v[130:131], v[130:131], v[150:151]
	v_mov_b32_e32 v133, v10
	v_sub_f32_e32 v132, v130, v131
	v_mov_b32_e32 v130, v17
	v_mov_b32_e32 v131, v9
	v_pk_mul_f32 v[130:131], v[130:131], v[152:153]
	s_nop 0
	v_sub_f32_e32 v130, v130, v131
	v_cvt_pk_bf16_f32 v130, v132, v130
	v_mov_b32_e32 v132, v18
	v_pk_mul_f32 v[132:133], v[132:133], v[160:161]
	s_nop 0
	v_sub_f32_e32 v131, v132, v133
	v_mov_b32_e32 v132, v19
	v_mov_b32_e32 v133, v11
	v_pk_mul_f32 v[132:133], v[132:133], v[154:155]
	s_nop 0
	v_sub_f32_e32 v132, v132, v133
	v_cvt_pk_bf16_f32 v131, v131, v132
	v_mov_b32_e32 v132, v8
	v_mov_b32_e32 v133, v16
	v_pk_mul_f32 v[132:133], v[132:133], v[150:151]
	v_mov_b32_e32 v150, v10
	v_add_f32_e32 v147, v133, v132
	v_mov_b32_e32 v132, v9
	v_mov_b32_e32 v133, v17
	v_mov_b32_e32 v151, v18
	v_pk_mul_f32 v[132:133], v[132:133], v[152:153]
	v_pk_mul_f32 v[150:151], v[150:151], v[160:161]
	v_add_f32_e32 v132, v133, v132
	v_add_f32_e32 v133, v151, v150
	v_mov_b32_e32 v150, v11
	v_mov_b32_e32 v151, v19
	v_pk_mul_f32 v[150:151], v[150:151], v[154:155]
	v_cvt_pk_bf16_f32 v132, v147, v132
	s_nop 0
	v_add_f32_e32 v147, v151, v150
	v_cvt_pk_bf16_f32 v133, v133, v147
	global_store_dwordx4 v[162:163], v[130:133], off offset:256 sc1
	v_mov_b32_e32 v162, v14
	v_mov_b32_e32 v163, v22
	v_add_u32_e32 v130, 0xb0, v144
	v_lshrrev_b32_e32 v131, 6, v130
	v_cndmask_b32_e64 v130, v130, v131, s[40:41]
	v_lshlrev_b32_e32 v130, 5, v130
	v_and_b32_e32 v130, 0x7e0, v130
	v_add_lshl_u32 v130, v130, v145, 1
	v_ashrrev_i32_e32 v131, 31, v130
	v_lshl_add_u64 v[150:151], v[130:131], 2, s[20:21]
	global_load_dwordx4 v[130:133], v[150:151], off offset:16
	s_nop 0
	global_load_dwordx4 v[150:153], v[150:151], off
	s_waitcnt vmcnt(1)
	v_cndmask_b32_e64 v161, v131, 0, vcc
	s_waitcnt vmcnt(0)
	v_cndmask_b32_e64 v151, v151, 0, vcc
	v_cndmask_b32_e64 v150, v150, 1.0, vcc
	v_cndmask_b32_e64 v160, v130, 1.0, vcc
	v_mov_b32_e32 v130, v20
	v_mov_b32_e32 v131, v12
	v_pk_mul_f32 v[130:131], v[130:131], v[150:151]
	v_cndmask_b32_e64 v153, v153, 0, vcc
	v_cndmask_b32_e64 v152, v152, 1.0, vcc
	v_cndmask_b32_e64 v154, v132, 1.0, vcc
	v_sub_f32_e32 v132, v130, v131
	v_mov_b32_e32 v130, v21
	v_mov_b32_e32 v131, v13
	v_pk_mul_f32 v[130:131], v[130:131], v[152:153]
	v_cndmask_b32_e64 v155, v133, 0, vcc
	v_sub_f32_e32 v130, v130, v131
	v_cvt_pk_bf16_f32 v130, v132, v130
	v_mov_b32_e32 v132, v22
	v_mov_b32_e32 v133, v14
	v_pk_mul_f32 v[132:133], v[132:133], v[160:161]
	v_pk_mul_f32 v[162:163], v[162:163], v[160:161]
	v_sub_f32_e32 v131, v132, v133
	v_mov_b32_e32 v132, v23
	v_mov_b32_e32 v133, v15
	v_pk_mul_f32 v[132:133], v[132:133], v[154:155]
	v_add_co_u32_e32 v148, vcc, s18, v148
	v_sub_f32_e32 v132, v132, v133
	v_cvt_pk_bf16_f32 v131, v131, v132
	v_mov_b32_e32 v132, v12
	v_mov_b32_e32 v133, v20
	v_pk_mul_f32 v[132:133], v[132:133], v[150:151]
	v_addc_co_u32_e32 v149, vcc, 0, v149, vcc
	v_add_f32_e32 v145, v133, v132
	v_mov_b32_e32 v132, v13
	v_mov_b32_e32 v133, v21
	v_pk_mul_f32 v[132:133], v[132:133], v[152:153]
	s_nop 0
	v_add_f32_e32 v132, v133, v132
	v_add_f32_e32 v133, v163, v162
	v_mov_b32_e32 v162, v15
	v_mov_b32_e32 v163, v23
	v_pk_mul_f32 v[162:163], v[162:163], v[154:155]
	v_cvt_pk_bf16_f32 v132, v145, v132
	s_nop 0
	v_add_f32_e32 v145, v163, v162
	v_cvt_pk_bf16_f32 v133, v133, v145
	global_store_dwordx4 v[148:149], v[130:133], off sc1
	s_nop 1
	v_mov_b32_e32 v130, v4
	v_mov_b32_e32 v131, v0
	v_pk_mul_f32 v[130:131], v[130:131], v[150:151]
	v_mov_b32_e32 v133, v2
	v_sub_f32_e32 v132, v130, v131
	v_mov_b32_e32 v130, v5
	v_mov_b32_e32 v131, v1
	v_pk_mul_f32 v[130:131], v[130:131], v[152:153]
	s_nop 0
	v_sub_f32_e32 v130, v130, v131
	v_cvt_pk_bf16_f32 v130, v132, v130
	v_mov_b32_e32 v132, v6
	v_pk_mul_f32 v[132:133], v[132:133], v[160:161]
	s_nop 0
	v_sub_f32_e32 v131, v132, v133
	v_mov_b32_e32 v132, v7
	v_mov_b32_e32 v133, v3
	v_pk_mul_f32 v[132:133], v[132:133], v[154:155]
	s_nop 0
	v_sub_f32_e32 v132, v132, v133
	v_cvt_pk_bf16_f32 v131, v131, v132
	v_mov_b32_e32 v132, v0
	v_mov_b32_e32 v133, v4
	v_pk_mul_f32 v[132:133], v[132:133], v[150:151]
	v_mov_b32_e32 v150, v2
	v_add_f32_e32 v145, v133, v132
	v_mov_b32_e32 v132, v1
	v_mov_b32_e32 v133, v5
	v_mov_b32_e32 v151, v6
	v_pk_mul_f32 v[132:133], v[132:133], v[152:153]
	v_pk_mul_f32 v[150:151], v[150:151], v[160:161]
	v_add_f32_e32 v132, v133, v132
	v_add_f32_e32 v133, v151, v150
	v_mov_b32_e32 v150, v3
	v_mov_b32_e32 v151, v7
	v_pk_mul_f32 v[150:151], v[150:151], v[154:155]
	v_cvt_pk_bf16_f32 v132, v145, v132
	s_nop 0
	v_add_f32_e32 v145, v151, v150
	v_cvt_pk_bf16_f32 v133, v133, v145
	global_store_dwordx4 v[148:149], v[130:133], off offset:256 sc1

; __device__ __forceinline__ unsigned cvt_pk_bf16(float lo, float hi) { unsigned r; asm volatile("v_cvt_pk_bf16_f32 %0, %1, %2" : "=v"(r) : "v"(lo), "v"(hi)); return r; }
;     template <int LDC> __device__ __forceinline__ void store(const f32x4 (&acc)[2][2][4][2], bf16_t* base, int row0) const {
;         bf16_t* rp = base + (size_t)row0 * LDC;
; #pragma unroll
;         for (int ai = 0; ai < 2; ++ai)
; #pragma unroll
;             for (int m = 0; m < 4; ++m) { bf16_t* rowp = rp + (size_t)(ai * HALF + m * 16) * LDC;
; #pragma unroll
;                 for (int bj = 0; bj < 2; ++bj) { const f32x4 v0 = acc[ai][bj][m][0], v1 = acc[ai][bj][m][1];
;                     u32x4 w; w.x = cvt_pk_bf16(v0[0], v0[1]); w.y = cvt_pk_bf16(v0[2], v0[3]); w.z = cvt_pk_bf16(v1[0], v1[1]); w.w = cvt_pk_bf16(v1[2], v1[3]);
;                     *(u32x4*)(rowp + bj * HALF) = w; } }
;     __device__ __forceinline__ void operator()(const f32x4 (&acc)[2][2][4][2], const Unit& u, int wr, int wc, int fr, int fq) const {
;         const int pn = u.pn; const int row0 = u.pm * BM + wr * 64 + fr, col0 = wc * 32 + 8 * fq;
;         if (pn < 8) { bf16_t* base = (pn < 4 ? XR + pn * 256 : GR + (pn - 4) * 256) + col0; store<1024>(acc, base, row0); }
.LBB0_603:
	s_lshl_b32 s18, s63, 8
	s_ashr_i32 s19, s18, 31
	s_lshl_b64 s[52:53], s[18:19], 1
	v_readlane_b32 s54, v255, 22
	v_readlane_b32 s55, v255, 23
	s_add_u32 s45, s54, s52
	s_mov_b32 s19, s9
	s_addc_u32 s47, s55, s53
	s_lshl_b64 s[18:19], s[18:19], 1
	v_readlane_b32 s52, v255, 24
	v_readlane_b32 s53, v255, 25
	s_add_u32 s18, s52, s18
	s_addc_u32 s19, s53, s19
	s_add_u32 s18, s18, 0xfffff800
	s_addc_u32 s19, s19, -1
	s_cmp_lt_i32 s63, 4
	s_cselect_b32 s19, s47, s19
	s_cselect_b32 s18, s45, s18
	v_mov_b32_e32 v130, s18
	v_mov_b32_e32 v131, s19
	v_ashrrev_i32_e32 v147, 31, v146
	v_ashrrev_i32_e32 v145, 31, v144
	v_lshl_add_u64 v[130:131], v[146:147], 1, v[130:131]
	v_lshlrev_b64 v[132:133], 11, v[144:145]
	v_lshl_add_u64 v[130:131], v[130:131], 0, v[132:133]
	s_mov_b32 s18, 0x8000
	v_cvt_pk_bf16_f32 v126, v126, v127
	v_cvt_pk_bf16_f32 v127, v128, v129
	v_cvt_pk_bf16_f32 v128, v122, v123
	v_cvt_pk_bf16_f32 v129, v124, v125
	global_store_dwordx4 v[130:131], v[126:129], off sc1
	v_cvt_pk_bf16_f32 v114, v114, v115
	v_cvt_pk_bf16_f32 v115, v116, v117
	v_cvt_pk_bf16_f32 v116, v106, v107
	v_cvt_pk_bf16_f32 v117, v108, v109
	global_store_dwordx4 v[130:131], v[114:117], off offset:256 sc1
	v_cvt_pk_bf16_f32 v106, v118, v119
	v_cvt_pk_bf16_f32 v107, v120, v121
	v_cvt_pk_bf16_f32 v108, v110, v111
	v_add_co_u32_e32 v110, vcc, s18, v130
	s_mov_b32 s18, 0x10000
	s_nop 0
	v_addc_co_u32_e32 v111, vcc, 0, v131, vcc
	v_cvt_pk_bf16_f32 v109, v112, v113
	global_store_dwordx4 v[110:111], v[106:109], off sc1
	v_cvt_pk_bf16_f32 v98, v98, v99
	v_cvt_pk_bf16_f32 v99, v100, v101
	v_cvt_pk_bf16_f32 v100, v90, v91
	v_cvt_pk_bf16_f32 v101, v92, v93
	global_store_dwordx4 v[110:111], v[98:101], off offset:256 sc1
	v_cvt_pk_bf16_f32 v90, v102, v103
	v_cvt_pk_bf16_f32 v91, v104, v105
	v_cvt_pk_bf16_f32 v92, v94, v95
	v_add_co_u32_e32 v94, vcc, s18, v130
	v_cvt_pk_bf16_f32 v93, v96, v97
	s_mov_b32 s18, 0x40000
	s_nop 0
	v_addc_co_u32_e32 v95, vcc, 0, v131, vcc
	global_store_dwordx4 v[94:95], v[90:93], off sc1
	v_cvt_pk_bf16_f32 v82, v82, v83
	v_cvt_pk_bf16_f32 v83, v84, v85
	v_cvt_pk_bf16_f32 v84, v74, v75
	v_cvt_pk_bf16_f32 v85, v76, v77
	global_store_dwordx4 v[94:95], v[82:85], off offset:256 sc1
	v_cvt_pk_bf16_f32 v74, v86, v87
	v_cvt_pk_bf16_f32 v75, v88, v89
	v_cvt_pk_bf16_f32 v76, v78, v79
	v_add_co_u32_e32 v78, vcc, s92, v130
	v_cvt_pk_bf16_f32 v77, v80, v81
	s_nop 1
	v_addc_co_u32_e32 v79, vcc, 0, v131, vcc
	global_store_dwordx4 v[78:79], v[74:77], off sc1
	v_cvt_pk_bf16_f32 v70, v70, v71
	v_cvt_pk_bf16_f32 v71, v72, v73
	v_cvt_pk_bf16_f32 v72, v66, v67
	v_cvt_pk_bf16_f32 v73, v68, v69
	global_store_dwordx4 v[78:79], v[70:73], off offset:256 sc1
	v_cvt_pk_bf16_f32 v62, v62, v63
	v_cvt_pk_bf16_f32 v63, v64, v65
	v_cvt_pk_bf16_f32 v64, v58, v59
	v_add_co_u32_e32 v58, vcc, s18, v130
	v_cvt_pk_bf16_f32 v65, v60, v61
	s_mov_b32 s18, 0x50000
	s_nop 0
	v_addc_co_u32_e32 v59, vcc, 0, v131, vcc
	global_store_dwordx4 v[58:59], v[62:65], off sc1
	v_cvt_pk_bf16_f32 v50, v50, v51
	v_cvt_pk_bf16_f32 v51, v52, v53
	v_cvt_pk_bf16_f32 v52, v42, v43
	v_cvt_pk_bf16_f32 v53, v44, v45
	global_store_dwordx4 v[58:59], v[50:53], off offset:256 sc1
	v_cvt_pk_bf16_f32 v42, v54, v55
	v_cvt_pk_bf16_f32 v43, v56, v57
	v_cvt_pk_bf16_f32 v44, v46, v47
	v_add_co_u32_e32 v46, vcc, s93, v130
	v_cvt_pk_bf16_f32 v45, v48, v49
	s_nop 1
	v_addc_co_u32_e32 v47, vcc, 0, v131, vcc
	global_store_dwordx4 v[46:47], v[42:45], off sc1
	v_cvt_pk_bf16_f32 v34, v34, v35
	v_cvt_pk_bf16_f32 v35, v36, v37
	v_cvt_pk_bf16_f32 v36, v24, v25
	v_cvt_pk_bf16_f32 v37, v26, v27
	global_store_dwordx4 v[46:47], v[34:37], off offset:256 sc1
	v_cvt_pk_bf16_f32 v24, v38, v39
	v_cvt_pk_bf16_f32 v25, v40, v41
	v_cvt_pk_bf16_f32 v26, v28, v29
	v_add_co_u32_e32 v28, vcc, s18, v130
	s_mov_b32 s18, 0x58000
	s_nop 0
	v_addc_co_u32_e32 v29, vcc, 0, v131, vcc
	v_cvt_pk_bf16_f32 v27, v30, v31
	global_store_dwordx4 v[28:29], v[24:27], off sc1
	v_cvt_pk_bf16_f32 v16, v16, v17
	v_cvt_pk_bf16_f32 v17, v18, v19
	v_cvt_pk_bf16_f32 v18, v8, v9
	v_cvt_pk_bf16_f32 v19, v10, v11
	global_store_dwordx4 v[28:29], v[16:19], off offset:256 sc1
	v_cvt_pk_bf16_f32 v8, v20, v21
	v_cvt_pk_bf16_f32 v9, v22, v23
	v_cvt_pk_bf16_f32 v10, v12, v13
	v_add_co_u32_e32 v12, vcc, s18, v130
	v_cvt_pk_bf16_f32 v11, v14, v15
	s_nop 1
	v_addc_co_u32_e32 v13, vcc, 0, v131, vcc
	global_store_dwordx4 v[12:13], v[8:11], off sc1
	v_cvt_pk_bf16_f32 v4, v4, v5
	v_cvt_pk_bf16_f32 v5, v6, v7
	v_cvt_pk_bf16_f32 v6, v0, v1
	v_cvt_pk_bf16_f32 v7, v2, v3
	global_store_dwordx4 v[12:13], v[4:7], off offset:256 sc1
	s_andn2_b64 vcc, exec, s[42:43]
	s_mov_b64 s[18:19], -1
	s_cbranch_vccnz .LBB0_580
